# DPP/permlane swap reductions instead of ds_bpermute in norm phases and q/k norm; uniform-mask branch replaces per-element cndmask in attention loop
# speedup vs baseline: 1.0015x; 1.0015x over previous
; __device__ __forceinline__ unsigned cvt_pk_bf16(float lo, float hi) { f32x2_t v = {lo, hi}; bf16x2_t b = __builtin_convertvector(v, bf16x2_t); return __builtin_bit_cast(unsigned, b); }
; __device__ __forceinline__ float wave_sum(float v) {
; #pragma unroll
;     for (int o = 1; o < 64; o <<= 1) v += __shfl_xor(v, o);
;     return v;
; }
; __device__ __forceinline__ void norm_mod_rows(const float* x, const float* g, const float* ada, int shift_off, int scale_off, bf16* XN, int gw, int NGW, int lane) {
;     ...
;         for (int i = 0; i < 16; ++i) {
;             const size_t row = (size_t)chunk * 16 + i;
;             { const f32x4* xr = (const f32x4*)(x + (row + (i < 15 ? 1 : 0)) * DM) + lane;
; #pragma unroll
;               for (int j = 0; j < 8; ++j) vn[j] = __builtin_nontemporal_load(xr + 64 * j); }
;             float s = 0.f;
; #pragma unroll
;             for (int j = 0; j < 8; ++j) s += (v[j].x * v[j].x + v[j].y * v[j].y) + (v[j].z * v[j].z + v[j].w * v[j].w);
;             const float rs = 1.0f / sqrtf(wave_sum(s) * (1.f / DM) + EPS);
;             v2u* o8 = (v2u*)(XN + row * DM) + lane;
; #pragma unroll
;             for (int j = 0; j < 8; ++j) { const f32x4 y = v[j] * rs * ca[j] + cb[j]; v2u w; w.x = pg8::cvt_pk_bf16(y.x, y.y); w.y = pg8::cvt_pk_bf16(y.z, y.w); o8[64 * j] = w; }
.LBB0_107:
	s_cmp_lg_u32 s26, 15
	s_cselect_b64 s[28:29], -1, 0
	s_mov_b32 s13, 0
	s_waitcnt vmcnt(0)
	v_pk_mul_f32 v[70:71], v[62:63], v[62:63]
	v_pk_mul_f32 v[72:73], v[60:61], v[60:61]
	v_pk_mul_f32 v[74:75], v[46:47], v[46:47]
	v_pk_mul_f32 v[76:77], v[44:45], v[44:45]
	v_pk_mul_f32 v[78:79], v[34:35], v[34:35]
	v_pk_mul_f32 v[80:81], v[38:39], v[38:39]
	v_pk_mul_f32 v[82:83], v[32:33], v[32:33]
	v_pk_mul_f32 v[84:85], v[36:37], v[36:37]
	v_mul_f32_e32 v86, v48, v48
	v_mul_f32_e32 v88, v50, v50
	v_cndmask_b32_e64 v66, 0, 1, s[28:29]
	s_add_u32 s28, s18, s26
	v_mov_b32_e32 v67, s13
	v_mov_b32_e32 v94, v82
	v_mov_b32_e32 v95, v84
	v_mov_b32_e32 v84, v83
	v_mov_b32_e32 v82, v78
	v_mov_b32_e32 v83, v80
	v_mov_b32_e32 v80, v79
	v_pk_mov_b32 v[78:79], v[76:77], v[74:75] op_sel:[1,0]
	v_mov_b32_e32 v77, v75
	v_pk_fma_f32 v[74:75], v[48:49], v[48:49], v[86:87] op_sel_hi:[1,1,0]
	v_pk_fma_f32 v[86:87], v[50:51], v[50:51], v[88:89] op_sel_hi:[1,1,0]
	v_pk_mov_b32 v[88:89], v[72:73], v[70:71] op_sel:[1,0]
	v_mov_b32_e32 v73, v71
	s_addc_u32 s29, s19, s27
	v_mul_f32_e32 v90, v52, v52
	v_mul_f32_e32 v92, v54, v54
	v_pk_add_f32 v[72:73], v[88:89], v[72:73]
	v_lshl_add_u64 v[66:67], s[28:29], 0, v[66:67]
	v_pk_fma_f32 v[70:71], v[52:53], v[52:53], v[90:91] op_sel_hi:[1,1,0]
	v_pk_fma_f32 v[90:91], v[54:55], v[54:55], v[92:93] op_sel_hi:[1,1,0]
	v_pk_add_f32 v[84:85], v[94:95], v[84:85]
	v_pk_add_f32 v[80:81], v[82:83], v[80:81]
	v_pk_add_f32 v[164:165], v[72:73], v[72:73] op_sel_hi:[0,1]
	v_lshlrev_b64 v[66:67], 13, v[66:67]
	v_pk_add_f32 v[76:77], v[78:79], v[76:77]
	v_mul_f32_e32 v74, v56, v56
	v_mul_f32_e32 v86, v57, v57
	v_mul_f32_e32 v70, v68, v68
	v_mul_f32_e32 v90, v65, v65
	v_pk_add_f32 v[68:69], v[84:85], v[80:81]
	v_mul_f32_e32 v164, v64, v64
	v_lshl_add_u64 v[64:65], v[96:97], 0, v[66:67]
	v_pk_add_f32 v[76:77], v[76:77], v[76:77] op_sel_hi:[0,1]
	v_pk_add_f32 v[162:163], v[74:75], v[86:87]
	v_pk_add_f32 v[166:167], v[70:71], v[90:91]
	v_pk_add_f32 v[68:69], v[68:69], v[68:69] op_sel_hi:[0,1]
	global_load_dwordx4 v[92:95], v[64:65], off nt
	global_load_dwordx4 v[88:91], v[64:65], off offset:1024 nt
	global_load_dwordx4 v[84:87], v[64:65], off offset:2048 nt
	global_load_dwordx4 v[80:83], v[64:65], off offset:3072 nt
	v_add_co_u32_e32 v64, vcc, s3, v64
	v_mul_f32_e32 v76, v58, v58
	v_mul_f32_e32 v68, v59, v59
	v_addc_co_u32_e32 v65, vcc, 0, v65, vcc
	v_pk_add_f32 v[168:169], v[76:77], v[68:69]
	global_load_dwordx4 v[76:79], v[64:65], off nt
	global_load_dwordx4 v[72:75], v[64:65], off offset:1024 nt
	global_load_dwordx4 v[68:71], v[64:65], off offset:2048 nt
	s_nop 0
	global_load_dwordx4 v[64:67], v[64:65], off offset:3072 nt
	v_pk_add_f32 v[162:163], v[162:163], v[168:169]
	s_mov_b32 s13, 0xf800000
	v_pk_add_f32 v[162:163], v[162:163], v[162:163] op_sel_hi:[0,1]
	v_mul_f32_e32 v162, v160, v160
	v_pk_add_f32 v[160:161], v[164:165], v[162:163]
	s_add_u32 s26, s26, 1
	v_pk_add_f32 v[160:161], v[166:167], v[160:161]
	s_addc_u32 s27, s27, 0
	v_add_f32_e32 v160, v160, v161
	s_nop 1
	v_mov_b32_dpp v161, v160 quad_perm:[1,0,3,2] row_mask:0xf bank_mask:0xf
	s_cmp_eq_u32 s26, 16
	s_waitcnt lgkmcnt(0)
	v_add_f32_e32 v160, v160, v161
	s_nop 1
	v_mov_b32_dpp v161, v160 quad_perm:[2,3,0,1] row_mask:0xf bank_mask:0xf
	s_waitcnt lgkmcnt(0)
	v_add_f32_e32 v160, v160, v161
	s_nop 1
	v_mov_b32_dpp v161, v160 row_half_mirror row_mask:0xf bank_mask:0xf
	s_waitcnt lgkmcnt(0)
	v_add_f32_e32 v160, v160, v161
	s_nop 1
	v_mov_b32_dpp v161, v160 row_mirror row_mask:0xf bank_mask:0xf
	s_waitcnt lgkmcnt(0)
	v_add_f32_e32 v160, v160, v161
	v_mov_b32_e32 v161, v160
	s_nop 1
	v_permlane16_swap_b32_e32 v160, v161
	s_waitcnt lgkmcnt(0)
	v_add_f32_e32 v160, v160, v161
	v_mov_b32_e32 v161, v160
	s_nop 1
	v_permlane32_swap_b32_e32 v160, v161
	s_waitcnt lgkmcnt(0)
; __device__ __forceinline__ unsigned cvt_pk_bf16(float lo, float hi) { f32x2_t v = {lo, hi}; bf16x2_t b = __builtin_convertvector(v, bf16x2_t); return __builtin_bit_cast(unsigned, b); }
; __device__ __forceinline__ void norm_mod_rows(const float* x, const float* g, const float* ada, int shift_off, int scale_off, bf16* XN, int gw, int NGW, int lane) {
;     ...
;             float s = 0.f;
; #pragma unroll
;             for (int j = 0; j < 8; ++j) s += (v[j].x * v[j].x + v[j].y * v[j].y) + (v[j].z * v[j].z + v[j].w * v[j].w);
;             const float rs = 1.0f / sqrtf(wave_sum(s) * (1.f / DM) + EPS);
;             v2u* o8 = (v2u*)(XN + row * DM) + lane;
; #pragma unroll
;             for (int j = 0; j < 8; ++j) { const f32x4 y = v[j] * rs * ca[j] + cb[j]; v2u w; w.x = pg8::cvt_pk_bf16(y.x, y.y); w.y = pg8::cvt_pk_bf16(y.z, y.w); o8[64 * j] = w; }
; #pragma unroll
;             for (int j = 0; j < 8; ++j) v[j] = vn[j];
;         }
;     }
	v_add_f32_e32 v160, v160, v161
	v_fmamk_f32 v160, v160, 0x3a000000, v158
	v_mul_f32_e32 v161, 0x4f800000, v160
	v_cmp_gt_f32_e32 vcc, s13, v160
	s_nop 1
	v_cndmask_b32_e32 v160, v160, v161, vcc
	v_sqrt_f32_e32 v161, v160
	s_nop 0
	v_add_u32_e32 v162, -1, v161
	v_add_u32_e32 v163, 1, v161
	v_fma_f32 v164, -v162, v161, v160
	v_fma_f32 v165, -v163, v161, v160
	v_cmp_ge_f32_e64 s[38:39], 0, v164
	s_nop 1
	v_cndmask_b32_e64 v161, v161, v162, s[38:39]
	v_cmp_lt_f32_e64 s[38:39], 0, v165
	s_nop 1
	v_cndmask_b32_e64 v161, v161, v163, s[38:39]
	v_mul_f32_e32 v162, 0x37800000, v161
	v_cndmask_b32_e32 v161, v161, v162, vcc
	v_cmp_class_f32_e32 vcc, v160, v159
	s_nop 1
	v_cndmask_b32_e32 v160, v161, v160, vcc
	v_div_scale_f32 v161, s[28:29], v160, v160, 1.0
	v_rcp_f32_e32 v163, v161
	v_div_scale_f32 v162, vcc, 1.0, v160, 1.0
	v_fma_f32 v164, -v161, v163, 1.0
	v_fmac_f32_e32 v163, v164, v163
	v_mul_f32_e32 v164, v162, v163
	v_fma_f32 v165, -v161, v164, v162
	v_fmac_f32_e32 v164, v165, v163
	v_fma_f32 v161, -v161, v164, v162
	v_div_fmas_f32 v161, v161, v163, v164
	v_div_fixup_f32 v160, v161, v160, 1.0
	v_pk_mul_f32 v[32:33], v[32:33], v[160:161] op_sel_hi:[1,0]
	v_pk_mul_f32 v[34:35], v[34:35], v[160:161] op_sel_hi:[1,0]
	v_pk_mul_f32 v[40:41], v[40:41], v[160:161] op_sel_hi:[1,0]
	v_pk_mul_f32 v[42:43], v[42:43], v[160:161] op_sel_hi:[1,0]
	v_pk_mul_f32 v[36:37], v[36:37], v[160:161] op_sel_hi:[1,0]
	v_pk_mul_f32 v[38:39], v[38:39], v[160:161] op_sel_hi:[1,0]
	v_pk_mul_f32 v[44:45], v[44:45], v[160:161] op_sel_hi:[1,0]
	v_pk_mul_f32 v[46:47], v[46:47], v[160:161] op_sel_hi:[1,0]
	v_pk_mul_f32 v[48:49], v[48:49], v[160:161] op_sel_hi:[1,0]
	v_pk_mul_f32 v[50:51], v[50:51], v[160:161] op_sel_hi:[1,0]
	v_pk_mul_f32 v[56:57], v[56:57], v[160:161] op_sel_hi:[1,0]
	v_pk_mul_f32 v[58:59], v[58:59], v[160:161] op_sel_hi:[1,0]
	v_pk_mul_f32 v[60:61], v[60:61], v[160:161] op_sel_hi:[1,0]
	v_pk_mul_f32 v[62:63], v[62:63], v[160:161] op_sel_hi:[1,0]
	v_pk_mul_f32 v[52:53], v[52:53], v[160:161] op_sel_hi:[1,0]
	v_pk_mul_f32 v[54:55], v[54:55], v[160:161] op_sel_hi:[1,0]
	v_pk_fma_f32 v[34:35], v[112:113], v[34:35], v[2:3]
	v_pk_fma_f32 v[32:33], v[114:115], v[32:33], v[0:1]
	v_pk_fma_f32 v[42:43], v[140:141], v[42:43], v[30:31]
	v_pk_fma_f32 v[40:41], v[142:143], v[40:41], v[28:29]
	v_pk_fma_f32 v[38:39], v[116:117], v[38:39], v[6:7]
	v_pk_fma_f32 v[36:37], v[118:119], v[36:37], v[4:5]
	v_pk_fma_f32 v[46:47], v[120:121], v[46:47], v[10:11]
	v_pk_fma_f32 v[44:45], v[122:123], v[44:45], v[8:9]
	v_pk_fma_f32 v[50:51], v[124:125], v[50:51], v[14:15]
	v_pk_fma_f32 v[48:49], v[126:127], v[48:49], v[12:13]
	v_pk_fma_f32 v[58:59], v[128:129], v[58:59], v[18:19]
	v_pk_fma_f32 v[56:57], v[130:131], v[56:57], v[16:17]
	v_pk_fma_f32 v[62:63], v[132:133], v[62:63], v[22:23]
	v_pk_fma_f32 v[60:61], v[134:135], v[60:61], v[20:21]
	v_pk_fma_f32 v[54:55], v[136:137], v[54:55], v[26:27]
	v_pk_fma_f32 v[52:53], v[138:139], v[52:53], v[24:25]
	v_cvt_pk_bf16_f32 v32, v32, v33
	v_cvt_pk_bf16_f32 v33, v34, v35
	v_cvt_pk_bf16_f32 v40, v40, v41
	v_cvt_pk_bf16_f32 v41, v42, v43
	v_cvt_pk_bf16_f32 v34, v36, v37
	v_cvt_pk_bf16_f32 v35, v38, v39
	v_cvt_pk_bf16_f32 v36, v44, v45
	v_cvt_pk_bf16_f32 v37, v46, v47
	v_cvt_pk_bf16_f32 v38, v48, v49
	v_cvt_pk_bf16_f32 v39, v50, v51
	v_cvt_pk_bf16_f32 v44, v56, v57
	v_cvt_pk_bf16_f32 v45, v58, v59
	v_cvt_pk_bf16_f32 v46, v60, v61
	v_cvt_pk_bf16_f32 v47, v62, v63
	v_cvt_pk_bf16_f32 v48, v52, v53
	v_cvt_pk_bf16_f32 v49, v54, v55
	global_store_dwordx2 v[110:111], v[32:33], off offset:-2048
	global_store_dwordx2 v[110:111], v[34:35], off offset:-1536
	global_store_dwordx2 v[110:111], v[36:37], off offset:-1024
	global_store_dwordx2 v[110:111], v[38:39], off offset:-512
	global_store_dwordx2 v[110:111], v[44:45], off
	global_store_dwordx2 v[110:111], v[46:47], off offset:512
	global_store_dwordx2 v[110:111], v[48:49], off offset:1024
	global_store_dwordx2 v[110:111], v[40:41], off offset:1536
	s_waitcnt vmcnt(8)
	v_mov_b64_e32 v[40:41], v[64:65]
	v_lshl_add_u64 v[110:111], v[110:111], 0, s[24:25]
	v_mov_b32_e32 v32, v92
	v_mov_b32_e32 v33, v93
	v_mov_b32_e32 v34, v94
	v_mov_b32_e32 v35, v95
	v_mov_b32_e32 v36, v88
	v_mov_b32_e32 v37, v89
	v_mov_b32_e32 v38, v90
	v_mov_b32_e32 v39, v91
	v_mov_b32_e32 v44, v84
	v_mov_b32_e32 v45, v85
	v_mov_b32_e32 v46, v86
	v_mov_b32_e32 v47, v87
	v_mov_b32_e32 v48, v80
	v_mov_b32_e32 v49, v81
	v_mov_b32_e32 v50, v82
	v_mov_b32_e32 v51, v83
	v_mov_b64_e32 v[42:43], v[66:67]
	v_mov_b32_e32 v56, v76
	v_mov_b32_e32 v57, v77
	v_mov_b32_e32 v58, v78
	v_mov_b32_e32 v59, v79
	v_mov_b32_e32 v60, v72
	v_mov_b32_e32 v61, v73
	v_mov_b32_e32 v62, v74
	v_mov_b32_e32 v63, v75
	v_mov_b32_e32 v52, v68
	v_mov_b32_e32 v53, v69
	v_mov_b32_e32 v54, v70
	v_mov_b32_e32 v55, v71
	v_mov_b32_e32 v68, v64
	v_mov_b32_e32 v64, v66
	v_mov_b32_e32 v160, v67
	s_cbranch_scc0 .LBB0_107
	s_add_i32 s14, s14, s12
	s_add_u32 s18, s18, s20
	s_addc_u32 s19, s19, s21
	s_cmpk_gt_i32 s14, 0x7ff
	v_lshl_add_u64 v[108:109], v[108:109], 0, s[22:23]
	s_cbranch_scc0 .LBB0_106
	v_readlane_b32 s24, v254, 43
	v_readlane_b32 s36, v254, 45
	v_readlane_b32 s38, v254, 47
	v_readlane_b32 s25, v254, 44
	v_readlane_b32 s37, v254, 46
	v_readlane_b32 s39, v254, 48

; __device__ __forceinline__ unsigned cvt_pk_bf16(float lo, float hi) { f32x2_t v = {lo, hi}; bf16x2_t b = __builtin_convertvector(v, bf16x2_t); return __builtin_bit_cast(unsigned, b); }
; __global__ void __launch_bounds__(NTHR, 2) mega_fwd(Args args) {
;     ...
;             for (int tg = gw; tg < T / 4; tg += NGW) {
;                 const int tkn = tg * 4 + tq, b = tkn >> 13, sq = tkn & 8191;
;                 const float pf = (float)pos[tkn]; float cs[4], sn[4];
; #pragma unroll
;                 for (int e = 0; e < 4; ++e) { const float angf = pf * invf[e]; const double rev = (double)angf * 0.15915494309189535; const float fr = (float)(rev - rint(rev));
;                     sn[e] = __builtin_amdgcn_sinf(fr); cs[e] = __builtin_amdgcn_cosf(fr); }
;                 const bf16* src = QKR + (size_t)tkn * 2048 + 4 * l16;
;                 v2u r0[16], r1[16];
; #pragma unroll
;                 for (int hm = 0; hm < 16; ++hm) { r0[hm] = *(const v2u*)(src + hm * 128); r1[hm] = *(const v2u*)(src + hm * 128 + 64); }
; #pragma unroll
;                 for (int hm = 0; hm < 16; ++hm) {
;                     const f32x4 x1 = {pg8::bflo(r0[hm].x), pg8::bfhi(r0[hm].x), pg8::bflo(r0[hm].y), pg8::bfhi(r0[hm].y)}, x2 = {pg8::bflo(r1[hm].x), pg8::bfhi(r1[hm].x), pg8::bflo(r1[hm].y), pg8::bfhi(r1[hm].y)};
;                     float ss = (x1.x * x1.x + x1.y * x1.y) + (x1.z * x1.z + x1.w * x1.w) + (x2.x * x2.x + x2.y * x2.y) + (x2.z * x2.z + x2.w * x2.w);
;                     ss += __shfl_xor(ss, 1); ss += __shfl_xor(ss, 2); ss += __shfl_xor(ss, 4); ss += __shfl_xor(ss, 8);
;                     const float rs = 1.0f / sqrtf(ss * (1.f / 128.f) + EPS);
;                     const f32x4 y1 = x1 * rs * (hm < 8 ? qg0 : kg0), y2 = x2 * rs * (hm < 8 ? qg1 : kg1);
;                     bf16* dst = (hm < 8 ? QH : KH) + ((size_t)((b * 8 + (hm & 7)) * SEQ + sq)) * 128 + 4 * l16;
;                     v2u o1, o2;
;                     o1.x = pg8::cvt_pk_bf16(y1.x * cs[0] - y2.x * sn[0], y1.y * cs[1] - y2.y * sn[1]); o1.y = pg8::cvt_pk_bf16(y1.z * cs[2] - y2.z * sn[2], y1.w * cs[3] - y2.w * sn[3]);
;                     o2.x = pg8::cvt_pk_bf16(y2.x * cs[0] + y1.x * sn[0], y2.y * cs[1] + y1.y * sn[1]); o2.y = pg8::cvt_pk_bf16(y2.z * cs[2] + y1.z * sn[2], y2.w * cs[3] + y1.w * sn[3]);
;                     *(v2u*)dst = o1; *(v2u*)(dst + 64) = o2;
;                 }
;             }
.LBB0_261:
	v_ashrrev_i32_e32 v23, 31, v22
	v_lshl_add_u64 v[24:25], v[22:23], 2, s[42:43]
	global_load_dword v24, v[24:25], off
	s_waitcnt vmcnt(0)
	v_cvt_f32_i32_e32 v32, v24
	v_mul_f32_e32 v24, v96, v32
	v_cvt_f64_f32_e32 v[24:25], v24
	v_mul_f64 v[26:27], v[24:25], s[40:41]
	v_rndne_f64_e32 v[26:27], v[26:27]
	v_fma_f64 v[24:25], v[24:25], s[40:41], -v[26:27]
	v_cvt_f32_f64_e32 v25, v[24:25]
	v_sin_f32_e32 v24, v25
	v_cos_f32_e32 v26, v25
	v_mul_f32_e32 v25, v97, v32
	v_cvt_f64_f32_e32 v[28:29], v25
	v_mul_f64 v[30:31], v[28:29], s[40:41]
	v_rndne_f64_e32 v[30:31], v[30:31]
	v_fma_f64 v[28:29], v[28:29], s[40:41], -v[30:31]
	v_cvt_f32_f64_e32 v27, v[28:29]
	v_mul_f32_e32 v28, v98, v32
	v_cvt_f64_f32_e32 v[28:29], v28
	v_mul_f64 v[30:31], v[28:29], s[40:41]
	v_rndne_f64_e32 v[30:31], v[30:31]
	v_fma_f64 v[28:29], v[28:29], s[40:41], -v[30:31]
	v_cvt_f32_f64_e32 v29, v[28:29]
	v_sin_f32_e32 v28, v29
	v_cos_f32_e32 v30, v29
	v_mul_f32_e32 v29, v99, v32
	v_cvt_f64_f32_e32 v[32:33], v29
	v_mul_f64 v[34:35], v[32:33], s[40:41]
	v_rndne_f64_e32 v[34:35], v[34:35]
	v_fma_f64 v[32:33], v[32:33], s[40:41], -v[34:35]
	v_cvt_f32_f64_e32 v31, v[32:33]
	v_lshlrev_b64 v[32:33], 12, v[22:23]
	v_lshl_add_u64 v[32:33], v[16:17], 0, v[32:33]
	global_load_dwordx2 v[76:77], v[32:33], off
	global_load_dwordx2 v[88:89], v[32:33], off offset:128
	global_load_dwordx2 v[94:95], v[32:33], off offset:256
	global_load_dwordx2 v[78:79], v[32:33], off offset:384
	global_load_dwordx2 v[92:93], v[32:33], off offset:512
	global_load_dwordx2 v[80:81], v[32:33], off offset:640
	global_load_dwordx2 v[90:91], v[32:33], off offset:768
	global_load_dwordx2 v[82:83], v[32:33], off offset:896
	global_load_dwordx2 v[86:87], v[32:33], off offset:1024
	global_load_dwordx2 v[84:85], v[32:33], off offset:1152
	global_load_dwordx2 v[74:75], v[32:33], off offset:1280
	global_load_dwordx2 v[72:73], v[32:33], off offset:1408
	global_load_dwordx2 v[70:71], v[32:33], off offset:1536
	global_load_dwordx2 v[68:69], v[32:33], off offset:1664
	global_load_dwordx2 v[66:67], v[32:33], off offset:1792
	global_load_dwordx2 v[64:65], v[32:33], off offset:1920
	global_load_dwordx2 v[62:63], v[32:33], off offset:2048
	global_load_dwordx2 v[60:61], v[32:33], off offset:2176
	global_load_dwordx2 v[58:59], v[32:33], off offset:2304
	global_load_dwordx2 v[56:57], v[32:33], off offset:2432
	global_load_dwordx2 v[54:55], v[32:33], off offset:2560
	global_load_dwordx2 v[52:53], v[32:33], off offset:2688
	global_load_dwordx2 v[50:51], v[32:33], off offset:2816
	global_load_dwordx2 v[48:49], v[32:33], off offset:2944
	global_load_dwordx2 v[46:47], v[32:33], off offset:3072
	global_load_dwordx2 v[44:45], v[32:33], off offset:3200
	global_load_dwordx2 v[42:43], v[32:33], off offset:3328
	global_load_dwordx2 v[40:41], v[32:33], off offset:3456
	global_load_dwordx2 v[38:39], v[32:33], off offset:3584
	global_load_dwordx2 v[36:37], v[32:33], off offset:3712
	global_load_dwordx2 v[34:35], v[32:33], off offset:3840
	s_nop 0
	global_load_dwordx2 v[32:33], v[32:33], off offset:3968
	v_sin_f32_e32 v25, v27
	v_sin_f32_e32 v29, v31
	v_cos_f32_e32 v27, v27
	v_cos_f32_e32 v31, v31
	v_and_b32_e32 v23, 0x1fff, v22
	v_add_u32_e32 v22, s14, v22
	s_waitcnt vmcnt(31)
	v_lshlrev_b32_e32 v107, 16, v77
	v_lshlrev_b32_e32 v106, 16, v76
	v_and_b32_e32 v77, 0xffff0000, v77
	v_and_b32_e32 v76, 0xffff0000, v76
	v_pk_mul_f32 v[108:109], v[76:77], v[76:77]
	s_waitcnt vmcnt(30)
	v_lshlrev_b32_e32 v111, 16, v89
	v_lshlrev_b32_e32 v110, 16, v88
	v_and_b32_e32 v89, 0xffff0000, v89
	v_and_b32_e32 v88, 0xffff0000, v88
	v_pk_fma_f32 v[108:109], v[106:107], v[106:107], v[108:109]
	v_pk_mul_f32 v[112:113], v[88:89], v[88:89]
	v_add_f32_e32 v108, v108, v109
	v_pk_fma_f32 v[112:113], v[110:111], v[110:111], v[112:113]
	s_nop 0
	v_add_f32_e32 v108, v108, v112
	v_add_f32_e32 v108, v113, v108
	s_nop 1
	v_mov_b32_dpp v109, v108 quad_perm:[1,0,3,2] row_mask:0xf bank_mask:0xf
	s_waitcnt lgkmcnt(0)
	v_add_f32_e32 v108, v108, v109
	s_nop 1
	v_mov_b32_dpp v109, v108 quad_perm:[2,3,0,1] row_mask:0xf bank_mask:0xf
	s_waitcnt lgkmcnt(0)
	v_add_f32_e32 v108, v108, v109
	s_nop 1
	v_mov_b32_dpp v109, v108 row_half_mirror row_mask:0xf bank_mask:0xf
	s_waitcnt lgkmcnt(0)
	v_add_f32_e32 v108, v108, v109
	s_nop 1
	v_mov_b32_dpp v109, v108 row_mirror row_mask:0xf bank_mask:0xf
	s_waitcnt lgkmcnt(0)
	v_add_f32_e32 v108, v108, v109
	v_fmamk_f32 v108, v108, 0x3c000000, v104
	v_cmp_gt_f32_e32 vcc, s15, v108
	v_mul_f32_e32 v109, 0x4f800000, v108
	s_nop 0
	v_cndmask_b32_e32 v108, v108, v109, vcc
	v_sqrt_f32_e32 v109, v108
	s_nop 0
	v_add_u32_e32 v112, -1, v109
	v_fma_f32 v113, -v112, v109, v108
	v_cmp_ge_f32_e64 s[38:39], 0, v113
	v_add_u32_e32 v113, 1, v109
	s_nop 0
	v_cndmask_b32_e64 v112, v109, v112, s[38:39]
	v_fma_f32 v109, -v113, v109, v108
	v_cmp_lt_f32_e64 s[38:39], 0, v109
	s_nop 1
	v_cndmask_b32_e64 v109, v112, v113, s[38:39]
	v_mul_f32_e32 v112, 0x37800000, v109
	v_cndmask_b32_e32 v109, v109, v112, vcc
	v_cmp_class_f32_e32 vcc, v108, v105
	s_nop 1
	v_cndmask_b32_e32 v108, v109, v108, vcc
	v_div_scale_f32 v109, s[16:17], v108, v108, 1.0
	v_rcp_f32_e32 v112, v109
	s_lshl_b32 s16, s13, 5
	s_and_b32 s16, s16, 0xffff0000
	s_add_i32 s13, s13, s12
	v_fma_f32 v113, -v109, v112, 1.0
	v_fmac_f32_e32 v112, v113, v112
	v_div_scale_f32 v113, vcc, 1.0, v108, 1.0
	v_mul_f32_e32 v114, v113, v112
	v_fma_f32 v115, -v109, v114, v113
	v_fmac_f32_e32 v114, v115, v112
	v_fma_f32 v109, -v109, v114, v113
	v_div_fmas_f32 v109, v109, v112, v114
	v_div_fixup_f32 v108, v109, v108, 1.0
	v_mov_b32_e32 v113, v76
	v_mov_b32_e32 v76, v107
	v_pk_mul_f32 v[76:77], v[108:109], v[76:77] op_sel_hi:[0,1]
	v_mov_b32_e32 v112, v106
	v_pk_mul_f32 v[106:107], v[2:3], v[76:77]
	v_mov_b32_e32 v76, v110
	v_mov_b32_e32 v77, v88
	v_mov_b32_e32 v88, v111
	v_pk_mul_f32 v[76:77], v[108:109], v[76:77] op_sel_hi:[0,1]
	v_pk_mul_f32 v[88:89], v[108:109], v[88:89] op_sel_hi:[0,1]
	v_pk_mul_f32 v[112:113], v[108:109], v[112:113] op_sel_hi:[0,1]
	v_pk_mul_f32 v[108:109], v[6:7], v[88:89]
	v_pk_mul_f32 v[110:111], v[4:5], v[76:77]
	v_pk_mul_f32 v[112:113], v[0:1], v[112:113]
	v_or_b32_e32 v88, s16, v23
	v_pk_mul_f32 v[116:117], v[24:25], v[110:111]
	v_pk_mul_f32 v[118:119], v[28:29], v[108:109]
	v_ashrrev_i32_e32 v89, 31, v88
	v_pk_fma_f32 v[116:117], v[26:27], v[112:113], v[116:117] neg_lo:[0,0,1] neg_hi:[0,0,1]
	v_pk_fma_f32 v[118:119], v[30:31], v[106:107], v[118:119] neg_lo:[0,0,1] neg_hi:[0,0,1]
	v_pk_mul_f32 v[112:113], v[24:25], v[112:113]
	v_pk_mul_f32 v[106:107], v[28:29], v[106:107]
	v_lshlrev_b64 v[76:77], 8, v[88:89]
	v_pk_fma_f32 v[110:111], v[26:27], v[110:111], v[112:113]
	v_pk_fma_f32 v[106:107], v[30:31], v[108:109], v[106:107]
	v_lshl_add_u64 v[114:115], v[18:19], 0, v[76:77]
	v_cvt_pk_bf16_f32 v116, v116, v117
	v_cvt_pk_bf16_f32 v117, v118, v119
	v_cvt_pk_bf16_f32 v110, v110, v111
	v_cvt_pk_bf16_f32 v111, v106, v107
	s_waitcnt vmcnt(29)
; __device__ __forceinline__ unsigned cvt_pk_bf16(float lo, float hi) { f32x2_t v = {lo, hi}; bf16x2_t b = __builtin_convertvector(v, bf16x2_t); return __builtin_bit_cast(unsigned, b); }
; __device__ __forceinline__ float bflo(unsigned w) { return __uint_as_float(w << 16); }
; __device__ __forceinline__ float bfhi(unsigned w) { return __uint_as_float(w & 0xffff0000u); }
; __global__ void __launch_bounds__(NTHR, 2) mega_fwd(Args args) {
;     ...
;                 for (int hm = 0; hm < 16; ++hm) { r0[hm] = *(const v2u*)(src + hm * 128); r1[hm] = *(const v2u*)(src + hm * 128 + 64); }
; #pragma unroll
;                 for (int hm = 0; hm < 16; ++hm) {
;                     const f32x4 x1 = {pg8::bflo(r0[hm].x), pg8::bfhi(r0[hm].x), pg8::bflo(r0[hm].y), pg8::bfhi(r0[hm].y)}, x2 = {pg8::bflo(r1[hm].x), pg8::bfhi(r1[hm].x), pg8::bflo(r1[hm].y), pg8::bfhi(r1[hm].y)};
;                     float ss = (x1.x * x1.x + x1.y * x1.y) + (x1.z * x1.z + x1.w * x1.w) + (x2.x * x2.x + x2.y * x2.y) + (x2.z * x2.z + x2.w * x2.w);
;                     ss += __shfl_xor(ss, 1); ss += __shfl_xor(ss, 2); ss += __shfl_xor(ss, 4); ss += __shfl_xor(ss, 8);
;                     const float rs = 1.0f / sqrtf(ss * (1.f / 128.f) + EPS);
;                     const f32x4 y1 = x1 * rs * (hm < 8 ? qg0 : kg0), y2 = x2 * rs * (hm < 8 ? qg1 : kg1);
;                     bf16* dst = (hm < 8 ? QH : KH) + ((size_t)((b * 8 + (hm & 7)) * SEQ + sq)) * 128 + 4 * l16;
;                     v2u o1, o2;
;                     o1.x = pg8::cvt_pk_bf16(y1.x * cs[0] - y2.x * sn[0], y1.y * cs[1] - y2.y * sn[1]); o1.y = pg8::cvt_pk_bf16(y1.z * cs[2] - y2.z * sn[2], y1.w * cs[3] - y2.w * sn[3]);
;                     o2.x = pg8::cvt_pk_bf16(y2.x * cs[0] + y1.x * sn[0], y2.y * cs[1] + y1.y * sn[1]); o2.y = pg8::cvt_pk_bf16(y2.z * cs[2] + y1.z * sn[2], y2.w * cs[3] + y1.w * sn[3]);
;                     *(v2u*)dst = o1; *(v2u*)(dst + 64) = o2;
;                 }
	v_lshlrev_b32_e32 v107, 16, v95
	v_lshlrev_b32_e32 v106, 16, v94
	v_and_b32_e32 v95, 0xffff0000, v95
	v_and_b32_e32 v94, 0xffff0000, v94
	global_store_dwordx2 v[114:115], v[116:117], off
	global_store_dwordx2 v[114:115], v[110:111], off offset:128
	v_pk_mul_f32 v[108:109], v[94:95], v[94:95]
	s_waitcnt vmcnt(30)
	v_lshlrev_b32_e32 v111, 16, v79
	v_lshlrev_b32_e32 v110, 16, v78
	v_and_b32_e32 v79, 0xffff0000, v79
	v_and_b32_e32 v78, 0xffff0000, v78
	v_pk_fma_f32 v[108:109], v[106:107], v[106:107], v[108:109]
	v_pk_mul_f32 v[112:113], v[78:79], v[78:79]
	v_add_f32_e32 v23, v108, v109
	v_pk_fma_f32 v[112:113], v[110:111], v[110:111], v[112:113]
	s_cmpk_gt_i32 s13, 0x1fff
	v_add_f32_e32 v23, v23, v112
	v_add_f32_e32 v23, v113, v23
	s_nop 1
	v_mov_b32_dpp v89, v23 quad_perm:[1,0,3,2] row_mask:0xf bank_mask:0xf
	s_waitcnt lgkmcnt(0)
	v_add_f32_e32 v23, v23, v89
	s_nop 1
	v_mov_b32_dpp v89, v23 quad_perm:[2,3,0,1] row_mask:0xf bank_mask:0xf
	s_waitcnt lgkmcnt(0)
	v_add_f32_e32 v23, v23, v89
	s_nop 1
	v_mov_b32_dpp v89, v23 row_half_mirror row_mask:0xf bank_mask:0xf
	s_waitcnt lgkmcnt(0)
	v_add_f32_e32 v23, v23, v89
	s_nop 1
	v_mov_b32_dpp v89, v23 row_mirror row_mask:0xf bank_mask:0xf
	s_waitcnt lgkmcnt(0)
	v_add_f32_e32 v23, v23, v89
	v_fmamk_f32 v23, v23, 0x3c000000, v104
	v_cmp_gt_f32_e32 vcc, s15, v23
	v_mul_f32_e32 v89, 0x4f800000, v23
	s_nop 0
	v_cndmask_b32_e32 v23, v23, v89, vcc
	v_sqrt_f32_e32 v89, v23
	s_nop 0
	v_add_u32_e32 v108, -1, v89
	v_fma_f32 v109, -v108, v89, v23
	v_cmp_ge_f32_e64 s[38:39], 0, v109
	v_add_u32_e32 v109, 1, v89
	s_nop 0
	v_cndmask_b32_e64 v108, v89, v108, s[38:39]
	v_fma_f32 v89, -v109, v89, v23
	v_cmp_lt_f32_e64 s[38:39], 0, v89
	s_nop 1
	v_cndmask_b32_e64 v89, v108, v109, s[38:39]
	v_mul_f32_e32 v108, 0x37800000, v89
	v_cndmask_b32_e32 v89, v89, v108, vcc
	v_cmp_class_f32_e32 vcc, v23, v105
	s_nop 1
	v_cndmask_b32_e32 v23, v89, v23, vcc
	v_div_scale_f32 v89, s[16:17], v23, v23, 1.0
	v_rcp_f32_e32 v108, v89
	s_nop 0
	v_fma_f32 v109, -v89, v108, 1.0
	v_fmac_f32_e32 v108, v109, v108
	v_div_scale_f32 v109, vcc, 1.0, v23, 1.0
	v_mul_f32_e32 v112, v109, v108
	v_fma_f32 v113, -v89, v112, v109
	v_fmac_f32_e32 v112, v113, v108
	v_fma_f32 v89, -v89, v112, v109
	v_div_fmas_f32 v89, v89, v108, v112
	v_div_fixup_f32 v108, v89, v23, 1.0
	v_mov_b32_e32 v112, v106
	v_mov_b32_e32 v113, v94
	v_pk_mul_f32 v[112:113], v[108:109], v[112:113] op_sel_hi:[0,1]
	v_mov_b32_e32 v94, v107
	v_pk_mul_f32 v[106:107], v[0:1], v[112:113]
	v_mov_b32_e32 v112, v110
	v_mov_b32_e32 v113, v78
	v_mov_b32_e32 v78, v111
	v_pk_mul_f32 v[112:113], v[108:109], v[112:113] op_sel_hi:[0,1]
	v_pk_mul_f32 v[78:79], v[108:109], v[78:79] op_sel_hi:[0,1]
	v_pk_mul_f32 v[94:95], v[108:109], v[94:95] op_sel_hi:[0,1]
	v_pk_mul_f32 v[108:109], v[6:7], v[78:79]
	v_pk_mul_f32 v[110:111], v[4:5], v[112:113]
	v_pk_mul_f32 v[94:95], v[2:3], v[94:95]
	v_or_b32_e32 v78, 0x2000, v88
	v_pk_mul_f32 v[114:115], v[24:25], v[110:111]
	v_pk_mul_f32 v[116:117], v[28:29], v[108:109]
	v_ashrrev_i32_e32 v79, 31, v78
	v_pk_fma_f32 v[114:115], v[26:27], v[106:107], v[114:115] neg_lo:[0,0,1] neg_hi:[0,0,1]
	v_pk_fma_f32 v[116:117], v[30:31], v[94:95], v[116:117] neg_lo:[0,0,1] neg_hi:[0,0,1]
	v_pk_mul_f32 v[106:107], v[24:25], v[106:107]
	v_pk_mul_f32 v[94:95], v[28:29], v[94:95]
	v_lshlrev_b64 v[78:79], 8, v[78:79]
	v_pk_fma_f32 v[106:107], v[26:27], v[110:111], v[106:107]
	v_pk_fma_f32 v[94:95], v[30:31], v[108:109], v[94:95]
	v_lshl_add_u64 v[112:113], v[18:19], 0, v[78:79]
	v_cvt_pk_bf16_f32 v114, v114, v115
	v_cvt_pk_bf16_f32 v115, v116, v117
	v_cvt_pk_bf16_f32 v106, v106, v107
	v_cvt_pk_bf16_f32 v107, v94, v95
	s_waitcnt vmcnt(29)
	v_lshlrev_b32_e32 v95, 16, v93
	v_lshlrev_b32_e32 v94, 16, v92
	v_and_b32_e32 v93, 0xffff0000, v93
	v_and_b32_e32 v92, 0xffff0000, v92
	global_store_dwordx2 v[112:113], v[114:115], off
	global_store_dwordx2 v[112:113], v[106:107], off offset:128
	v_pk_mul_f32 v[106:107], v[92:93], v[92:93]
	s_waitcnt vmcnt(30)
	v_lshlrev_b32_e32 v109, 16, v81
	v_lshlrev_b32_e32 v108, 16, v80
	v_and_b32_e32 v81, 0xffff0000, v81
	v_and_b32_e32 v80, 0xffff0000, v80
	v_pk_fma_f32 v[106:107], v[94:95], v[94:95], v[106:107]
	v_pk_mul_f32 v[110:111], v[80:81], v[80:81]
	v_add_f32_e32 v23, v106, v107
	v_pk_fma_f32 v[110:111], v[108:109], v[108:109], v[110:111]
	s_nop 0
	v_add_f32_e32 v23, v23, v110
	v_add_f32_e32 v23, v111, v23
	s_nop 1
	v_mov_b32_dpp v89, v23 quad_perm:[1,0,3,2] row_mask:0xf bank_mask:0xf
	s_waitcnt lgkmcnt(0)
	v_add_f32_e32 v23, v23, v89
	s_nop 1
	v_mov_b32_dpp v89, v23 quad_perm:[2,3,0,1] row_mask:0xf bank_mask:0xf
	s_waitcnt lgkmcnt(0)
	v_add_f32_e32 v23, v23, v89
	s_nop 1
	v_mov_b32_dpp v89, v23 row_half_mirror row_mask:0xf bank_mask:0xf
	s_waitcnt lgkmcnt(0)
	v_add_f32_e32 v23, v23, v89
	s_nop 1
	v_mov_b32_dpp v89, v23 row_mirror row_mask:0xf bank_mask:0xf
	s_waitcnt lgkmcnt(0)
; __device__ __forceinline__ unsigned cvt_pk_bf16(float lo, float hi) { f32x2_t v = {lo, hi}; bf16x2_t b = __builtin_convertvector(v, bf16x2_t); return __builtin_bit_cast(unsigned, b); }
; __device__ __forceinline__ float bflo(unsigned w) { return __uint_as_float(w << 16); }
; __device__ __forceinline__ float bfhi(unsigned w) { return __uint_as_float(w & 0xffff0000u); }
; __global__ void __launch_bounds__(NTHR, 2) mega_fwd(Args args) {
;     ...
;                 for (int hm = 0; hm < 16; ++hm) { r0[hm] = *(const v2u*)(src + hm * 128); r1[hm] = *(const v2u*)(src + hm * 128 + 64); }
; #pragma unroll
;                 for (int hm = 0; hm < 16; ++hm) {
;                     const f32x4 x1 = {pg8::bflo(r0[hm].x), pg8::bfhi(r0[hm].x), pg8::bflo(r0[hm].y), pg8::bfhi(r0[hm].y)}, x2 = {pg8::bflo(r1[hm].x), pg8::bfhi(r1[hm].x), pg8::bflo(r1[hm].y), pg8::bfhi(r1[hm].y)};
;                     float ss = (x1.x * x1.x + x1.y * x1.y) + (x1.z * x1.z + x1.w * x1.w) + (x2.x * x2.x + x2.y * x2.y) + (x2.z * x2.z + x2.w * x2.w);
;                     ss += __shfl_xor(ss, 1); ss += __shfl_xor(ss, 2); ss += __shfl_xor(ss, 4); ss += __shfl_xor(ss, 8);
;                     const float rs = 1.0f / sqrtf(ss * (1.f / 128.f) + EPS);
;                     const f32x4 y1 = x1 * rs * (hm < 8 ? qg0 : kg0), y2 = x2 * rs * (hm < 8 ? qg1 : kg1);
;                     bf16* dst = (hm < 8 ? QH : KH) + ((size_t)((b * 8 + (hm & 7)) * SEQ + sq)) * 128 + 4 * l16;
;                     v2u o1, o2;
;                     o1.x = pg8::cvt_pk_bf16(y1.x * cs[0] - y2.x * sn[0], y1.y * cs[1] - y2.y * sn[1]); o1.y = pg8::cvt_pk_bf16(y1.z * cs[2] - y2.z * sn[2], y1.w * cs[3] - y2.w * sn[3]);
;                     o2.x = pg8::cvt_pk_bf16(y2.x * cs[0] + y1.x * sn[0], y2.y * cs[1] + y1.y * sn[1]); o2.y = pg8::cvt_pk_bf16(y2.z * cs[2] + y1.z * sn[2], y2.w * cs[3] + y1.w * sn[3]);
;                     *(v2u*)dst = o1; *(v2u*)(dst + 64) = o2;
;                 }
	v_add_f32_e32 v23, v23, v89
	v_fmamk_f32 v23, v23, 0x3c000000, v104
	v_cmp_gt_f32_e32 vcc, s15, v23
	v_mul_f32_e32 v89, 0x4f800000, v23
	s_nop 0
	v_cndmask_b32_e32 v23, v23, v89, vcc
	v_sqrt_f32_e32 v89, v23
	s_nop 0
	v_add_u32_e32 v106, -1, v89
	v_fma_f32 v107, -v106, v89, v23
	v_cmp_ge_f32_e64 s[38:39], 0, v107
	v_add_u32_e32 v107, 1, v89
	s_nop 0
	v_cndmask_b32_e64 v106, v89, v106, s[38:39]
	v_fma_f32 v89, -v107, v89, v23
	v_cmp_lt_f32_e64 s[38:39], 0, v89
	s_nop 1
	v_cndmask_b32_e64 v89, v106, v107, s[38:39]
	v_mul_f32_e32 v106, 0x37800000, v89
	v_cndmask_b32_e32 v89, v89, v106, vcc
	v_cmp_class_f32_e32 vcc, v23, v105
	s_nop 1
	v_cndmask_b32_e32 v23, v89, v23, vcc
	v_div_scale_f32 v89, s[16:17], v23, v23, 1.0
	v_rcp_f32_e32 v106, v89
	s_nop 0
	v_fma_f32 v107, -v89, v106, 1.0
	v_fmac_f32_e32 v106, v107, v106
	v_div_scale_f32 v107, vcc, 1.0, v23, 1.0
	v_mul_f32_e32 v110, v107, v106
	v_fma_f32 v111, -v89, v110, v107
	v_fmac_f32_e32 v110, v111, v106
	v_fma_f32 v89, -v89, v110, v107
	v_div_fmas_f32 v89, v89, v106, v110
	v_div_fixup_f32 v106, v89, v23, 1.0
	v_mov_b32_e32 v110, v94
	v_mov_b32_e32 v111, v92
	v_pk_mul_f32 v[110:111], v[106:107], v[110:111] op_sel_hi:[0,1]
	v_mov_b32_e32 v92, v95
	v_pk_mul_f32 v[94:95], v[0:1], v[110:111]
	v_mov_b32_e32 v110, v108
	v_mov_b32_e32 v111, v80
	v_mov_b32_e32 v80, v109
	v_pk_mul_f32 v[110:111], v[106:107], v[110:111] op_sel_hi:[0,1]
	v_pk_mul_f32 v[80:81], v[106:107], v[80:81] op_sel_hi:[0,1]
	v_pk_mul_f32 v[92:93], v[106:107], v[92:93] op_sel_hi:[0,1]
	v_pk_mul_f32 v[106:107], v[6:7], v[80:81]
	v_pk_mul_f32 v[108:109], v[4:5], v[110:111]
	v_pk_mul_f32 v[92:93], v[2:3], v[92:93]
	v_or_b32_e32 v80, 0x4000, v88
	v_pk_mul_f32 v[112:113], v[24:25], v[108:109]
	v_pk_mul_f32 v[114:115], v[28:29], v[106:107]
	v_ashrrev_i32_e32 v81, 31, v80
	v_pk_fma_f32 v[112:113], v[26:27], v[94:95], v[112:113] neg_lo:[0,0,1] neg_hi:[0,0,1]
	v_pk_fma_f32 v[114:115], v[30:31], v[92:93], v[114:115] neg_lo:[0,0,1] neg_hi:[0,0,1]
	v_pk_mul_f32 v[94:95], v[24:25], v[94:95]
	v_pk_mul_f32 v[92:93], v[28:29], v[92:93]
	v_lshlrev_b64 v[80:81], 8, v[80:81]
	v_pk_fma_f32 v[94:95], v[26:27], v[108:109], v[94:95]
	v_pk_fma_f32 v[92:93], v[30:31], v[106:107], v[92:93]
	v_lshl_add_u64 v[110:111], v[18:19], 0, v[80:81]
	v_cvt_pk_bf16_f32 v112, v112, v113
	v_cvt_pk_bf16_f32 v113, v114, v115
	v_cvt_pk_bf16_f32 v94, v94, v95
	v_cvt_pk_bf16_f32 v95, v92, v93
	s_waitcnt vmcnt(29)
	v_lshlrev_b32_e32 v93, 16, v91
	v_lshlrev_b32_e32 v92, 16, v90
	v_and_b32_e32 v91, 0xffff0000, v91
	v_and_b32_e32 v90, 0xffff0000, v90
	global_store_dwordx2 v[110:111], v[112:113], off
	global_store_dwordx2 v[110:111], v[94:95], off offset:128
	v_pk_mul_f32 v[94:95], v[90:91], v[90:91]
	s_waitcnt vmcnt(30)
	v_lshlrev_b32_e32 v107, 16, v83
	v_lshlrev_b32_e32 v106, 16, v82
	v_and_b32_e32 v83, 0xffff0000, v83
	v_and_b32_e32 v82, 0xffff0000, v82
	v_pk_fma_f32 v[94:95], v[92:93], v[92:93], v[94:95]
	v_pk_mul_f32 v[108:109], v[82:83], v[82:83]
	v_add_f32_e32 v23, v94, v95
	v_pk_fma_f32 v[108:109], v[106:107], v[106:107], v[108:109]
	s_nop 0
	v_add_f32_e32 v23, v23, v108
	v_add_f32_e32 v23, v109, v23
	s_nop 1
	v_mov_b32_dpp v89, v23 quad_perm:[1,0,3,2] row_mask:0xf bank_mask:0xf
	s_waitcnt lgkmcnt(0)
	v_add_f32_e32 v23, v23, v89
	s_nop 1
	v_mov_b32_dpp v89, v23 quad_perm:[2,3,0,1] row_mask:0xf bank_mask:0xf
	s_waitcnt lgkmcnt(0)
	v_add_f32_e32 v23, v23, v89
	s_nop 1
	v_mov_b32_dpp v89, v23 row_half_mirror row_mask:0xf bank_mask:0xf
	s_waitcnt lgkmcnt(0)
	v_add_f32_e32 v23, v23, v89
	s_nop 1
	v_mov_b32_dpp v89, v23 row_mirror row_mask:0xf bank_mask:0xf
	s_waitcnt lgkmcnt(0)
	v_add_f32_e32 v23, v23, v89
	v_fmamk_f32 v23, v23, 0x3c000000, v104
	v_cmp_gt_f32_e32 vcc, s15, v23
	v_mul_f32_e32 v89, 0x4f800000, v23
	s_nop 0
	v_cndmask_b32_e32 v23, v23, v89, vcc
	v_sqrt_f32_e32 v89, v23
	s_nop 0
	v_add_u32_e32 v94, -1, v89
	v_fma_f32 v95, -v94, v89, v23
	v_cmp_ge_f32_e64 s[38:39], 0, v95
	v_add_u32_e32 v95, 1, v89
	s_nop 0
	v_cndmask_b32_e64 v94, v89, v94, s[38:39]
	v_fma_f32 v89, -v95, v89, v23
	v_cmp_lt_f32_e64 s[38:39], 0, v89
	s_nop 1
	v_cndmask_b32_e64 v89, v94, v95, s[38:39]
	v_mul_f32_e32 v94, 0x37800000, v89
	v_cndmask_b32_e32 v89, v89, v94, vcc
	v_cmp_class_f32_e32 vcc, v23, v105
	s_nop 1
	v_cndmask_b32_e32 v23, v89, v23, vcc
	v_div_scale_f32 v89, s[16:17], v23, v23, 1.0
	v_rcp_f32_e32 v94, v89
	s_nop 0
	v_fma_f32 v95, -v89, v94, 1.0
	v_fmac_f32_e32 v94, v95, v94
	v_div_scale_f32 v95, vcc, 1.0, v23, 1.0
	v_mul_f32_e32 v108, v95, v94
	v_fma_f32 v109, -v89, v108, v95
	v_fmac_f32_e32 v108, v109, v94
	v_fma_f32 v89, -v89, v108, v95
	v_div_fmas_f32 v89, v89, v94, v108
	v_div_fixup_f32 v94, v89, v23, 1.0
	v_mov_b32_e32 v108, v92
	v_mov_b32_e32 v109, v90
	v_pk_mul_f32 v[108:109], v[94:95], v[108:109] op_sel_hi:[0,1]
	v_mov_b32_e32 v90, v93
	v_pk_mul_f32 v[92:93], v[0:1], v[108:109]
	v_mov_b32_e32 v108, v106
	v_mov_b32_e32 v109, v82
	v_mov_b32_e32 v82, v107
	v_pk_mul_f32 v[108:109], v[94:95], v[108:109] op_sel_hi:[0,1]
	v_pk_mul_f32 v[82:83], v[94:95], v[82:83] op_sel_hi:[0,1]
	v_pk_mul_f32 v[90:91], v[94:95], v[90:91] op_sel_hi:[0,1]
	v_pk_mul_f32 v[94:95], v[6:7], v[82:83]
	v_pk_mul_f32 v[106:107], v[4:5], v[108:109]
	v_pk_mul_f32 v[90:91], v[2:3], v[90:91]
	v_or_b32_e32 v82, 0x6000, v88
	v_pk_mul_f32 v[110:111], v[24:25], v[106:107]
	v_pk_mul_f32 v[112:113], v[28:29], v[94:95]
	v_ashrrev_i32_e32 v83, 31, v82
	v_pk_fma_f32 v[110:111], v[26:27], v[92:93], v[110:111] neg_lo:[0,0,1] neg_hi:[0,0,1]
	v_pk_fma_f32 v[112:113], v[30:31], v[90:91], v[112:113] neg_lo:[0,0,1] neg_hi:[0,0,1]
	v_pk_mul_f32 v[92:93], v[24:25], v[92:93]
	v_pk_mul_f32 v[90:91], v[28:29], v[90:91]
	v_lshlrev_b64 v[82:83], 8, v[82:83]
	v_pk_fma_f32 v[92:93], v[26:27], v[106:107], v[92:93]
	v_pk_fma_f32 v[90:91], v[30:31], v[94:95], v[90:91]
	v_lshl_add_u64 v[108:109], v[18:19], 0, v[82:83]
	v_cvt_pk_bf16_f32 v110, v110, v111
	v_cvt_pk_bf16_f32 v111, v112, v113
	v_cvt_pk_bf16_f32 v92, v92, v93
	v_cvt_pk_bf16_f32 v93, v90, v91
	s_waitcnt vmcnt(29)
; __device__ __forceinline__ unsigned cvt_pk_bf16(float lo, float hi) { f32x2_t v = {lo, hi}; bf16x2_t b = __builtin_convertvector(v, bf16x2_t); return __builtin_bit_cast(unsigned, b); }
; __device__ __forceinline__ float bflo(unsigned w) { return __uint_as_float(w << 16); }
; __device__ __forceinline__ float bfhi(unsigned w) { return __uint_as_float(w & 0xffff0000u); }
; __global__ void __launch_bounds__(NTHR, 2) mega_fwd(Args args) {
;     ...
;                 for (int hm = 0; hm < 16; ++hm) { r0[hm] = *(const v2u*)(src + hm * 128); r1[hm] = *(const v2u*)(src + hm * 128 + 64); }
; #pragma unroll
;                 for (int hm = 0; hm < 16; ++hm) {
;                     const f32x4 x1 = {pg8::bflo(r0[hm].x), pg8::bfhi(r0[hm].x), pg8::bflo(r0[hm].y), pg8::bfhi(r0[hm].y)}, x2 = {pg8::bflo(r1[hm].x), pg8::bfhi(r1[hm].x), pg8::bflo(r1[hm].y), pg8::bfhi(r1[hm].y)};
;                     float ss = (x1.x * x1.x + x1.y * x1.y) + (x1.z * x1.z + x1.w * x1.w) + (x2.x * x2.x + x2.y * x2.y) + (x2.z * x2.z + x2.w * x2.w);
;                     ss += __shfl_xor(ss, 1); ss += __shfl_xor(ss, 2); ss += __shfl_xor(ss, 4); ss += __shfl_xor(ss, 8);
;                     const float rs = 1.0f / sqrtf(ss * (1.f / 128.f) + EPS);
;                     const f32x4 y1 = x1 * rs * (hm < 8 ? qg0 : kg0), y2 = x2 * rs * (hm < 8 ? qg1 : kg1);
;                     bf16* dst = (hm < 8 ? QH : KH) + ((size_t)((b * 8 + (hm & 7)) * SEQ + sq)) * 128 + 4 * l16;
;                     v2u o1, o2;
;                     o1.x = pg8::cvt_pk_bf16(y1.x * cs[0] - y2.x * sn[0], y1.y * cs[1] - y2.y * sn[1]); o1.y = pg8::cvt_pk_bf16(y1.z * cs[2] - y2.z * sn[2], y1.w * cs[3] - y2.w * sn[3]);
;                     o2.x = pg8::cvt_pk_bf16(y2.x * cs[0] + y1.x * sn[0], y2.y * cs[1] + y1.y * sn[1]); o2.y = pg8::cvt_pk_bf16(y2.z * cs[2] + y1.z * sn[2], y2.w * cs[3] + y1.w * sn[3]);
;                     *(v2u*)dst = o1; *(v2u*)(dst + 64) = o2;
;                 }
	v_lshlrev_b32_e32 v91, 16, v87
	v_lshlrev_b32_e32 v90, 16, v86
	v_and_b32_e32 v87, 0xffff0000, v87
	v_and_b32_e32 v86, 0xffff0000, v86
	global_store_dwordx2 v[108:109], v[110:111], off
	global_store_dwordx2 v[108:109], v[92:93], off offset:128
	v_pk_mul_f32 v[92:93], v[86:87], v[86:87]
	s_waitcnt vmcnt(30)
	v_lshlrev_b32_e32 v95, 16, v85
	v_lshlrev_b32_e32 v94, 16, v84
	v_and_b32_e32 v85, 0xffff0000, v85
	v_and_b32_e32 v84, 0xffff0000, v84
	v_pk_fma_f32 v[92:93], v[90:91], v[90:91], v[92:93]
	v_pk_mul_f32 v[106:107], v[84:85], v[84:85]
	v_add_f32_e32 v23, v92, v93
	v_pk_fma_f32 v[106:107], v[94:95], v[94:95], v[106:107]
	s_nop 0
	v_add_f32_e32 v23, v23, v106
	v_add_f32_e32 v23, v107, v23
	s_nop 1
	v_mov_b32_dpp v89, v23 quad_perm:[1,0,3,2] row_mask:0xf bank_mask:0xf
	s_waitcnt lgkmcnt(0)
	v_add_f32_e32 v23, v23, v89
	s_nop 1
	v_mov_b32_dpp v89, v23 quad_perm:[2,3,0,1] row_mask:0xf bank_mask:0xf
	s_waitcnt lgkmcnt(0)
	v_add_f32_e32 v23, v23, v89
	s_nop 1
	v_mov_b32_dpp v89, v23 row_half_mirror row_mask:0xf bank_mask:0xf
	s_waitcnt lgkmcnt(0)
	v_add_f32_e32 v23, v23, v89
	s_nop 1
	v_mov_b32_dpp v89, v23 row_mirror row_mask:0xf bank_mask:0xf
	s_waitcnt lgkmcnt(0)
	v_add_f32_e32 v23, v23, v89
	v_fmamk_f32 v23, v23, 0x3c000000, v104
	v_cmp_gt_f32_e32 vcc, s15, v23
	v_mul_f32_e32 v89, 0x4f800000, v23
	s_nop 0
	v_cndmask_b32_e32 v23, v23, v89, vcc
	v_sqrt_f32_e32 v89, v23
	s_nop 0
	v_add_u32_e32 v92, -1, v89
	v_fma_f32 v93, -v92, v89, v23
	v_cmp_ge_f32_e64 s[38:39], 0, v93
	v_add_u32_e32 v93, 1, v89
	s_nop 0
	v_cndmask_b32_e64 v92, v89, v92, s[38:39]
	v_fma_f32 v89, -v93, v89, v23
	v_cmp_lt_f32_e64 s[38:39], 0, v89
	s_nop 1
	v_cndmask_b32_e64 v89, v92, v93, s[38:39]
	v_mul_f32_e32 v92, 0x37800000, v89
	v_cndmask_b32_e32 v89, v89, v92, vcc
	v_cmp_class_f32_e32 vcc, v23, v105
	s_nop 1
	v_cndmask_b32_e32 v23, v89, v23, vcc
	v_div_scale_f32 v89, s[16:17], v23, v23, 1.0
	v_rcp_f32_e32 v92, v89
	s_nop 0
	v_fma_f32 v93, -v89, v92, 1.0
	v_fmac_f32_e32 v92, v93, v92
	v_div_scale_f32 v93, vcc, 1.0, v23, 1.0
	v_mul_f32_e32 v106, v93, v92
	v_fma_f32 v107, -v89, v106, v93
	v_fmac_f32_e32 v106, v107, v92
	v_fma_f32 v89, -v89, v106, v93
	v_div_fmas_f32 v89, v89, v92, v106
	v_div_fixup_f32 v92, v89, v23, 1.0
	v_mov_b32_e32 v106, v90
	v_mov_b32_e32 v107, v86
	v_pk_mul_f32 v[106:107], v[92:93], v[106:107] op_sel_hi:[0,1]
	v_mov_b32_e32 v86, v91
	v_pk_mul_f32 v[90:91], v[0:1], v[106:107]
	v_mov_b32_e32 v106, v94
	v_mov_b32_e32 v107, v84
	v_mov_b32_e32 v84, v95
	v_pk_mul_f32 v[106:107], v[92:93], v[106:107] op_sel_hi:[0,1]
	v_pk_mul_f32 v[84:85], v[92:93], v[84:85] op_sel_hi:[0,1]
	v_pk_mul_f32 v[86:87], v[92:93], v[86:87] op_sel_hi:[0,1]
	v_pk_mul_f32 v[92:93], v[6:7], v[84:85]
	v_pk_mul_f32 v[94:95], v[4:5], v[106:107]
	v_pk_mul_f32 v[86:87], v[2:3], v[86:87]
	v_or_b32_e32 v84, 0x8000, v88
	v_pk_mul_f32 v[108:109], v[24:25], v[94:95]
	v_pk_mul_f32 v[110:111], v[28:29], v[92:93]
	v_ashrrev_i32_e32 v85, 31, v84
	v_pk_fma_f32 v[108:109], v[26:27], v[90:91], v[108:109] neg_lo:[0,0,1] neg_hi:[0,0,1]
	v_pk_fma_f32 v[110:111], v[30:31], v[86:87], v[110:111] neg_lo:[0,0,1] neg_hi:[0,0,1]
	v_pk_mul_f32 v[90:91], v[24:25], v[90:91]
	v_pk_mul_f32 v[86:87], v[28:29], v[86:87]
	v_lshlrev_b64 v[84:85], 8, v[84:85]
	v_pk_fma_f32 v[90:91], v[26:27], v[94:95], v[90:91]
	v_pk_fma_f32 v[86:87], v[30:31], v[92:93], v[86:87]
	v_lshl_add_u64 v[106:107], v[18:19], 0, v[84:85]
	v_cvt_pk_bf16_f32 v108, v108, v109
	v_cvt_pk_bf16_f32 v109, v110, v111
	v_cvt_pk_bf16_f32 v90, v90, v91
	v_cvt_pk_bf16_f32 v91, v86, v87
	s_waitcnt vmcnt(29)
	v_lshlrev_b32_e32 v87, 16, v75
	v_lshlrev_b32_e32 v86, 16, v74
	v_and_b32_e32 v75, 0xffff0000, v75
	v_and_b32_e32 v74, 0xffff0000, v74
	global_store_dwordx2 v[106:107], v[108:109], off
	global_store_dwordx2 v[106:107], v[90:91], off offset:128
	v_pk_mul_f32 v[90:91], v[74:75], v[74:75]
	s_waitcnt vmcnt(30)
	v_lshlrev_b32_e32 v93, 16, v73
	v_lshlrev_b32_e32 v92, 16, v72
	v_and_b32_e32 v73, 0xffff0000, v73
	v_and_b32_e32 v72, 0xffff0000, v72
	v_pk_fma_f32 v[90:91], v[86:87], v[86:87], v[90:91]
	v_pk_mul_f32 v[94:95], v[72:73], v[72:73]
	v_add_f32_e32 v23, v90, v91
	v_pk_fma_f32 v[94:95], v[92:93], v[92:93], v[94:95]
	s_nop 0
	v_add_f32_e32 v23, v23, v94
	v_add_f32_e32 v23, v95, v23
	s_nop 1
	v_mov_b32_dpp v89, v23 quad_perm:[1,0,3,2] row_mask:0xf bank_mask:0xf
	s_waitcnt lgkmcnt(0)
	v_add_f32_e32 v23, v23, v89
	s_nop 1
	v_mov_b32_dpp v89, v23 quad_perm:[2,3,0,1] row_mask:0xf bank_mask:0xf
	s_waitcnt lgkmcnt(0)
	v_add_f32_e32 v23, v23, v89
	s_nop 1
	v_mov_b32_dpp v89, v23 row_half_mirror row_mask:0xf bank_mask:0xf
	s_waitcnt lgkmcnt(0)
	v_add_f32_e32 v23, v23, v89
	s_nop 1
	v_mov_b32_dpp v89, v23 row_mirror row_mask:0xf bank_mask:0xf
	s_waitcnt lgkmcnt(0)
; __device__ __forceinline__ unsigned cvt_pk_bf16(float lo, float hi) { f32x2_t v = {lo, hi}; bf16x2_t b = __builtin_convertvector(v, bf16x2_t); return __builtin_bit_cast(unsigned, b); }
; __device__ __forceinline__ float bflo(unsigned w) { return __uint_as_float(w << 16); }
; __device__ __forceinline__ float bfhi(unsigned w) { return __uint_as_float(w & 0xffff0000u); }
; __global__ void __launch_bounds__(NTHR, 2) mega_fwd(Args args) {
;     ...
;                 for (int hm = 0; hm < 16; ++hm) { r0[hm] = *(const v2u*)(src + hm * 128); r1[hm] = *(const v2u*)(src + hm * 128 + 64); }
; #pragma unroll
;                 for (int hm = 0; hm < 16; ++hm) {
;                     const f32x4 x1 = {pg8::bflo(r0[hm].x), pg8::bfhi(r0[hm].x), pg8::bflo(r0[hm].y), pg8::bfhi(r0[hm].y)}, x2 = {pg8::bflo(r1[hm].x), pg8::bfhi(r1[hm].x), pg8::bflo(r1[hm].y), pg8::bfhi(r1[hm].y)};
;                     float ss = (x1.x * x1.x + x1.y * x1.y) + (x1.z * x1.z + x1.w * x1.w) + (x2.x * x2.x + x2.y * x2.y) + (x2.z * x2.z + x2.w * x2.w);
;                     ss += __shfl_xor(ss, 1); ss += __shfl_xor(ss, 2); ss += __shfl_xor(ss, 4); ss += __shfl_xor(ss, 8);
;                     const float rs = 1.0f / sqrtf(ss * (1.f / 128.f) + EPS);
;                     const f32x4 y1 = x1 * rs * (hm < 8 ? qg0 : kg0), y2 = x2 * rs * (hm < 8 ? qg1 : kg1);
;                     bf16* dst = (hm < 8 ? QH : KH) + ((size_t)((b * 8 + (hm & 7)) * SEQ + sq)) * 128 + 4 * l16;
;                     v2u o1, o2;
;                     o1.x = pg8::cvt_pk_bf16(y1.x * cs[0] - y2.x * sn[0], y1.y * cs[1] - y2.y * sn[1]); o1.y = pg8::cvt_pk_bf16(y1.z * cs[2] - y2.z * sn[2], y1.w * cs[3] - y2.w * sn[3]);
;                     o2.x = pg8::cvt_pk_bf16(y2.x * cs[0] + y1.x * sn[0], y2.y * cs[1] + y1.y * sn[1]); o2.y = pg8::cvt_pk_bf16(y2.z * cs[2] + y1.z * sn[2], y2.w * cs[3] + y1.w * sn[3]);
;                     *(v2u*)dst = o1; *(v2u*)(dst + 64) = o2;
;                 }
	v_add_f32_e32 v23, v23, v89
	v_fmamk_f32 v23, v23, 0x3c000000, v104
	v_cmp_gt_f32_e32 vcc, s15, v23
	v_mul_f32_e32 v89, 0x4f800000, v23
	s_nop 0
	v_cndmask_b32_e32 v23, v23, v89, vcc
	v_sqrt_f32_e32 v89, v23
	s_nop 0
	v_add_u32_e32 v90, -1, v89
	v_fma_f32 v91, -v90, v89, v23
	v_cmp_ge_f32_e64 s[38:39], 0, v91
	v_add_u32_e32 v91, 1, v89
	s_nop 0
	v_cndmask_b32_e64 v90, v89, v90, s[38:39]
	v_fma_f32 v89, -v91, v89, v23
	v_cmp_lt_f32_e64 s[38:39], 0, v89
	s_nop 1
	v_cndmask_b32_e64 v89, v90, v91, s[38:39]
	v_mul_f32_e32 v90, 0x37800000, v89
	v_cndmask_b32_e32 v89, v89, v90, vcc
	v_cmp_class_f32_e32 vcc, v23, v105
	s_nop 1
	v_cndmask_b32_e32 v23, v89, v23, vcc
	v_div_scale_f32 v89, s[16:17], v23, v23, 1.0
	v_rcp_f32_e32 v90, v89
	s_nop 0
	v_fma_f32 v91, -v89, v90, 1.0
	v_fmac_f32_e32 v90, v91, v90
	v_div_scale_f32 v91, vcc, 1.0, v23, 1.0
	v_mul_f32_e32 v94, v91, v90
	v_fma_f32 v95, -v89, v94, v91
	v_fmac_f32_e32 v94, v95, v90
	v_fma_f32 v89, -v89, v94, v91
	v_div_fmas_f32 v89, v89, v90, v94
	v_div_fixup_f32 v90, v89, v23, 1.0
	v_mov_b32_e32 v94, v86
	v_mov_b32_e32 v95, v74
	v_pk_mul_f32 v[94:95], v[90:91], v[94:95] op_sel_hi:[0,1]
	v_mov_b32_e32 v74, v87
	v_pk_mul_f32 v[86:87], v[0:1], v[94:95]
	v_mov_b32_e32 v94, v92
	v_mov_b32_e32 v95, v72
	v_mov_b32_e32 v72, v93
	v_pk_mul_f32 v[94:95], v[90:91], v[94:95] op_sel_hi:[0,1]
	v_pk_mul_f32 v[72:73], v[90:91], v[72:73] op_sel_hi:[0,1]
	v_pk_mul_f32 v[74:75], v[90:91], v[74:75] op_sel_hi:[0,1]
	v_pk_mul_f32 v[90:91], v[6:7], v[72:73]
	v_pk_mul_f32 v[92:93], v[4:5], v[94:95]
	v_pk_mul_f32 v[74:75], v[2:3], v[74:75]
	v_or_b32_e32 v72, 0xa000, v88
	v_pk_mul_f32 v[106:107], v[24:25], v[92:93]
	v_pk_mul_f32 v[108:109], v[28:29], v[90:91]
	v_ashrrev_i32_e32 v73, 31, v72
	v_pk_fma_f32 v[106:107], v[26:27], v[86:87], v[106:107] neg_lo:[0,0,1] neg_hi:[0,0,1]
	v_pk_fma_f32 v[108:109], v[30:31], v[74:75], v[108:109] neg_lo:[0,0,1] neg_hi:[0,0,1]
	v_pk_mul_f32 v[86:87], v[24:25], v[86:87]
	v_pk_mul_f32 v[74:75], v[28:29], v[74:75]
	v_lshlrev_b64 v[72:73], 8, v[72:73]
	v_pk_fma_f32 v[86:87], v[26:27], v[92:93], v[86:87]
	v_pk_fma_f32 v[74:75], v[30:31], v[90:91], v[74:75]
	v_lshl_add_u64 v[94:95], v[18:19], 0, v[72:73]
	v_cvt_pk_bf16_f32 v106, v106, v107
	v_cvt_pk_bf16_f32 v107, v108, v109
	v_cvt_pk_bf16_f32 v86, v86, v87
	v_cvt_pk_bf16_f32 v87, v74, v75
	s_waitcnt vmcnt(29)
	v_lshlrev_b32_e32 v75, 16, v71
	v_lshlrev_b32_e32 v74, 16, v70
	v_and_b32_e32 v71, 0xffff0000, v71
	v_and_b32_e32 v70, 0xffff0000, v70
	global_store_dwordx2 v[94:95], v[106:107], off
	global_store_dwordx2 v[94:95], v[86:87], off offset:128
	v_pk_mul_f32 v[86:87], v[70:71], v[70:71]
	s_waitcnt vmcnt(30)
	v_lshlrev_b32_e32 v91, 16, v69
	v_lshlrev_b32_e32 v90, 16, v68
	v_and_b32_e32 v69, 0xffff0000, v69
	v_and_b32_e32 v68, 0xffff0000, v68
	v_pk_fma_f32 v[86:87], v[74:75], v[74:75], v[86:87]
	v_pk_mul_f32 v[92:93], v[68:69], v[68:69]
	v_add_f32_e32 v23, v86, v87
	v_pk_fma_f32 v[92:93], v[90:91], v[90:91], v[92:93]
	s_nop 0
	v_add_f32_e32 v23, v23, v92
	v_add_f32_e32 v23, v93, v23
	s_nop 1
	v_mov_b32_dpp v86, v23 quad_perm:[1,0,3,2] row_mask:0xf bank_mask:0xf
	s_waitcnt lgkmcnt(0)
	v_add_f32_e32 v23, v23, v86
	s_nop 1
	v_mov_b32_dpp v86, v23 quad_perm:[2,3,0,1] row_mask:0xf bank_mask:0xf
	s_waitcnt lgkmcnt(0)
	v_add_f32_e32 v23, v23, v86
	s_nop 1
	v_mov_b32_dpp v86, v23 row_half_mirror row_mask:0xf bank_mask:0xf
	s_waitcnt lgkmcnt(0)
	v_add_f32_e32 v23, v23, v86
	s_nop 1
	v_mov_b32_dpp v86, v23 row_mirror row_mask:0xf bank_mask:0xf
	s_waitcnt lgkmcnt(0)
	v_add_f32_e32 v23, v23, v86
	v_fmamk_f32 v23, v23, 0x3c000000, v104
	v_cmp_gt_f32_e32 vcc, s15, v23
	v_mul_f32_e32 v86, 0x4f800000, v23
	s_nop 0
	v_cndmask_b32_e32 v23, v23, v86, vcc
	v_sqrt_f32_e32 v86, v23
	s_nop 0
	v_add_u32_e32 v87, -1, v86
	v_fma_f32 v89, -v87, v86, v23
	v_cmp_ge_f32_e64 s[38:39], 0, v89
	v_add_u32_e32 v89, 1, v86
	s_nop 0
	v_cndmask_b32_e64 v87, v86, v87, s[38:39]
	v_fma_f32 v86, -v89, v86, v23
	v_cmp_lt_f32_e64 s[38:39], 0, v86
	s_nop 1
	v_cndmask_b32_e64 v86, v87, v89, s[38:39]
	v_mul_f32_e32 v87, 0x37800000, v86
	v_cndmask_b32_e32 v86, v86, v87, vcc
	v_cmp_class_f32_e32 vcc, v23, v105
	s_nop 1
	v_cndmask_b32_e32 v23, v86, v23, vcc
	v_div_scale_f32 v86, s[16:17], v23, v23, 1.0
	v_rcp_f32_e32 v87, v86
	s_nop 0
	v_fma_f32 v89, -v86, v87, 1.0
	v_fmac_f32_e32 v87, v89, v87
	v_div_scale_f32 v89, vcc, 1.0, v23, 1.0
	v_mul_f32_e32 v92, v89, v87
	v_fma_f32 v93, -v86, v92, v89
	v_fmac_f32_e32 v92, v93, v87
	v_fma_f32 v86, -v86, v92, v89
	v_div_fmas_f32 v86, v86, v87, v92
	v_div_fixup_f32 v86, v86, v23, 1.0
	v_mov_b32_e32 v92, v74
	v_mov_b32_e32 v93, v70
	v_pk_mul_f32 v[92:93], v[86:87], v[92:93] op_sel_hi:[0,1]
	v_mov_b32_e32 v70, v75
	v_pk_mul_f32 v[74:75], v[0:1], v[92:93]
	v_mov_b32_e32 v92, v90
	v_mov_b32_e32 v93, v68
	v_mov_b32_e32 v68, v91
	v_pk_mul_f32 v[92:93], v[86:87], v[92:93] op_sel_hi:[0,1]
	v_pk_mul_f32 v[68:69], v[86:87], v[68:69] op_sel_hi:[0,1]
	v_pk_mul_f32 v[70:71], v[86:87], v[70:71] op_sel_hi:[0,1]
	v_pk_mul_f32 v[86:87], v[6:7], v[68:69]
	v_pk_mul_f32 v[90:91], v[4:5], v[92:93]
	v_pk_mul_f32 v[70:71], v[2:3], v[70:71]
	v_or_b32_e32 v68, 0xc000, v88
	v_pk_mul_f32 v[94:95], v[24:25], v[90:91]
	v_pk_mul_f32 v[106:107], v[28:29], v[86:87]
	v_ashrrev_i32_e32 v69, 31, v68
	v_pk_fma_f32 v[94:95], v[26:27], v[74:75], v[94:95] neg_lo:[0,0,1] neg_hi:[0,0,1]
	v_pk_fma_f32 v[106:107], v[30:31], v[70:71], v[106:107] neg_lo:[0,0,1] neg_hi:[0,0,1]
	v_pk_mul_f32 v[74:75], v[24:25], v[74:75]
	v_pk_mul_f32 v[70:71], v[28:29], v[70:71]
	v_lshlrev_b64 v[68:69], 8, v[68:69]
	v_pk_fma_f32 v[74:75], v[26:27], v[90:91], v[74:75]
	v_pk_fma_f32 v[70:71], v[30:31], v[86:87], v[70:71]
	v_lshl_add_u64 v[92:93], v[18:19], 0, v[68:69]
	v_cvt_pk_bf16_f32 v94, v94, v95
	v_cvt_pk_bf16_f32 v95, v106, v107
	v_cvt_pk_bf16_f32 v74, v74, v75
	v_cvt_pk_bf16_f32 v75, v70, v71
	s_waitcnt vmcnt(29)
; __device__ __forceinline__ unsigned cvt_pk_bf16(float lo, float hi) { f32x2_t v = {lo, hi}; bf16x2_t b = __builtin_convertvector(v, bf16x2_t); return __builtin_bit_cast(unsigned, b); }
; __device__ __forceinline__ float bflo(unsigned w) { return __uint_as_float(w << 16); }
; __device__ __forceinline__ float bfhi(unsigned w) { return __uint_as_float(w & 0xffff0000u); }
; __global__ void __launch_bounds__(NTHR, 2) mega_fwd(Args args) {
;     ...
;                 for (int hm = 0; hm < 16; ++hm) { r0[hm] = *(const v2u*)(src + hm * 128); r1[hm] = *(const v2u*)(src + hm * 128 + 64); }
; #pragma unroll
;                 for (int hm = 0; hm < 16; ++hm) {
;                     const f32x4 x1 = {pg8::bflo(r0[hm].x), pg8::bfhi(r0[hm].x), pg8::bflo(r0[hm].y), pg8::bfhi(r0[hm].y)}, x2 = {pg8::bflo(r1[hm].x), pg8::bfhi(r1[hm].x), pg8::bflo(r1[hm].y), pg8::bfhi(r1[hm].y)};
;                     float ss = (x1.x * x1.x + x1.y * x1.y) + (x1.z * x1.z + x1.w * x1.w) + (x2.x * x2.x + x2.y * x2.y) + (x2.z * x2.z + x2.w * x2.w);
;                     ss += __shfl_xor(ss, 1); ss += __shfl_xor(ss, 2); ss += __shfl_xor(ss, 4); ss += __shfl_xor(ss, 8);
;                     const float rs = 1.0f / sqrtf(ss * (1.f / 128.f) + EPS);
;                     const f32x4 y1 = x1 * rs * (hm < 8 ? qg0 : kg0), y2 = x2 * rs * (hm < 8 ? qg1 : kg1);
;                     bf16* dst = (hm < 8 ? QH : KH) + ((size_t)((b * 8 + (hm & 7)) * SEQ + sq)) * 128 + 4 * l16;
;                     v2u o1, o2;
;                     o1.x = pg8::cvt_pk_bf16(y1.x * cs[0] - y2.x * sn[0], y1.y * cs[1] - y2.y * sn[1]); o1.y = pg8::cvt_pk_bf16(y1.z * cs[2] - y2.z * sn[2], y1.w * cs[3] - y2.w * sn[3]);
;                     o2.x = pg8::cvt_pk_bf16(y2.x * cs[0] + y1.x * sn[0], y2.y * cs[1] + y1.y * sn[1]); o2.y = pg8::cvt_pk_bf16(y2.z * cs[2] + y1.z * sn[2], y2.w * cs[3] + y1.w * sn[3]);
;                     *(v2u*)dst = o1; *(v2u*)(dst + 64) = o2;
;                 }
	v_lshlrev_b32_e32 v71, 16, v67
	v_lshlrev_b32_e32 v70, 16, v66
	v_and_b32_e32 v67, 0xffff0000, v67
	v_and_b32_e32 v66, 0xffff0000, v66
	global_store_dwordx2 v[92:93], v[94:95], off
	global_store_dwordx2 v[92:93], v[74:75], off offset:128
	v_pk_mul_f32 v[74:75], v[66:67], v[66:67]
	s_waitcnt vmcnt(30)
	v_lshlrev_b32_e32 v87, 16, v65
	v_lshlrev_b32_e32 v86, 16, v64
	v_and_b32_e32 v65, 0xffff0000, v65
	v_and_b32_e32 v64, 0xffff0000, v64
	v_pk_fma_f32 v[74:75], v[70:71], v[70:71], v[74:75]
	v_pk_mul_f32 v[90:91], v[64:65], v[64:65]
	v_add_f32_e32 v23, v74, v75
	v_pk_fma_f32 v[90:91], v[86:87], v[86:87], v[90:91]
	s_nop 0
	v_add_f32_e32 v23, v23, v90
	v_add_f32_e32 v23, v91, v23
	s_nop 1
	v_mov_b32_dpp v74, v23 quad_perm:[1,0,3,2] row_mask:0xf bank_mask:0xf
	s_waitcnt lgkmcnt(0)
	v_add_f32_e32 v23, v23, v74
	s_nop 1
	v_mov_b32_dpp v74, v23 quad_perm:[2,3,0,1] row_mask:0xf bank_mask:0xf
	s_waitcnt lgkmcnt(0)
	v_add_f32_e32 v23, v23, v74
	s_nop 1
	v_mov_b32_dpp v74, v23 row_half_mirror row_mask:0xf bank_mask:0xf
	s_waitcnt lgkmcnt(0)
	v_add_f32_e32 v23, v23, v74
	s_nop 1
	v_mov_b32_dpp v74, v23 row_mirror row_mask:0xf bank_mask:0xf
	s_waitcnt lgkmcnt(0)
	v_add_f32_e32 v23, v23, v74
	v_fmamk_f32 v23, v23, 0x3c000000, v104
	v_cmp_gt_f32_e32 vcc, s15, v23
	v_mul_f32_e32 v74, 0x4f800000, v23
	s_nop 0
	v_cndmask_b32_e32 v23, v23, v74, vcc
	v_sqrt_f32_e32 v74, v23
	s_nop 0
	v_add_u32_e32 v75, -1, v74
	v_fma_f32 v89, -v75, v74, v23
	v_cmp_ge_f32_e64 s[38:39], 0, v89
	v_add_u32_e32 v89, 1, v74
	s_nop 0
	v_cndmask_b32_e64 v75, v74, v75, s[38:39]
	v_fma_f32 v74, -v89, v74, v23
	v_cmp_lt_f32_e64 s[38:39], 0, v74
	s_nop 1
	v_cndmask_b32_e64 v74, v75, v89, s[38:39]
	v_mul_f32_e32 v75, 0x37800000, v74
	v_cndmask_b32_e32 v74, v74, v75, vcc
	v_cmp_class_f32_e32 vcc, v23, v105
	s_nop 1
	v_cndmask_b32_e32 v23, v74, v23, vcc
	v_div_scale_f32 v74, s[16:17], v23, v23, 1.0
	v_rcp_f32_e32 v75, v74
	s_nop 0
	v_fma_f32 v89, -v74, v75, 1.0
	v_fmac_f32_e32 v75, v89, v75
	v_div_scale_f32 v89, vcc, 1.0, v23, 1.0
	v_mul_f32_e32 v90, v89, v75
	v_fma_f32 v91, -v74, v90, v89
	v_fmac_f32_e32 v90, v91, v75
	v_fma_f32 v74, -v74, v90, v89
	v_div_fmas_f32 v74, v74, v75, v90
	v_div_fixup_f32 v74, v74, v23, 1.0
	v_mov_b32_e32 v90, v70
	v_mov_b32_e32 v91, v66
	v_pk_mul_f32 v[90:91], v[74:75], v[90:91] op_sel_hi:[0,1]
	v_mov_b32_e32 v66, v71
	v_pk_mul_f32 v[70:71], v[0:1], v[90:91]
	v_mov_b32_e32 v90, v86
	v_mov_b32_e32 v91, v64
	v_mov_b32_e32 v64, v87
	v_pk_mul_f32 v[90:91], v[74:75], v[90:91] op_sel_hi:[0,1]
	v_pk_mul_f32 v[64:65], v[74:75], v[64:65] op_sel_hi:[0,1]
	v_pk_mul_f32 v[66:67], v[74:75], v[66:67] op_sel_hi:[0,1]
	v_pk_mul_f32 v[74:75], v[6:7], v[64:65]
	v_pk_mul_f32 v[86:87], v[4:5], v[90:91]
	v_pk_mul_f32 v[66:67], v[2:3], v[66:67]
	v_or_b32_e32 v64, 0xe000, v88
	v_pk_mul_f32 v[90:91], v[24:25], v[86:87]
	v_pk_mul_f32 v[92:93], v[28:29], v[74:75]
	v_ashrrev_i32_e32 v65, 31, v64
	v_pk_fma_f32 v[90:91], v[26:27], v[70:71], v[90:91] neg_lo:[0,0,1] neg_hi:[0,0,1]
	v_pk_fma_f32 v[92:93], v[30:31], v[66:67], v[92:93] neg_lo:[0,0,1] neg_hi:[0,0,1]
	v_pk_mul_f32 v[70:71], v[24:25], v[70:71]
	v_pk_mul_f32 v[66:67], v[28:29], v[66:67]
	v_lshlrev_b64 v[64:65], 8, v[64:65]
	v_pk_fma_f32 v[70:71], v[26:27], v[86:87], v[70:71]
	v_pk_fma_f32 v[66:67], v[30:31], v[74:75], v[66:67]
	v_lshl_add_u64 v[88:89], v[18:19], 0, v[64:65]
	v_cvt_pk_bf16_f32 v90, v90, v91
	v_cvt_pk_bf16_f32 v91, v92, v93
	v_cvt_pk_bf16_f32 v70, v70, v71
	v_cvt_pk_bf16_f32 v71, v66, v67
	s_waitcnt vmcnt(29)
	v_lshlrev_b32_e32 v67, 16, v63
	v_lshlrev_b32_e32 v66, 16, v62
	v_and_b32_e32 v63, 0xffff0000, v63
	v_and_b32_e32 v62, 0xffff0000, v62
	global_store_dwordx2 v[88:89], v[90:91], off
	global_store_dwordx2 v[88:89], v[70:71], off offset:128
	v_pk_mul_f32 v[70:71], v[62:63], v[62:63]
	s_waitcnt vmcnt(30)
	v_lshlrev_b32_e32 v75, 16, v61
	v_lshlrev_b32_e32 v74, 16, v60
	v_and_b32_e32 v61, 0xffff0000, v61
	v_and_b32_e32 v60, 0xffff0000, v60
	v_pk_fma_f32 v[70:71], v[66:67], v[66:67], v[70:71]
	v_pk_mul_f32 v[86:87], v[60:61], v[60:61]
	v_add_f32_e32 v23, v70, v71
	v_pk_fma_f32 v[86:87], v[74:75], v[74:75], v[86:87]
	s_nop 0
	v_add_f32_e32 v23, v23, v86
	v_add_f32_e32 v23, v87, v23
	s_nop 1
	v_mov_b32_dpp v70, v23 quad_perm:[1,0,3,2] row_mask:0xf bank_mask:0xf
	s_waitcnt lgkmcnt(0)
	v_add_f32_e32 v23, v23, v70
	s_nop 1
	v_mov_b32_dpp v70, v23 quad_perm:[2,3,0,1] row_mask:0xf bank_mask:0xf
	s_waitcnt lgkmcnt(0)
	v_add_f32_e32 v23, v23, v70
	s_nop 1
	v_mov_b32_dpp v70, v23 row_half_mirror row_mask:0xf bank_mask:0xf
	s_waitcnt lgkmcnt(0)
	v_add_f32_e32 v23, v23, v70
	s_nop 1
	v_mov_b32_dpp v70, v23 row_mirror row_mask:0xf bank_mask:0xf
	s_waitcnt lgkmcnt(0)
; __device__ __forceinline__ unsigned cvt_pk_bf16(float lo, float hi) { f32x2_t v = {lo, hi}; bf16x2_t b = __builtin_convertvector(v, bf16x2_t); return __builtin_bit_cast(unsigned, b); }
; __device__ __forceinline__ float bflo(unsigned w) { return __uint_as_float(w << 16); }
; __device__ __forceinline__ float bfhi(unsigned w) { return __uint_as_float(w & 0xffff0000u); }
; __global__ void __launch_bounds__(NTHR, 2) mega_fwd(Args args) {
;     ...
;                 for (int hm = 0; hm < 16; ++hm) { r0[hm] = *(const v2u*)(src + hm * 128); r1[hm] = *(const v2u*)(src + hm * 128 + 64); }
; #pragma unroll
;                 for (int hm = 0; hm < 16; ++hm) {
;                     const f32x4 x1 = {pg8::bflo(r0[hm].x), pg8::bfhi(r0[hm].x), pg8::bflo(r0[hm].y), pg8::bfhi(r0[hm].y)}, x2 = {pg8::bflo(r1[hm].x), pg8::bfhi(r1[hm].x), pg8::bflo(r1[hm].y), pg8::bfhi(r1[hm].y)};
;                     float ss = (x1.x * x1.x + x1.y * x1.y) + (x1.z * x1.z + x1.w * x1.w) + (x2.x * x2.x + x2.y * x2.y) + (x2.z * x2.z + x2.w * x2.w);
;                     ss += __shfl_xor(ss, 1); ss += __shfl_xor(ss, 2); ss += __shfl_xor(ss, 4); ss += __shfl_xor(ss, 8);
;                     const float rs = 1.0f / sqrtf(ss * (1.f / 128.f) + EPS);
;                     const f32x4 y1 = x1 * rs * (hm < 8 ? qg0 : kg0), y2 = x2 * rs * (hm < 8 ? qg1 : kg1);
;                     bf16* dst = (hm < 8 ? QH : KH) + ((size_t)((b * 8 + (hm & 7)) * SEQ + sq)) * 128 + 4 * l16;
;                     v2u o1, o2;
;                     o1.x = pg8::cvt_pk_bf16(y1.x * cs[0] - y2.x * sn[0], y1.y * cs[1] - y2.y * sn[1]); o1.y = pg8::cvt_pk_bf16(y1.z * cs[2] - y2.z * sn[2], y1.w * cs[3] - y2.w * sn[3]);
;                     o2.x = pg8::cvt_pk_bf16(y2.x * cs[0] + y1.x * sn[0], y2.y * cs[1] + y1.y * sn[1]); o2.y = pg8::cvt_pk_bf16(y2.z * cs[2] + y1.z * sn[2], y2.w * cs[3] + y1.w * sn[3]);
;                     *(v2u*)dst = o1; *(v2u*)(dst + 64) = o2;
;                 }
	v_add_f32_e32 v23, v23, v70
	v_fmamk_f32 v23, v23, 0x3c000000, v104
	v_cmp_gt_f32_e32 vcc, s15, v23
	v_mul_f32_e32 v70, 0x4f800000, v23
	s_nop 0
	v_cndmask_b32_e32 v23, v23, v70, vcc
	v_sqrt_f32_e32 v70, v23
	s_nop 0
	v_add_u32_e32 v71, -1, v70
	v_fma_f32 v86, -v71, v70, v23
	v_cmp_ge_f32_e64 s[38:39], 0, v86
	v_add_u32_e32 v86, 1, v70
	s_nop 0
	v_cndmask_b32_e64 v71, v70, v71, s[38:39]
	v_fma_f32 v70, -v86, v70, v23
	v_cmp_lt_f32_e64 s[38:39], 0, v70
	s_nop 1
	v_cndmask_b32_e64 v70, v71, v86, s[38:39]
	v_mul_f32_e32 v71, 0x37800000, v70
	v_cndmask_b32_e32 v70, v70, v71, vcc
	v_cmp_class_f32_e32 vcc, v23, v105
	s_nop 1
	v_cndmask_b32_e32 v23, v70, v23, vcc
	v_div_scale_f32 v70, s[16:17], v23, v23, 1.0
	v_rcp_f32_e32 v71, v70
	s_nop 0
	v_fma_f32 v86, -v70, v71, 1.0
	v_fmac_f32_e32 v71, v86, v71
	v_div_scale_f32 v86, vcc, 1.0, v23, 1.0
	v_mul_f32_e32 v87, v86, v71
	v_fma_f32 v88, -v70, v87, v86
	v_fmac_f32_e32 v87, v88, v71
	v_fma_f32 v70, -v70, v87, v86
	v_div_fmas_f32 v70, v70, v71, v87
	v_div_fixup_f32 v70, v70, v23, 1.0
	v_mov_b32_e32 v86, v66
	v_mov_b32_e32 v87, v62
	v_pk_mul_f32 v[86:87], v[70:71], v[86:87] op_sel_hi:[0,1]
	v_mov_b32_e32 v62, v67
	v_pk_mul_f32 v[66:67], v[8:9], v[86:87]
	v_mov_b32_e32 v86, v74
	v_mov_b32_e32 v87, v60
	v_mov_b32_e32 v60, v75
	v_pk_mul_f32 v[86:87], v[70:71], v[86:87] op_sel_hi:[0,1]
	v_pk_mul_f32 v[60:61], v[70:71], v[60:61] op_sel_hi:[0,1]
	v_pk_mul_f32 v[62:63], v[70:71], v[62:63] op_sel_hi:[0,1]
	v_pk_mul_f32 v[60:61], v[14:15], v[60:61]
	v_pk_mul_f32 v[70:71], v[12:13], v[86:87]
	v_pk_mul_f32 v[62:63], v[10:11], v[62:63]
	v_lshl_add_u64 v[74:75], v[20:21], 0, v[76:77]
	v_pk_mul_f32 v[76:77], v[24:25], v[70:71]
	v_pk_mul_f32 v[86:87], v[28:29], v[60:61]
	v_pk_fma_f32 v[76:77], v[26:27], v[66:67], v[76:77] neg_lo:[0,0,1] neg_hi:[0,0,1]
	v_pk_fma_f32 v[86:87], v[30:31], v[62:63], v[86:87] neg_lo:[0,0,1] neg_hi:[0,0,1]
	v_pk_mul_f32 v[66:67], v[24:25], v[66:67]
	v_pk_mul_f32 v[62:63], v[28:29], v[62:63]
	v_pk_fma_f32 v[66:67], v[26:27], v[70:71], v[66:67]
	v_pk_fma_f32 v[60:61], v[30:31], v[60:61], v[62:63]
	v_cvt_pk_bf16_f32 v76, v76, v77
	v_cvt_pk_bf16_f32 v77, v86, v87
	v_cvt_pk_bf16_f32 v66, v66, v67
	v_cvt_pk_bf16_f32 v67, v60, v61
	s_waitcnt vmcnt(29)
	v_lshlrev_b32_e32 v61, 16, v59
	v_lshlrev_b32_e32 v60, 16, v58
	v_and_b32_e32 v59, 0xffff0000, v59
	v_and_b32_e32 v58, 0xffff0000, v58
	global_store_dwordx2 v[74:75], v[76:77], off
	global_store_dwordx2 v[74:75], v[66:67], off offset:128
	v_pk_mul_f32 v[62:63], v[58:59], v[58:59]
	s_waitcnt vmcnt(30)
	v_lshlrev_b32_e32 v67, 16, v57
	v_lshlrev_b32_e32 v66, 16, v56
	v_and_b32_e32 v57, 0xffff0000, v57
	v_and_b32_e32 v56, 0xffff0000, v56
	v_pk_fma_f32 v[62:63], v[60:61], v[60:61], v[62:63]
	v_pk_mul_f32 v[70:71], v[56:57], v[56:57]
	v_add_f32_e32 v23, v62, v63
	v_pk_fma_f32 v[70:71], v[66:67], v[66:67], v[70:71]
	s_nop 0
	v_add_f32_e32 v23, v23, v70
	v_add_f32_e32 v23, v71, v23
	s_nop 1
	v_mov_b32_dpp v62, v23 quad_perm:[1,0,3,2] row_mask:0xf bank_mask:0xf
	s_waitcnt lgkmcnt(0)
	v_add_f32_e32 v23, v23, v62
	s_nop 1
	v_mov_b32_dpp v62, v23 quad_perm:[2,3,0,1] row_mask:0xf bank_mask:0xf
	s_waitcnt lgkmcnt(0)
	v_add_f32_e32 v23, v23, v62
	s_nop 1
	v_mov_b32_dpp v62, v23 row_half_mirror row_mask:0xf bank_mask:0xf
	s_waitcnt lgkmcnt(0)
	v_add_f32_e32 v23, v23, v62
	s_nop 1
	v_mov_b32_dpp v62, v23 row_mirror row_mask:0xf bank_mask:0xf
	s_waitcnt lgkmcnt(0)
	v_add_f32_e32 v23, v23, v62
	v_fmamk_f32 v23, v23, 0x3c000000, v104
	v_cmp_gt_f32_e32 vcc, s15, v23
	v_mul_f32_e32 v62, 0x4f800000, v23
	s_nop 0
	v_cndmask_b32_e32 v23, v23, v62, vcc
	v_sqrt_f32_e32 v62, v23
	s_nop 0
	v_add_u32_e32 v63, -1, v62
	v_fma_f32 v70, -v63, v62, v23
	v_cmp_ge_f32_e64 s[38:39], 0, v70
	v_add_u32_e32 v70, 1, v62
	s_nop 0
	v_cndmask_b32_e64 v63, v62, v63, s[38:39]
	v_fma_f32 v62, -v70, v62, v23
	v_cmp_lt_f32_e64 s[38:39], 0, v62
	s_nop 1
	v_cndmask_b32_e64 v62, v63, v70, s[38:39]
	v_mul_f32_e32 v63, 0x37800000, v62
	v_cndmask_b32_e32 v62, v62, v63, vcc
	v_cmp_class_f32_e32 vcc, v23, v105
	s_nop 1
	v_cndmask_b32_e32 v23, v62, v23, vcc
	v_div_scale_f32 v62, s[16:17], v23, v23, 1.0
	v_rcp_f32_e32 v63, v62
	s_nop 0
	v_fma_f32 v70, -v62, v63, 1.0
	v_fmac_f32_e32 v63, v70, v63
	v_div_scale_f32 v70, vcc, 1.0, v23, 1.0
	v_mul_f32_e32 v71, v70, v63
	v_fma_f32 v74, -v62, v71, v70
	v_fmac_f32_e32 v71, v74, v63
	v_fma_f32 v62, -v62, v71, v70
	v_div_fmas_f32 v62, v62, v63, v71
	v_div_fixup_f32 v62, v62, v23, 1.0
	v_mov_b32_e32 v70, v60
	v_mov_b32_e32 v71, v58
	v_pk_mul_f32 v[70:71], v[62:63], v[70:71] op_sel_hi:[0,1]
	v_mov_b32_e32 v58, v61
	v_pk_mul_f32 v[60:61], v[8:9], v[70:71]
	v_mov_b32_e32 v70, v66
	v_mov_b32_e32 v71, v56
	v_mov_b32_e32 v56, v67
	v_pk_mul_f32 v[70:71], v[62:63], v[70:71] op_sel_hi:[0,1]
	v_pk_mul_f32 v[56:57], v[62:63], v[56:57] op_sel_hi:[0,1]
	v_pk_mul_f32 v[58:59], v[62:63], v[58:59] op_sel_hi:[0,1]
	v_pk_mul_f32 v[56:57], v[14:15], v[56:57]
	v_pk_mul_f32 v[62:63], v[12:13], v[70:71]
	v_pk_mul_f32 v[58:59], v[10:11], v[58:59]
	v_pk_mul_f32 v[70:71], v[24:25], v[62:63]
	v_pk_mul_f32 v[74:75], v[28:29], v[56:57]
	v_pk_fma_f32 v[70:71], v[26:27], v[60:61], v[70:71] neg_lo:[0,0,1] neg_hi:[0,0,1]
	v_pk_fma_f32 v[74:75], v[30:31], v[58:59], v[74:75] neg_lo:[0,0,1] neg_hi:[0,0,1]
	v_pk_mul_f32 v[60:61], v[24:25], v[60:61]
	v_pk_mul_f32 v[58:59], v[28:29], v[58:59]
	v_pk_fma_f32 v[60:61], v[26:27], v[62:63], v[60:61]
	v_pk_fma_f32 v[56:57], v[30:31], v[56:57], v[58:59]
	v_lshl_add_u64 v[66:67], v[20:21], 0, v[78:79]
	v_cvt_pk_bf16_f32 v70, v70, v71
	v_cvt_pk_bf16_f32 v71, v74, v75
	v_cvt_pk_bf16_f32 v60, v60, v61
	v_cvt_pk_bf16_f32 v61, v56, v57
	s_waitcnt vmcnt(29)
; __device__ __forceinline__ unsigned cvt_pk_bf16(float lo, float hi) { f32x2_t v = {lo, hi}; bf16x2_t b = __builtin_convertvector(v, bf16x2_t); return __builtin_bit_cast(unsigned, b); }
; __device__ __forceinline__ float bflo(unsigned w) { return __uint_as_float(w << 16); }
; __device__ __forceinline__ float bfhi(unsigned w) { return __uint_as_float(w & 0xffff0000u); }
; __global__ void __launch_bounds__(NTHR, 2) mega_fwd(Args args) {
;     ...
;                 for (int hm = 0; hm < 16; ++hm) { r0[hm] = *(const v2u*)(src + hm * 128); r1[hm] = *(const v2u*)(src + hm * 128 + 64); }
; #pragma unroll
;                 for (int hm = 0; hm < 16; ++hm) {
;                     const f32x4 x1 = {pg8::bflo(r0[hm].x), pg8::bfhi(r0[hm].x), pg8::bflo(r0[hm].y), pg8::bfhi(r0[hm].y)}, x2 = {pg8::bflo(r1[hm].x), pg8::bfhi(r1[hm].x), pg8::bflo(r1[hm].y), pg8::bfhi(r1[hm].y)};
;                     float ss = (x1.x * x1.x + x1.y * x1.y) + (x1.z * x1.z + x1.w * x1.w) + (x2.x * x2.x + x2.y * x2.y) + (x2.z * x2.z + x2.w * x2.w);
;                     ss += __shfl_xor(ss, 1); ss += __shfl_xor(ss, 2); ss += __shfl_xor(ss, 4); ss += __shfl_xor(ss, 8);
;                     const float rs = 1.0f / sqrtf(ss * (1.f / 128.f) + EPS);
;                     const f32x4 y1 = x1 * rs * (hm < 8 ? qg0 : kg0), y2 = x2 * rs * (hm < 8 ? qg1 : kg1);
;                     bf16* dst = (hm < 8 ? QH : KH) + ((size_t)((b * 8 + (hm & 7)) * SEQ + sq)) * 128 + 4 * l16;
;                     v2u o1, o2;
;                     o1.x = pg8::cvt_pk_bf16(y1.x * cs[0] - y2.x * sn[0], y1.y * cs[1] - y2.y * sn[1]); o1.y = pg8::cvt_pk_bf16(y1.z * cs[2] - y2.z * sn[2], y1.w * cs[3] - y2.w * sn[3]);
;                     o2.x = pg8::cvt_pk_bf16(y2.x * cs[0] + y1.x * sn[0], y2.y * cs[1] + y1.y * sn[1]); o2.y = pg8::cvt_pk_bf16(y2.z * cs[2] + y1.z * sn[2], y2.w * cs[3] + y1.w * sn[3]);
;                     *(v2u*)dst = o1; *(v2u*)(dst + 64) = o2;
;                 }
	v_lshlrev_b32_e32 v57, 16, v55
	v_lshlrev_b32_e32 v56, 16, v54
	v_and_b32_e32 v55, 0xffff0000, v55
	v_and_b32_e32 v54, 0xffff0000, v54
	global_store_dwordx2 v[66:67], v[70:71], off
	global_store_dwordx2 v[66:67], v[60:61], off offset:128
	v_pk_mul_f32 v[58:59], v[54:55], v[54:55]
	s_waitcnt vmcnt(30)
	v_lshlrev_b32_e32 v61, 16, v53
	v_lshlrev_b32_e32 v60, 16, v52
	v_and_b32_e32 v53, 0xffff0000, v53
	v_and_b32_e32 v52, 0xffff0000, v52
	v_pk_fma_f32 v[58:59], v[56:57], v[56:57], v[58:59]
	v_pk_mul_f32 v[62:63], v[52:53], v[52:53]
	v_add_f32_e32 v23, v58, v59
	v_pk_fma_f32 v[62:63], v[60:61], v[60:61], v[62:63]
	s_nop 0
	v_add_f32_e32 v23, v23, v62
	v_add_f32_e32 v23, v63, v23
	s_nop 1
	v_mov_b32_dpp v58, v23 quad_perm:[1,0,3,2] row_mask:0xf bank_mask:0xf
	s_waitcnt lgkmcnt(0)
	v_add_f32_e32 v23, v23, v58
	s_nop 1
	v_mov_b32_dpp v58, v23 quad_perm:[2,3,0,1] row_mask:0xf bank_mask:0xf
	s_waitcnt lgkmcnt(0)
	v_add_f32_e32 v23, v23, v58
	s_nop 1
	v_mov_b32_dpp v58, v23 row_half_mirror row_mask:0xf bank_mask:0xf
	s_waitcnt lgkmcnt(0)
	v_add_f32_e32 v23, v23, v58
	s_nop 1
	v_mov_b32_dpp v58, v23 row_mirror row_mask:0xf bank_mask:0xf
	s_waitcnt lgkmcnt(0)
	v_add_f32_e32 v23, v23, v58
	v_fmamk_f32 v23, v23, 0x3c000000, v104
	v_cmp_gt_f32_e32 vcc, s15, v23
	v_mul_f32_e32 v58, 0x4f800000, v23
	s_nop 0
	v_cndmask_b32_e32 v23, v23, v58, vcc
	v_sqrt_f32_e32 v58, v23
	s_nop 0
	v_add_u32_e32 v59, -1, v58
	v_fma_f32 v62, -v59, v58, v23
	v_cmp_ge_f32_e64 s[38:39], 0, v62
	v_add_u32_e32 v62, 1, v58
	s_nop 0
	v_cndmask_b32_e64 v59, v58, v59, s[38:39]
	v_fma_f32 v58, -v62, v58, v23
	v_cmp_lt_f32_e64 s[38:39], 0, v58
	s_nop 1
	v_cndmask_b32_e64 v58, v59, v62, s[38:39]
	v_mul_f32_e32 v59, 0x37800000, v58
	v_cndmask_b32_e32 v58, v58, v59, vcc
	v_cmp_class_f32_e32 vcc, v23, v105
	s_nop 1
	v_cndmask_b32_e32 v23, v58, v23, vcc
	v_div_scale_f32 v58, s[16:17], v23, v23, 1.0
	v_rcp_f32_e32 v59, v58
	s_nop 0
	v_fma_f32 v62, -v58, v59, 1.0
	v_fmac_f32_e32 v59, v62, v59
	v_div_scale_f32 v62, vcc, 1.0, v23, 1.0
	v_mul_f32_e32 v63, v62, v59
	v_fma_f32 v66, -v58, v63, v62
	v_fmac_f32_e32 v63, v66, v59
	v_fma_f32 v58, -v58, v63, v62
	v_div_fmas_f32 v58, v58, v59, v63
	v_div_fixup_f32 v58, v58, v23, 1.0
	v_mov_b32_e32 v62, v56
	v_mov_b32_e32 v63, v54
	v_pk_mul_f32 v[62:63], v[58:59], v[62:63] op_sel_hi:[0,1]
	v_mov_b32_e32 v54, v57
	v_pk_mul_f32 v[56:57], v[8:9], v[62:63]
	v_mov_b32_e32 v62, v60
	v_mov_b32_e32 v63, v52
	v_mov_b32_e32 v52, v61
	v_pk_mul_f32 v[62:63], v[58:59], v[62:63] op_sel_hi:[0,1]
	v_pk_mul_f32 v[52:53], v[58:59], v[52:53] op_sel_hi:[0,1]
	v_pk_mul_f32 v[54:55], v[58:59], v[54:55] op_sel_hi:[0,1]
	v_pk_mul_f32 v[52:53], v[14:15], v[52:53]
	v_pk_mul_f32 v[58:59], v[12:13], v[62:63]
	v_pk_mul_f32 v[54:55], v[10:11], v[54:55]
	v_pk_mul_f32 v[62:63], v[24:25], v[58:59]
	v_pk_mul_f32 v[66:67], v[28:29], v[52:53]
	v_pk_fma_f32 v[62:63], v[26:27], v[56:57], v[62:63] neg_lo:[0,0,1] neg_hi:[0,0,1]
	v_pk_fma_f32 v[66:67], v[30:31], v[54:55], v[66:67] neg_lo:[0,0,1] neg_hi:[0,0,1]
	v_pk_mul_f32 v[56:57], v[24:25], v[56:57]
	v_pk_mul_f32 v[54:55], v[28:29], v[54:55]
	v_pk_fma_f32 v[56:57], v[26:27], v[58:59], v[56:57]
	v_pk_fma_f32 v[52:53], v[30:31], v[52:53], v[54:55]
	v_lshl_add_u64 v[60:61], v[20:21], 0, v[80:81]
	v_cvt_pk_bf16_f32 v62, v62, v63
	v_cvt_pk_bf16_f32 v63, v66, v67
	v_cvt_pk_bf16_f32 v56, v56, v57
	v_cvt_pk_bf16_f32 v57, v52, v53
	s_waitcnt vmcnt(29)
	v_lshlrev_b32_e32 v53, 16, v51
	v_lshlrev_b32_e32 v52, 16, v50
	v_and_b32_e32 v51, 0xffff0000, v51
	v_and_b32_e32 v50, 0xffff0000, v50
	global_store_dwordx2 v[60:61], v[62:63], off
	global_store_dwordx2 v[60:61], v[56:57], off offset:128
	v_pk_mul_f32 v[54:55], v[50:51], v[50:51]
	s_waitcnt vmcnt(30)
	v_lshlrev_b32_e32 v57, 16, v49
	v_lshlrev_b32_e32 v56, 16, v48
	v_and_b32_e32 v49, 0xffff0000, v49
	v_and_b32_e32 v48, 0xffff0000, v48
	v_pk_fma_f32 v[54:55], v[52:53], v[52:53], v[54:55]
	v_pk_mul_f32 v[58:59], v[48:49], v[48:49]
	v_add_f32_e32 v23, v54, v55
	v_pk_fma_f32 v[58:59], v[56:57], v[56:57], v[58:59]
	s_nop 0
	v_add_f32_e32 v23, v23, v58
	v_add_f32_e32 v23, v59, v23
	s_nop 1
	v_mov_b32_dpp v54, v23 quad_perm:[1,0,3,2] row_mask:0xf bank_mask:0xf
	s_waitcnt lgkmcnt(0)
	v_add_f32_e32 v23, v23, v54
	s_nop 1
	v_mov_b32_dpp v54, v23 quad_perm:[2,3,0,1] row_mask:0xf bank_mask:0xf
	s_waitcnt lgkmcnt(0)
	v_add_f32_e32 v23, v23, v54
	s_nop 1
	v_mov_b32_dpp v54, v23 row_half_mirror row_mask:0xf bank_mask:0xf
	s_waitcnt lgkmcnt(0)
	v_add_f32_e32 v23, v23, v54
	s_nop 1
	v_mov_b32_dpp v54, v23 row_mirror row_mask:0xf bank_mask:0xf
	s_waitcnt lgkmcnt(0)
; __device__ __forceinline__ unsigned cvt_pk_bf16(float lo, float hi) { f32x2_t v = {lo, hi}; bf16x2_t b = __builtin_convertvector(v, bf16x2_t); return __builtin_bit_cast(unsigned, b); }
; __device__ __forceinline__ float bflo(unsigned w) { return __uint_as_float(w << 16); }
; __device__ __forceinline__ float bfhi(unsigned w) { return __uint_as_float(w & 0xffff0000u); }
; __global__ void __launch_bounds__(NTHR, 2) mega_fwd(Args args) {
;     ...
;                 for (int hm = 0; hm < 16; ++hm) { r0[hm] = *(const v2u*)(src + hm * 128); r1[hm] = *(const v2u*)(src + hm * 128 + 64); }
; #pragma unroll
;                 for (int hm = 0; hm < 16; ++hm) {
;                     const f32x4 x1 = {pg8::bflo(r0[hm].x), pg8::bfhi(r0[hm].x), pg8::bflo(r0[hm].y), pg8::bfhi(r0[hm].y)}, x2 = {pg8::bflo(r1[hm].x), pg8::bfhi(r1[hm].x), pg8::bflo(r1[hm].y), pg8::bfhi(r1[hm].y)};
;                     float ss = (x1.x * x1.x + x1.y * x1.y) + (x1.z * x1.z + x1.w * x1.w) + (x2.x * x2.x + x2.y * x2.y) + (x2.z * x2.z + x2.w * x2.w);
;                     ss += __shfl_xor(ss, 1); ss += __shfl_xor(ss, 2); ss += __shfl_xor(ss, 4); ss += __shfl_xor(ss, 8);
;                     const float rs = 1.0f / sqrtf(ss * (1.f / 128.f) + EPS);
;                     const f32x4 y1 = x1 * rs * (hm < 8 ? qg0 : kg0), y2 = x2 * rs * (hm < 8 ? qg1 : kg1);
;                     bf16* dst = (hm < 8 ? QH : KH) + ((size_t)((b * 8 + (hm & 7)) * SEQ + sq)) * 128 + 4 * l16;
;                     v2u o1, o2;
;                     o1.x = pg8::cvt_pk_bf16(y1.x * cs[0] - y2.x * sn[0], y1.y * cs[1] - y2.y * sn[1]); o1.y = pg8::cvt_pk_bf16(y1.z * cs[2] - y2.z * sn[2], y1.w * cs[3] - y2.w * sn[3]);
;                     o2.x = pg8::cvt_pk_bf16(y2.x * cs[0] + y1.x * sn[0], y2.y * cs[1] + y1.y * sn[1]); o2.y = pg8::cvt_pk_bf16(y2.z * cs[2] + y1.z * sn[2], y2.w * cs[3] + y1.w * sn[3]);
;                     *(v2u*)dst = o1; *(v2u*)(dst + 64) = o2;
;                 }
	v_add_f32_e32 v23, v23, v54
	v_fmamk_f32 v23, v23, 0x3c000000, v104
	v_cmp_gt_f32_e32 vcc, s15, v23
	v_mul_f32_e32 v54, 0x4f800000, v23
	s_nop 0
	v_cndmask_b32_e32 v23, v23, v54, vcc
	v_sqrt_f32_e32 v54, v23
	s_nop 0
	v_add_u32_e32 v55, -1, v54
	v_fma_f32 v58, -v55, v54, v23
	v_cmp_ge_f32_e64 s[38:39], 0, v58
	v_add_u32_e32 v58, 1, v54
	s_nop 0
	v_cndmask_b32_e64 v55, v54, v55, s[38:39]
	v_fma_f32 v54, -v58, v54, v23
	v_cmp_lt_f32_e64 s[38:39], 0, v54
	s_nop 1
	v_cndmask_b32_e64 v54, v55, v58, s[38:39]
	v_mul_f32_e32 v55, 0x37800000, v54
	v_cndmask_b32_e32 v54, v54, v55, vcc
	v_cmp_class_f32_e32 vcc, v23, v105
	s_nop 1
	v_cndmask_b32_e32 v23, v54, v23, vcc
	v_div_scale_f32 v54, s[16:17], v23, v23, 1.0
	v_rcp_f32_e32 v55, v54
	s_nop 0
	v_fma_f32 v58, -v54, v55, 1.0
	v_fmac_f32_e32 v55, v58, v55
	v_div_scale_f32 v58, vcc, 1.0, v23, 1.0
	v_mul_f32_e32 v59, v58, v55
	v_fma_f32 v60, -v54, v59, v58
	v_fmac_f32_e32 v59, v60, v55
	v_fma_f32 v54, -v54, v59, v58
	v_div_fmas_f32 v54, v54, v55, v59
	v_div_fixup_f32 v54, v54, v23, 1.0
	v_mov_b32_e32 v58, v52
	v_mov_b32_e32 v59, v50
	v_pk_mul_f32 v[58:59], v[54:55], v[58:59] op_sel_hi:[0,1]
	v_mov_b32_e32 v50, v53
	v_pk_mul_f32 v[52:53], v[8:9], v[58:59]
	v_mov_b32_e32 v58, v56
	v_mov_b32_e32 v59, v48
	v_mov_b32_e32 v48, v57
	v_pk_mul_f32 v[58:59], v[54:55], v[58:59] op_sel_hi:[0,1]
	v_pk_mul_f32 v[48:49], v[54:55], v[48:49] op_sel_hi:[0,1]
	v_pk_mul_f32 v[50:51], v[54:55], v[50:51] op_sel_hi:[0,1]
	v_pk_mul_f32 v[48:49], v[14:15], v[48:49]
	v_pk_mul_f32 v[54:55], v[12:13], v[58:59]
	v_pk_mul_f32 v[50:51], v[10:11], v[50:51]
	v_pk_mul_f32 v[58:59], v[24:25], v[54:55]
	v_pk_mul_f32 v[60:61], v[28:29], v[48:49]
	v_pk_fma_f32 v[58:59], v[26:27], v[52:53], v[58:59] neg_lo:[0,0,1] neg_hi:[0,0,1]
	v_pk_fma_f32 v[60:61], v[30:31], v[50:51], v[60:61] neg_lo:[0,0,1] neg_hi:[0,0,1]
	v_pk_mul_f32 v[52:53], v[24:25], v[52:53]
	v_pk_mul_f32 v[50:51], v[28:29], v[50:51]
	v_pk_fma_f32 v[52:53], v[26:27], v[54:55], v[52:53]
	v_pk_fma_f32 v[48:49], v[30:31], v[48:49], v[50:51]
	v_lshl_add_u64 v[56:57], v[20:21], 0, v[82:83]
	v_cvt_pk_bf16_f32 v58, v58, v59
	v_cvt_pk_bf16_f32 v59, v60, v61
	v_cvt_pk_bf16_f32 v52, v52, v53
	v_cvt_pk_bf16_f32 v53, v48, v49
	s_waitcnt vmcnt(29)
	v_lshlrev_b32_e32 v49, 16, v47
	v_lshlrev_b32_e32 v48, 16, v46
	v_and_b32_e32 v47, 0xffff0000, v47
	v_and_b32_e32 v46, 0xffff0000, v46
	global_store_dwordx2 v[56:57], v[58:59], off
	global_store_dwordx2 v[56:57], v[52:53], off offset:128
	v_pk_mul_f32 v[50:51], v[46:47], v[46:47]
	s_waitcnt vmcnt(30)
	v_lshlrev_b32_e32 v53, 16, v45
	v_lshlrev_b32_e32 v52, 16, v44
	v_and_b32_e32 v45, 0xffff0000, v45
	v_and_b32_e32 v44, 0xffff0000, v44
	v_pk_fma_f32 v[50:51], v[48:49], v[48:49], v[50:51]
	v_pk_mul_f32 v[54:55], v[44:45], v[44:45]
	v_add_f32_e32 v23, v50, v51
	v_pk_fma_f32 v[54:55], v[52:53], v[52:53], v[54:55]
	s_nop 0
	v_add_f32_e32 v23, v23, v54
	v_add_f32_e32 v23, v55, v23
	s_nop 1
	v_mov_b32_dpp v50, v23 quad_perm:[1,0,3,2] row_mask:0xf bank_mask:0xf
	s_waitcnt lgkmcnt(0)
	v_add_f32_e32 v23, v23, v50
	s_nop 1
	v_mov_b32_dpp v50, v23 quad_perm:[2,3,0,1] row_mask:0xf bank_mask:0xf
	s_waitcnt lgkmcnt(0)
	v_add_f32_e32 v23, v23, v50
	s_nop 1
	v_mov_b32_dpp v50, v23 row_half_mirror row_mask:0xf bank_mask:0xf
	s_waitcnt lgkmcnt(0)
	v_add_f32_e32 v23, v23, v50
	s_nop 1
	v_mov_b32_dpp v50, v23 row_mirror row_mask:0xf bank_mask:0xf
	s_waitcnt lgkmcnt(0)
	v_add_f32_e32 v23, v23, v50
	v_fmamk_f32 v23, v23, 0x3c000000, v104
	v_cmp_gt_f32_e32 vcc, s15, v23
	v_mul_f32_e32 v50, 0x4f800000, v23
	s_nop 0
	v_cndmask_b32_e32 v23, v23, v50, vcc
	v_sqrt_f32_e32 v50, v23
	s_nop 0
	v_add_u32_e32 v51, -1, v50
	v_fma_f32 v54, -v51, v50, v23
	v_cmp_ge_f32_e64 s[38:39], 0, v54
	v_add_u32_e32 v54, 1, v50
	s_nop 0
	v_cndmask_b32_e64 v51, v50, v51, s[38:39]
	v_fma_f32 v50, -v54, v50, v23
	v_cmp_lt_f32_e64 s[38:39], 0, v50
	s_nop 1
	v_cndmask_b32_e64 v50, v51, v54, s[38:39]
	v_mul_f32_e32 v51, 0x37800000, v50
	v_cndmask_b32_e32 v50, v50, v51, vcc
	v_cmp_class_f32_e32 vcc, v23, v105
	s_nop 1
	v_cndmask_b32_e32 v23, v50, v23, vcc
	v_div_scale_f32 v50, s[16:17], v23, v23, 1.0
	v_rcp_f32_e32 v51, v50
	s_nop 0
	v_fma_f32 v54, -v50, v51, 1.0
	v_fmac_f32_e32 v51, v54, v51
	v_div_scale_f32 v54, vcc, 1.0, v23, 1.0
	v_mul_f32_e32 v55, v54, v51
	v_fma_f32 v56, -v50, v55, v54
	v_fmac_f32_e32 v55, v56, v51
	v_fma_f32 v50, -v50, v55, v54
	v_div_fmas_f32 v50, v50, v51, v55
	v_div_fixup_f32 v50, v50, v23, 1.0
	v_mov_b32_e32 v54, v48
	v_mov_b32_e32 v55, v46
	v_pk_mul_f32 v[54:55], v[50:51], v[54:55] op_sel_hi:[0,1]
	v_mov_b32_e32 v46, v49
	v_pk_mul_f32 v[48:49], v[8:9], v[54:55]
	v_mov_b32_e32 v54, v52
	v_mov_b32_e32 v55, v44
	v_mov_b32_e32 v44, v53
	v_pk_mul_f32 v[54:55], v[50:51], v[54:55] op_sel_hi:[0,1]
	v_pk_mul_f32 v[44:45], v[50:51], v[44:45] op_sel_hi:[0,1]
	v_pk_mul_f32 v[46:47], v[50:51], v[46:47] op_sel_hi:[0,1]
	v_pk_mul_f32 v[44:45], v[14:15], v[44:45]
	v_pk_mul_f32 v[50:51], v[12:13], v[54:55]
	v_pk_mul_f32 v[46:47], v[10:11], v[46:47]
	v_pk_mul_f32 v[54:55], v[24:25], v[50:51]
	v_pk_mul_f32 v[56:57], v[28:29], v[44:45]
	v_pk_fma_f32 v[54:55], v[26:27], v[48:49], v[54:55] neg_lo:[0,0,1] neg_hi:[0,0,1]
	v_pk_fma_f32 v[56:57], v[30:31], v[46:47], v[56:57] neg_lo:[0,0,1] neg_hi:[0,0,1]
	v_pk_mul_f32 v[48:49], v[24:25], v[48:49]
	v_pk_mul_f32 v[46:47], v[28:29], v[46:47]
	v_pk_fma_f32 v[48:49], v[26:27], v[50:51], v[48:49]
	v_pk_fma_f32 v[44:45], v[30:31], v[44:45], v[46:47]
	v_lshl_add_u64 v[52:53], v[20:21], 0, v[84:85]
	v_cvt_pk_bf16_f32 v54, v54, v55
	v_cvt_pk_bf16_f32 v55, v56, v57
	v_cvt_pk_bf16_f32 v48, v48, v49
	v_cvt_pk_bf16_f32 v49, v44, v45
	s_waitcnt vmcnt(29)
; __device__ __forceinline__ unsigned cvt_pk_bf16(float lo, float hi) { f32x2_t v = {lo, hi}; bf16x2_t b = __builtin_convertvector(v, bf16x2_t); return __builtin_bit_cast(unsigned, b); }
; __device__ __forceinline__ float bflo(unsigned w) { return __uint_as_float(w << 16); }
; __device__ __forceinline__ float bfhi(unsigned w) { return __uint_as_float(w & 0xffff0000u); }
; __global__ void __launch_bounds__(NTHR, 2) mega_fwd(Args args) {
;     ...
;                 for (int hm = 0; hm < 16; ++hm) { r0[hm] = *(const v2u*)(src + hm * 128); r1[hm] = *(const v2u*)(src + hm * 128 + 64); }
; #pragma unroll
;                 for (int hm = 0; hm < 16; ++hm) {
;                     const f32x4 x1 = {pg8::bflo(r0[hm].x), pg8::bfhi(r0[hm].x), pg8::bflo(r0[hm].y), pg8::bfhi(r0[hm].y)}, x2 = {pg8::bflo(r1[hm].x), pg8::bfhi(r1[hm].x), pg8::bflo(r1[hm].y), pg8::bfhi(r1[hm].y)};
;                     float ss = (x1.x * x1.x + x1.y * x1.y) + (x1.z * x1.z + x1.w * x1.w) + (x2.x * x2.x + x2.y * x2.y) + (x2.z * x2.z + x2.w * x2.w);
;                     ss += __shfl_xor(ss, 1); ss += __shfl_xor(ss, 2); ss += __shfl_xor(ss, 4); ss += __shfl_xor(ss, 8);
;                     const float rs = 1.0f / sqrtf(ss * (1.f / 128.f) + EPS);
;                     const f32x4 y1 = x1 * rs * (hm < 8 ? qg0 : kg0), y2 = x2 * rs * (hm < 8 ? qg1 : kg1);
;                     bf16* dst = (hm < 8 ? QH : KH) + ((size_t)((b * 8 + (hm & 7)) * SEQ + sq)) * 128 + 4 * l16;
;                     v2u o1, o2;
;                     o1.x = pg8::cvt_pk_bf16(y1.x * cs[0] - y2.x * sn[0], y1.y * cs[1] - y2.y * sn[1]); o1.y = pg8::cvt_pk_bf16(y1.z * cs[2] - y2.z * sn[2], y1.w * cs[3] - y2.w * sn[3]);
;                     o2.x = pg8::cvt_pk_bf16(y2.x * cs[0] + y1.x * sn[0], y2.y * cs[1] + y1.y * sn[1]); o2.y = pg8::cvt_pk_bf16(y2.z * cs[2] + y1.z * sn[2], y2.w * cs[3] + y1.w * sn[3]);
;                     *(v2u*)dst = o1; *(v2u*)(dst + 64) = o2;
;                 }
	v_lshlrev_b32_e32 v45, 16, v43
	v_lshlrev_b32_e32 v44, 16, v42
	v_and_b32_e32 v43, 0xffff0000, v43
	v_and_b32_e32 v42, 0xffff0000, v42
	global_store_dwordx2 v[52:53], v[54:55], off
	global_store_dwordx2 v[52:53], v[48:49], off offset:128
	v_pk_mul_f32 v[46:47], v[42:43], v[42:43]
	s_waitcnt vmcnt(30)
	v_lshlrev_b32_e32 v49, 16, v41
	v_lshlrev_b32_e32 v48, 16, v40
	v_and_b32_e32 v41, 0xffff0000, v41
	v_and_b32_e32 v40, 0xffff0000, v40
	v_pk_fma_f32 v[46:47], v[44:45], v[44:45], v[46:47]
	v_pk_mul_f32 v[50:51], v[40:41], v[40:41]
	v_add_f32_e32 v23, v46, v47
	v_pk_fma_f32 v[50:51], v[48:49], v[48:49], v[50:51]
	s_nop 0
	v_add_f32_e32 v23, v23, v50
	v_add_f32_e32 v23, v51, v23
	s_nop 1
	v_mov_b32_dpp v46, v23 quad_perm:[1,0,3,2] row_mask:0xf bank_mask:0xf
	s_waitcnt lgkmcnt(0)
	v_add_f32_e32 v23, v23, v46
	s_nop 1
	v_mov_b32_dpp v46, v23 quad_perm:[2,3,0,1] row_mask:0xf bank_mask:0xf
	s_waitcnt lgkmcnt(0)
	v_add_f32_e32 v23, v23, v46
	s_nop 1
	v_mov_b32_dpp v46, v23 row_half_mirror row_mask:0xf bank_mask:0xf
	s_waitcnt lgkmcnt(0)
	v_add_f32_e32 v23, v23, v46
	s_nop 1
	v_mov_b32_dpp v46, v23 row_mirror row_mask:0xf bank_mask:0xf
	s_waitcnt lgkmcnt(0)
	v_add_f32_e32 v23, v23, v46
	v_fmamk_f32 v23, v23, 0x3c000000, v104
	v_cmp_gt_f32_e32 vcc, s15, v23
	v_mul_f32_e32 v46, 0x4f800000, v23
	s_nop 0
	v_cndmask_b32_e32 v23, v23, v46, vcc
	v_sqrt_f32_e32 v46, v23
	s_nop 0
	v_add_u32_e32 v47, -1, v46
	v_fma_f32 v50, -v47, v46, v23
	v_cmp_ge_f32_e64 s[38:39], 0, v50
	v_add_u32_e32 v50, 1, v46
	s_nop 0
	v_cndmask_b32_e64 v47, v46, v47, s[38:39]
	v_fma_f32 v46, -v50, v46, v23
	v_cmp_lt_f32_e64 s[38:39], 0, v46
	s_nop 1
	v_cndmask_b32_e64 v46, v47, v50, s[38:39]
	v_mul_f32_e32 v47, 0x37800000, v46
	v_cndmask_b32_e32 v46, v46, v47, vcc
	v_cmp_class_f32_e32 vcc, v23, v105
	s_nop 1
	v_cndmask_b32_e32 v23, v46, v23, vcc
	v_div_scale_f32 v46, s[16:17], v23, v23, 1.0
	v_rcp_f32_e32 v47, v46
	s_nop 0
	v_fma_f32 v50, -v46, v47, 1.0
	v_fmac_f32_e32 v47, v50, v47
	v_div_scale_f32 v50, vcc, 1.0, v23, 1.0
	v_mul_f32_e32 v51, v50, v47
	v_fma_f32 v52, -v46, v51, v50
	v_fmac_f32_e32 v51, v52, v47
	v_fma_f32 v46, -v46, v51, v50
	v_div_fmas_f32 v46, v46, v47, v51
	v_div_fixup_f32 v46, v46, v23, 1.0
	v_mov_b32_e32 v50, v44
	v_mov_b32_e32 v51, v42
	v_pk_mul_f32 v[50:51], v[46:47], v[50:51] op_sel_hi:[0,1]
	v_mov_b32_e32 v42, v45
	v_pk_mul_f32 v[44:45], v[8:9], v[50:51]
	v_mov_b32_e32 v50, v48
	v_mov_b32_e32 v51, v40
	v_mov_b32_e32 v40, v49
	v_pk_mul_f32 v[50:51], v[46:47], v[50:51] op_sel_hi:[0,1]
	v_pk_mul_f32 v[40:41], v[46:47], v[40:41] op_sel_hi:[0,1]
	v_pk_mul_f32 v[42:43], v[46:47], v[42:43] op_sel_hi:[0,1]
	v_pk_mul_f32 v[40:41], v[14:15], v[40:41]
	v_pk_mul_f32 v[46:47], v[12:13], v[50:51]
	v_pk_mul_f32 v[42:43], v[10:11], v[42:43]
	v_pk_mul_f32 v[50:51], v[24:25], v[46:47]
	v_pk_mul_f32 v[52:53], v[28:29], v[40:41]
	v_pk_fma_f32 v[50:51], v[26:27], v[44:45], v[50:51] neg_lo:[0,0,1] neg_hi:[0,0,1]
	v_pk_fma_f32 v[52:53], v[30:31], v[42:43], v[52:53] neg_lo:[0,0,1] neg_hi:[0,0,1]
	v_pk_mul_f32 v[44:45], v[24:25], v[44:45]
	v_pk_mul_f32 v[42:43], v[28:29], v[42:43]
	v_pk_fma_f32 v[44:45], v[26:27], v[46:47], v[44:45]
	v_pk_fma_f32 v[40:41], v[30:31], v[40:41], v[42:43]
	v_lshl_add_u64 v[48:49], v[20:21], 0, v[72:73]
	v_cvt_pk_bf16_f32 v50, v50, v51
	v_cvt_pk_bf16_f32 v51, v52, v53
	v_cvt_pk_bf16_f32 v44, v44, v45
	v_cvt_pk_bf16_f32 v45, v40, v41
	s_waitcnt vmcnt(29)
	v_lshlrev_b32_e32 v41, 16, v39
	v_lshlrev_b32_e32 v40, 16, v38
	v_and_b32_e32 v39, 0xffff0000, v39
	v_and_b32_e32 v38, 0xffff0000, v38
	global_store_dwordx2 v[48:49], v[50:51], off
	global_store_dwordx2 v[48:49], v[44:45], off offset:128
	v_pk_mul_f32 v[42:43], v[38:39], v[38:39]
	s_waitcnt vmcnt(30)
	v_lshlrev_b32_e32 v45, 16, v37
	v_lshlrev_b32_e32 v44, 16, v36
	v_and_b32_e32 v37, 0xffff0000, v37
	v_and_b32_e32 v36, 0xffff0000, v36
	v_pk_fma_f32 v[42:43], v[40:41], v[40:41], v[42:43]
	v_pk_mul_f32 v[46:47], v[36:37], v[36:37]
	v_add_f32_e32 v23, v42, v43
	v_pk_fma_f32 v[46:47], v[44:45], v[44:45], v[46:47]
	s_nop 0
	v_add_f32_e32 v23, v23, v46
	v_add_f32_e32 v23, v47, v23
	s_nop 1
	v_mov_b32_dpp v42, v23 quad_perm:[1,0,3,2] row_mask:0xf bank_mask:0xf
	s_waitcnt lgkmcnt(0)
	v_add_f32_e32 v23, v23, v42
	s_nop 1
	v_mov_b32_dpp v42, v23 quad_perm:[2,3,0,1] row_mask:0xf bank_mask:0xf
	s_waitcnt lgkmcnt(0)
	v_add_f32_e32 v23, v23, v42
	s_nop 1
	v_mov_b32_dpp v42, v23 row_half_mirror row_mask:0xf bank_mask:0xf
	s_waitcnt lgkmcnt(0)
	v_add_f32_e32 v23, v23, v42
	s_nop 1
	v_mov_b32_dpp v42, v23 row_mirror row_mask:0xf bank_mask:0xf
	s_waitcnt lgkmcnt(0)
; __device__ __forceinline__ unsigned cvt_pk_bf16(float lo, float hi) { f32x2_t v = {lo, hi}; bf16x2_t b = __builtin_convertvector(v, bf16x2_t); return __builtin_bit_cast(unsigned, b); }
; __device__ __forceinline__ float bflo(unsigned w) { return __uint_as_float(w << 16); }
; __device__ __forceinline__ float bfhi(unsigned w) { return __uint_as_float(w & 0xffff0000u); }
; __global__ void __launch_bounds__(NTHR, 2) mega_fwd(Args args) {
;     ...
;                 for (int hm = 0; hm < 16; ++hm) { r0[hm] = *(const v2u*)(src + hm * 128); r1[hm] = *(const v2u*)(src + hm * 128 + 64); }
; #pragma unroll
;                 for (int hm = 0; hm < 16; ++hm) {
;                     const f32x4 x1 = {pg8::bflo(r0[hm].x), pg8::bfhi(r0[hm].x), pg8::bflo(r0[hm].y), pg8::bfhi(r0[hm].y)}, x2 = {pg8::bflo(r1[hm].x), pg8::bfhi(r1[hm].x), pg8::bflo(r1[hm].y), pg8::bfhi(r1[hm].y)};
;                     float ss = (x1.x * x1.x + x1.y * x1.y) + (x1.z * x1.z + x1.w * x1.w) + (x2.x * x2.x + x2.y * x2.y) + (x2.z * x2.z + x2.w * x2.w);
;                     ss += __shfl_xor(ss, 1); ss += __shfl_xor(ss, 2); ss += __shfl_xor(ss, 4); ss += __shfl_xor(ss, 8);
;                     const float rs = 1.0f / sqrtf(ss * (1.f / 128.f) + EPS);
;                     const f32x4 y1 = x1 * rs * (hm < 8 ? qg0 : kg0), y2 = x2 * rs * (hm < 8 ? qg1 : kg1);
;                     bf16* dst = (hm < 8 ? QH : KH) + ((size_t)((b * 8 + (hm & 7)) * SEQ + sq)) * 128 + 4 * l16;
;                     v2u o1, o2;
;                     o1.x = pg8::cvt_pk_bf16(y1.x * cs[0] - y2.x * sn[0], y1.y * cs[1] - y2.y * sn[1]); o1.y = pg8::cvt_pk_bf16(y1.z * cs[2] - y2.z * sn[2], y1.w * cs[3] - y2.w * sn[3]);
;                     o2.x = pg8::cvt_pk_bf16(y2.x * cs[0] + y1.x * sn[0], y2.y * cs[1] + y1.y * sn[1]); o2.y = pg8::cvt_pk_bf16(y2.z * cs[2] + y1.z * sn[2], y2.w * cs[3] + y1.w * sn[3]);
;                     *(v2u*)dst = o1; *(v2u*)(dst + 64) = o2;
;                 }
;             }
	v_add_f32_e32 v23, v23, v42
	v_fmamk_f32 v23, v23, 0x3c000000, v104
	v_cmp_gt_f32_e32 vcc, s15, v23
	v_mul_f32_e32 v42, 0x4f800000, v23
	s_nop 0
	v_cndmask_b32_e32 v23, v23, v42, vcc
	v_sqrt_f32_e32 v42, v23
	s_nop 0
	v_add_u32_e32 v43, -1, v42
	v_fma_f32 v46, -v43, v42, v23
	v_cmp_ge_f32_e64 s[38:39], 0, v46
	v_add_u32_e32 v46, 1, v42
	s_nop 0
	v_cndmask_b32_e64 v43, v42, v43, s[38:39]
	v_fma_f32 v42, -v46, v42, v23
	v_cmp_lt_f32_e64 s[38:39], 0, v42
	s_nop 1
	v_cndmask_b32_e64 v42, v43, v46, s[38:39]
	v_mul_f32_e32 v43, 0x37800000, v42
	v_cndmask_b32_e32 v42, v42, v43, vcc
	v_cmp_class_f32_e32 vcc, v23, v105
	s_nop 1
	v_cndmask_b32_e32 v23, v42, v23, vcc
	v_div_scale_f32 v42, s[16:17], v23, v23, 1.0
	v_rcp_f32_e32 v43, v42
	s_nop 0
	v_fma_f32 v46, -v42, v43, 1.0
	v_fmac_f32_e32 v43, v46, v43
	v_div_scale_f32 v46, vcc, 1.0, v23, 1.0
	v_mul_f32_e32 v47, v46, v43
	v_fma_f32 v48, -v42, v47, v46
	v_fmac_f32_e32 v47, v48, v43
	v_fma_f32 v42, -v42, v47, v46
	v_div_fmas_f32 v42, v42, v43, v47
	v_div_fixup_f32 v42, v42, v23, 1.0
	v_mov_b32_e32 v46, v40
	v_mov_b32_e32 v47, v38
	v_pk_mul_f32 v[46:47], v[42:43], v[46:47] op_sel_hi:[0,1]
	v_mov_b32_e32 v38, v41
	v_pk_mul_f32 v[40:41], v[8:9], v[46:47]
	v_mov_b32_e32 v46, v44
	v_mov_b32_e32 v47, v36
	v_mov_b32_e32 v36, v45
	v_pk_mul_f32 v[46:47], v[42:43], v[46:47] op_sel_hi:[0,1]
	v_pk_mul_f32 v[36:37], v[42:43], v[36:37] op_sel_hi:[0,1]
	v_pk_mul_f32 v[38:39], v[42:43], v[38:39] op_sel_hi:[0,1]
	v_pk_mul_f32 v[36:37], v[14:15], v[36:37]
	v_pk_mul_f32 v[42:43], v[12:13], v[46:47]
	v_pk_mul_f32 v[38:39], v[10:11], v[38:39]
	v_pk_mul_f32 v[46:47], v[24:25], v[42:43]
	v_pk_mul_f32 v[48:49], v[28:29], v[36:37]
	v_pk_fma_f32 v[46:47], v[26:27], v[40:41], v[46:47] neg_lo:[0,0,1] neg_hi:[0,0,1]
	v_pk_fma_f32 v[48:49], v[30:31], v[38:39], v[48:49] neg_lo:[0,0,1] neg_hi:[0,0,1]
	v_pk_mul_f32 v[40:41], v[24:25], v[40:41]
	v_pk_mul_f32 v[38:39], v[28:29], v[38:39]
	v_pk_fma_f32 v[40:41], v[26:27], v[42:43], v[40:41]
	v_pk_fma_f32 v[36:37], v[30:31], v[36:37], v[38:39]
	v_lshl_add_u64 v[44:45], v[20:21], 0, v[68:69]
	v_cvt_pk_bf16_f32 v46, v46, v47
	v_cvt_pk_bf16_f32 v47, v48, v49
	v_cvt_pk_bf16_f32 v40, v40, v41
	v_cvt_pk_bf16_f32 v41, v36, v37
	s_waitcnt vmcnt(29)
	v_lshlrev_b32_e32 v37, 16, v35
	v_lshlrev_b32_e32 v36, 16, v34
	v_and_b32_e32 v35, 0xffff0000, v35
	v_and_b32_e32 v34, 0xffff0000, v34
	global_store_dwordx2 v[44:45], v[46:47], off
	global_store_dwordx2 v[44:45], v[40:41], off offset:128
	v_pk_mul_f32 v[38:39], v[34:35], v[34:35]
	s_waitcnt vmcnt(30)
	v_lshlrev_b32_e32 v41, 16, v33
	v_lshlrev_b32_e32 v40, 16, v32
	v_and_b32_e32 v33, 0xffff0000, v33
	v_and_b32_e32 v32, 0xffff0000, v32
	v_pk_fma_f32 v[38:39], v[36:37], v[36:37], v[38:39]
	v_pk_mul_f32 v[42:43], v[32:33], v[32:33]
	v_add_f32_e32 v23, v38, v39
	v_pk_fma_f32 v[42:43], v[40:41], v[40:41], v[42:43]
	s_nop 0
	v_add_f32_e32 v23, v23, v42
	v_add_f32_e32 v23, v43, v23
	s_nop 1
	v_mov_b32_dpp v38, v23 quad_perm:[1,0,3,2] row_mask:0xf bank_mask:0xf
	s_waitcnt lgkmcnt(0)
	v_add_f32_e32 v23, v23, v38
	s_nop 1
	v_mov_b32_dpp v38, v23 quad_perm:[2,3,0,1] row_mask:0xf bank_mask:0xf
	s_waitcnt lgkmcnt(0)
	v_add_f32_e32 v23, v23, v38
	s_nop 1
	v_mov_b32_dpp v38, v23 row_half_mirror row_mask:0xf bank_mask:0xf
	s_waitcnt lgkmcnt(0)
	v_add_f32_e32 v23, v23, v38
	s_nop 1
	v_mov_b32_dpp v38, v23 row_mirror row_mask:0xf bank_mask:0xf
	s_waitcnt lgkmcnt(0)
	v_add_f32_e32 v23, v23, v38
	v_fmamk_f32 v23, v23, 0x3c000000, v104
	v_cmp_gt_f32_e32 vcc, s15, v23
	v_mul_f32_e32 v38, 0x4f800000, v23
	s_nop 0
	v_cndmask_b32_e32 v23, v23, v38, vcc
	v_sqrt_f32_e32 v38, v23
	s_nop 0
	v_add_u32_e32 v39, -1, v38
	v_fma_f32 v42, -v39, v38, v23
	v_cmp_ge_f32_e64 s[38:39], 0, v42
	v_add_u32_e32 v42, 1, v38
	s_nop 0
	v_cndmask_b32_e64 v39, v38, v39, s[38:39]
	v_fma_f32 v38, -v42, v38, v23
	v_cmp_lt_f32_e64 s[38:39], 0, v38
	s_nop 1
	v_cndmask_b32_e64 v38, v39, v42, s[38:39]
	v_mul_f32_e32 v39, 0x37800000, v38
	v_cndmask_b32_e32 v38, v38, v39, vcc
	v_cmp_class_f32_e32 vcc, v23, v105
	s_nop 1
	v_cndmask_b32_e32 v23, v38, v23, vcc
	v_div_scale_f32 v38, s[16:17], v23, v23, 1.0
	v_rcp_f32_e32 v39, v38
	s_nop 0
	v_fma_f32 v42, -v38, v39, 1.0
	v_fmac_f32_e32 v39, v42, v39
	v_div_scale_f32 v42, vcc, 1.0, v23, 1.0
	v_mul_f32_e32 v43, v42, v39
	v_fma_f32 v44, -v38, v43, v42
	v_fmac_f32_e32 v43, v44, v39
	v_fma_f32 v38, -v38, v43, v42
	v_div_fmas_f32 v38, v38, v39, v43
	v_div_fixup_f32 v38, v38, v23, 1.0
	v_mov_b32_e32 v42, v36
	v_mov_b32_e32 v43, v34
	v_pk_mul_f32 v[42:43], v[38:39], v[42:43] op_sel_hi:[0,1]
	v_mov_b32_e32 v34, v37
	v_pk_mul_f32 v[36:37], v[8:9], v[42:43]
	v_mov_b32_e32 v42, v40
	v_mov_b32_e32 v43, v32
	v_mov_b32_e32 v32, v41
	v_pk_mul_f32 v[42:43], v[38:39], v[42:43] op_sel_hi:[0,1]
	v_pk_mul_f32 v[32:33], v[38:39], v[32:33] op_sel_hi:[0,1]
	v_pk_mul_f32 v[34:35], v[38:39], v[34:35] op_sel_hi:[0,1]
	v_pk_mul_f32 v[32:33], v[14:15], v[32:33]
	v_pk_mul_f32 v[38:39], v[12:13], v[42:43]
	v_pk_mul_f32 v[34:35], v[10:11], v[34:35]
	v_pk_mul_f32 v[42:43], v[24:25], v[38:39]
	v_pk_mul_f32 v[44:45], v[28:29], v[32:33]
	v_pk_mul_f32 v[24:25], v[24:25], v[36:37]
	v_pk_fma_f32 v[42:43], v[26:27], v[36:37], v[42:43] neg_lo:[0,0,1] neg_hi:[0,0,1]
	v_pk_fma_f32 v[44:45], v[30:31], v[34:35], v[44:45] neg_lo:[0,0,1] neg_hi:[0,0,1]
	v_pk_fma_f32 v[24:25], v[26:27], v[38:39], v[24:25]
	v_pk_mul_f32 v[26:27], v[28:29], v[34:35]
	v_lshl_add_u64 v[40:41], v[20:21], 0, v[64:65]
	v_cvt_pk_bf16_f32 v42, v42, v43
	v_cvt_pk_bf16_f32 v43, v44, v45
	v_pk_fma_f32 v[26:27], v[30:31], v[32:33], v[26:27]
	v_cvt_pk_bf16_f32 v24, v24, v25
	v_cvt_pk_bf16_f32 v25, v26, v27
	global_store_dwordx2 v[40:41], v[42:43], off
	global_store_dwordx2 v[40:41], v[24:25], off offset:128
	s_cbranch_scc0 .LBB0_261

; __device__ __forceinline__ void finishSM(f32x16& p0, f32x16& p1, float alpha, float& l_reg, bf16x8& pa0, bf16x8& pa1, bf16x8& pa2, bf16x8& pa3) {
;     for (int r = 0; r < 16; ++r) p1[r] = __builtin_amdgcn_exp2f(p1[r]);
;     float ps = 0; for (int r = 0; r < 16; ++r) ps += p0[r]; for (int r = 0; r < 16; ++r) ps += p1[r];
;     { auto rr = __builtin_amdgcn_permlane32_swap(__float_as_uint(ps), __float_as_uint(ps), false, false);
;       ps = __uint_as_float(rr[0]) + __uint_as_float(rr[1]); }
;     l_reg = l_reg * alpha + ps;
;     ...
;     PK4(p0, 0, pa0); PK4(p0, 8, pa1); PK4(p1, 0, pa2); PK4(p1, 8, pa3);
;     ...
; }
; template <int KB>
; __device__ __forceinline__ void qkt(f32x16& p0, f32x16& p1, const char* K_lds, int r32, int hi, const bf16x8* qr) {
;     p0 = f32x16{}; p1 = f32x16{};
;     const char* kb[4];
; #pragma unroll
;     for (int dd = 0; dd < 4; ++dd) kb[dd] = K_lds + KB * SHM_K + KSWZ(r32, (dd * 16 + hi * 8) * 2);
; #pragma unroll
;     for (int d0 = 0; d0 < 8; ++d0) { const char* a = kb[d0 & 3] + (d0 >> 2) * 128;
;         bf16x8 b0 = *reinterpret_cast<const bf16x8*>(a);
;         bf16x8 b1 = *reinterpret_cast<const bf16x8*>(a + 32 * 256);
;         p0 = __builtin_amdgcn_mfma_f32_32x32x16_bf16(b0, qr[d0], p0, 0, 0, 0);
;         p1 = __builtin_amdgcn_mfma_f32_32x32x16_bf16(b1, qr[d0], p1, 0, 0, 0); }
; }
; template <int VB>
; __device__ __forceinline__ void pv_tile(f32x16* o, int vb0, bf16x8 pa0, bf16x8 pa1, bf16x8 pa2, bf16x8 pa3) {
;     ...
;     PV_D0(0); PV_D0(1); PV_D0(2); PV_D0(3);
.LBB0_320:
	ds_read_b128 v[64:67], v201 offset:49152
	ds_read_b128 v[68:71], v201 offset:57344
	ds_read_b128 v[96:99], v230 offset:49152
	ds_read_b128 v[100:103], v230 offset:57344
	v_exp_f32_e32 v104, v126
	v_exp_f32_e32 v105, v127
	s_waitcnt lgkmcnt(3)
	v_mfma_f32_32x32x16_bf16 v[80:95], v[64:67], v[156:159], 0
	v_exp_f32_e32 v106, v122
	v_exp_f32_e32 v107, v123
	v_exp_f32_e32 v108, v118
	v_exp_f32_e32 v109, v119
	v_exp_f32_e32 v110, v116
	v_exp_f32_e32 v111, v117
	v_exp_f32_e32 v112, v112
	s_waitcnt lgkmcnt(2)
	v_mfma_f32_32x32x16_bf16 v[64:79], v[68:71], v[156:159], 0
	v_exp_f32_e32 v113, v113
	v_exp_f32_e32 v116, v124
	v_exp_f32_e32 v117, v125
	v_exp_f32_e32 v118, v120
	v_exp_f32_e32 v119, v121
	v_exp_f32_e32 v114, v114
	v_exp_f32_e32 v115, v115
	s_waitcnt lgkmcnt(1)
	v_mfma_f32_32x32x16_bf16 v[80:95], v[96:99], v[152:155], v[80:95]
	s_waitcnt lgkmcnt(0)
	v_mfma_f32_32x32x16_bf16 v[64:79], v[100:103], v[152:155], v[64:79]
	ds_read_b128 v[96:99], v229 offset:49152
	ds_read_b128 v[100:103], v229 offset:57344
	s_waitcnt lgkmcnt(1)
	v_mfma_f32_32x32x16_bf16 v[80:95], v[96:99], v[148:151], v[80:95]
	s_waitcnt lgkmcnt(0)
	v_mfma_f32_32x32x16_bf16 v[64:79], v[100:103], v[148:151], v[64:79]
	ds_read_b128 v[96:99], v207 offset:49152
	ds_read_b128 v[100:103], v207 offset:57344
	s_waitcnt lgkmcnt(1)
	v_mfma_f32_32x32x16_bf16 v[80:95], v[96:99], v[144:147], v[80:95]
	s_waitcnt lgkmcnt(0)
	v_mfma_f32_32x32x16_bf16 v[64:79], v[100:103], v[144:147], v[64:79]
	ds_read_b128 v[96:99], v201 offset:49280
	ds_read_b128 v[100:103], v201 offset:57472
	s_waitcnt lgkmcnt(1)
	v_mfma_f32_32x32x16_bf16 v[80:95], v[96:99], v[140:143], v[80:95]
	s_waitcnt lgkmcnt(0)
	v_mfma_f32_32x32x16_bf16 v[64:79], v[100:103], v[140:143], v[64:79]
	ds_read_b128 v[96:99], v230 offset:49280
	ds_read_b128 v[100:103], v230 offset:57472
	s_waitcnt lgkmcnt(1)
	v_mfma_f32_32x32x16_bf16 v[80:95], v[96:99], v[136:139], v[80:95]
	s_waitcnt lgkmcnt(0)
	v_mfma_f32_32x32x16_bf16 v[64:79], v[100:103], v[136:139], v[64:79]
	ds_read_b128 v[96:99], v229 offset:49280
	ds_read_b128 v[100:103], v229 offset:57472
	s_waitcnt lgkmcnt(1)
	v_mfma_f32_32x32x16_bf16 v[80:95], v[96:99], v[132:135], v[80:95]
	s_waitcnt lgkmcnt(0)
	v_mfma_f32_32x32x16_bf16 v[64:79], v[100:103], v[132:135], v[64:79]
	ds_read_b128 v[96:99], v207 offset:49280
	ds_read_b128 v[100:103], v207 offset:57472
	s_waitcnt lgkmcnt(1)
	v_mfma_f32_32x32x16_bf16 v[80:95], v[96:99], v[128:131], v[80:95]
	v_add_f32_e32 v96, 0, v169
	v_add_f32_e32 v96, v170, v96
	v_add_f32_e32 v96, v171, v96
	v_add_f32_e32 v96, v173, v96
	v_add_f32_e32 v96, v174, v96
	v_add_f32_e32 v96, v177, v96
	v_add_f32_e32 v96, v172, v96
	v_add_f32_e32 v96, v175, v96
	v_add_f32_e32 v96, v161, v96
	v_add_f32_e32 v96, v163, v96
	v_add_f32_e32 v96, v164, v96
	v_add_f32_e32 v96, v167, v96
	v_add_f32_e32 v96, v162, v96
	v_add_f32_e32 v96, v165, v96
	v_add_f32_e32 v96, v166, v96
	v_add_f32_e32 v96, v168, v96
	v_add_f32_e32 v96, v104, v96
	v_add_f32_e32 v96, v105, v96
	v_add_f32_e32 v96, v106, v96
	v_add_f32_e32 v96, v107, v96
	v_add_f32_e32 v96, v108, v96
	v_add_f32_e32 v96, v109, v96
	v_add_f32_e32 v96, v110, v96
	v_add_f32_e32 v96, v111, v96
	v_add_f32_e32 v96, v112, v96
	v_add_f32_e32 v96, v113, v96
	s_waitcnt lgkmcnt(0)
	v_mfma_f32_32x32x16_bf16 v[64:79], v[100:103], v[128:131], v[64:79]
	v_add_f32_e32 v96, v116, v96
	v_add_f32_e32 v96, v117, v96
	v_add_f32_e32 v96, v118, v96
	v_add_f32_e32 v96, v119, v96
	v_add_f32_e32 v96, v114, v96
	v_add_f32_e32 v194, v115, v96
	v_mov_b32_e32 v234, v194
	v_cvt_pk_bf16_f32 v96, v169, v170
	v_cvt_pk_bf16_f32 v97, v171, v173
	v_cvt_pk_bf16_f32 v98, v174, v177
	v_cvt_pk_bf16_f32 v99, v172, v175
	v_permlane32_swap_b32_e32 v194, v234
	v_permlane32_swap_b32_e32 v96, v98
	v_permlane32_swap_b32_e32 v97, v99
	v_cvt_pk_bf16_f32 v100, v161, v163
	v_cvt_pk_bf16_f32 v101, v164, v167
	v_cvt_pk_bf16_f32 v102, v162, v165
	v_cvt_pk_bf16_f32 v103, v166, v168
	v_cvt_pk_bf16_f32 v104, v104, v105
	v_cvt_pk_bf16_f32 v105, v106, v107
	v_cvt_pk_bf16_f32 v106, v108, v109
	v_cvt_pk_bf16_f32 v107, v110, v111
	v_cvt_pk_bf16_f32 v108, v112, v113
	v_cvt_pk_bf16_f32 v109, v116, v117
	v_cvt_pk_bf16_f32 v110, v118, v119
	v_cvt_pk_bf16_f32 v111, v114, v115
	v_permlane32_swap_b32_e32 v100, v102
	v_permlane32_swap_b32_e32 v101, v103
	v_permlane32_swap_b32_e32 v104, v106
	v_permlane32_swap_b32_e32 v105, v107
	v_permlane32_swap_b32_e32 v108, v110
	v_permlane32_swap_b32_e32 v109, v111
	v_add_u32_e32 v212, s50, v202
	v_ashrrev_i32_e32 v213, 31, v212
	v_add_u32_e32 v116, 32, v212
	v_lshlrev_b64 v[112:113], 8, v[212:213]
	v_ashrrev_i32_e32 v117, 31, v116
	v_lshl_add_u64 v[114:115], v[208:209], 0, v[112:113]
	v_lshlrev_b64 v[116:117], 8, v[116:117]
	v_lshl_add_u64 v[112:113], v[210:211], 0, v[112:113]
	v_lshl_add_u64 v[118:119], v[208:209], 0, v[116:117]
	global_load_dwordx4 v[160:163], v[114:115], off
	global_load_dwordx4 v[164:167], v[118:119], off
	v_lshl_add_u64 v[114:115], v[210:211], 0, v[116:117]
	global_load_dwordx4 v[168:171], v[112:113], off
	global_load_dwordx4 v[172:175], v[114:115], off
	ds_read_b64_tr_b16 v[112:113], v225 offset:0
	ds_read_b64_tr_b16 v[114:115], v225 offset:0x800
	ds_read_b64_tr_b16 v[116:117], v225 offset:0x1000
	ds_read_b64_tr_b16 v[118:119], v225 offset:0x1800
	ds_read_b64_tr_b16 v[120:121], v225 offset:0x2000
	ds_read_b64_tr_b16 v[122:123], v225 offset:0x2800
	ds_read_b64_tr_b16 v[124:125], v225 offset:0x3000
	ds_read_b64_tr_b16 v[126:127], v225 offset:0x3800
	s_waitcnt lgkmcnt(0)
; #define SBAR() __builtin_amdgcn_sched_barrier(0)
; #define VMW() asm volatile("s_waitcnt vmcnt(0)" ::: "memory")
; #define SLOAD_H(Kp, Vp, k0) do { S.st_v0 = load8(ROW(Vp, k0, sr)); S.st_v1 = load8(ROW(Vp, k0, 32 + sr)); S.st_k0 = load8(ROW(Kp, k0, sr)); S.st_k1 = load8(ROW(Kp, k0, 32 + sr)); } while (0)
; #define SWRITE_HV(bf) do { *(bf16x8*)(V_lds + (bf) * SHM_V + vst0) = S.st_v0; *(bf16x8*)(V_lds + (bf) * SHM_V + vst1) = S.st_v1; } while (0)
; #define SWRITE_H(bf) do { SWRITE_HV(bf); SWRITE_HK(bf); } while (0)
; #define MASKT(P0_, P1_, t) do { if (KBASE(t) > (qlo | 63)) { const float NEG_ = -__builtin_inff(); _Pragma("unroll") for (int r_ = 0; r_ < 16; ++r_) { P0_[r_] = NEG_; P1_[r_] = NEG_; } } } while (0)
; __device__ __forceinline__ void partialSM(f32x16& p0, f32x16& p1, float& m_reg, float& mn, float& alpha) {
;     float pmax = p0[0]; for (int r = 1; r < 16; ++r) pmax = fmaxf(pmax, p0[r]); for (int r = 0; r < 16; ++r) pmax = fmaxf(pmax, p1[r]);
;     { auto rr = __builtin_amdgcn_permlane32_swap(__float_as_uint(pmax), __float_as_uint(pmax), false, false);
;       pmax = fmaxf(__uint_as_float(rr[0]), __uint_as_float(rr[1])); }
;     constexpr float C2 = 1.4426950408889634f * SCALE;
;     if (__builtin_expect(__all((pmax - m_reg) * SCALE <= THR), 1)) { mn = m_reg; alpha = 1.f; }
;     else { mn = fmaxf(m_reg, pmax); alpha = __builtin_amdgcn_exp2f((m_reg - mn) * C2); m_reg = mn; }
;     const float mnL = -mn * C2;
;     for (int r = 0; r < 16; ++r) p0[r] = fmaf(p0[r], C2, mnL); for (int r = 0; r < 16; ++r) p1[r] = fmaf(p1[r], C2, mnL);
;     for (int r = 0; r < 16; ++r) p0[r] = __builtin_amdgcn_exp2f(p0[r]);
; }
; __device__ __forceinline__ void attn_block(const BlockRef& cur, const BlockRef& nxt, char* lds, Seam& S) {
;     ...
;     constexpr int NQL = 8;
;     ...
;     f32x16 pA0, pA1, pB0, pB1; float mnA, mnB, alA, alB; bf16x8 pa0, pa1, pa2, pa3;
;     SWRITE_HV(0); SBAR();
;     if (NT > 1) { SLOAD_H(Kh, Vh, KBASE(1)); }
;     SBAR(); qkt<0>(pA0, pA1, K_lds, r32, hi, S.qr);
;     MASKT(pA0, pA1, 0); partialSM(pA0, pA1, m_reg, mnA, alA);
;     if (NT > 1) { VMW(); SWRITE_H(1); }
;     __syncthreads();
	s_nop 0
	v_mfma_f32_32x32x16_bf16 v[0:15], v[96:99], v[112:115], v[0:15]
	ds_read_b64_tr_b16 v[112:113], v225 offset:0x200
	ds_read_b64_tr_b16 v[114:115], v225 offset:0xa00
	v_mfma_f32_32x32x16_bf16 v[0:15], v[100:103], v[116:119], v[0:15]
	ds_read_b64_tr_b16 v[116:117], v225 offset:0x1200
	ds_read_b64_tr_b16 v[118:119], v225 offset:0x1a00
	v_mfma_f32_32x32x16_bf16 v[0:15], v[104:107], v[120:123], v[0:15]
	ds_read_b64_tr_b16 v[120:121], v225 offset:0x2200
	ds_read_b64_tr_b16 v[122:123], v225 offset:0x2a00
	v_mfma_f32_32x32x16_bf16 v[0:15], v[108:111], v[124:127], v[0:15]
	ds_read_b64_tr_b16 v[124:125], v225 offset:0x3200
	ds_read_b64_tr_b16 v[126:127], v225 offset:0x3a00
	s_waitcnt lgkmcnt(0)
	v_mfma_f32_32x32x16_bf16 v[48:63], v[96:99], v[112:115], v[48:63]
	ds_read_b64_tr_b16 v[112:113], v225 offset:0x400
	ds_read_b64_tr_b16 v[114:115], v225 offset:0xc00
	v_mfma_f32_32x32x16_bf16 v[48:63], v[100:103], v[116:119], v[48:63]
	ds_read_b64_tr_b16 v[116:117], v225 offset:0x1400
	ds_read_b64_tr_b16 v[118:119], v225 offset:0x1c00
	v_mfma_f32_32x32x16_bf16 v[48:63], v[104:107], v[120:123], v[48:63]
	ds_read_b64_tr_b16 v[120:121], v225 offset:0x2400
	ds_read_b64_tr_b16 v[122:123], v225 offset:0x2c00
	v_mfma_f32_32x32x16_bf16 v[48:63], v[108:111], v[124:127], v[48:63]
	ds_read_b64_tr_b16 v[124:125], v225 offset:0x3400
	ds_read_b64_tr_b16 v[126:127], v225 offset:0x3c00
	s_waitcnt lgkmcnt(0)
	v_mfma_f32_32x32x16_bf16 v[32:47], v[96:99], v[112:115], v[32:47]
	ds_read_b64_tr_b16 v[112:113], v225 offset:0x600
	ds_read_b64_tr_b16 v[114:115], v225 offset:0xe00
	v_mfma_f32_32x32x16_bf16 v[32:47], v[100:103], v[116:119], v[32:47]
	ds_read_b64_tr_b16 v[116:117], v225 offset:0x1600
	ds_read_b64_tr_b16 v[118:119], v225 offset:0x1e00
	v_mfma_f32_32x32x16_bf16 v[32:47], v[104:107], v[120:123], v[32:47]
	ds_read_b64_tr_b16 v[120:121], v225 offset:0x2600
	ds_read_b64_tr_b16 v[122:123], v225 offset:0x2e00
	v_mfma_f32_32x32x16_bf16 v[32:47], v[108:111], v[124:127], v[32:47]
	ds_read_b64_tr_b16 v[124:125], v225 offset:0x3600
	ds_read_b64_tr_b16 v[126:127], v225 offset:0x3e00
	s_waitcnt lgkmcnt(0)
	s_sub_i32 s40, s50, 64
	s_cmp_gt_i32 s40, s49
	s_cbranch_scc0 .Lmy_nomask1
	v_mov_b32_e32 v64, v220
	v_mov_b32_e32 v65, v220
	v_mov_b32_e32 v66, v220
	v_mov_b32_e32 v67, v220
	v_mov_b32_e32 v68, v220
	v_mov_b32_e32 v69, v220
	v_mov_b32_e32 v70, v220
	v_mov_b32_e32 v71, v220
	v_mov_b32_e32 v72, v220
	v_mov_b32_e32 v73, v220
	v_mov_b32_e32 v74, v220
	v_mov_b32_e32 v75, v220
	v_mov_b32_e32 v76, v220
	v_mov_b32_e32 v77, v220
	v_mov_b32_e32 v78, v220
	v_mov_b32_e32 v79, v220
	v_mov_b32_e32 v80, v220
	v_mov_b32_e32 v81, v220
	v_mov_b32_e32 v82, v220
	v_mov_b32_e32 v83, v220
	v_mov_b32_e32 v84, v220
	v_mov_b32_e32 v85, v220
	v_mov_b32_e32 v86, v220
	v_mov_b32_e32 v87, v220
	v_mov_b32_e32 v88, v220
	v_mov_b32_e32 v89, v220
	v_mov_b32_e32 v90, v220
	v_mov_b32_e32 v91, v220
	v_mov_b32_e32 v92, v220
	v_mov_b32_e32 v93, v220
	v_mov_b32_e32 v94, v220
	v_mov_b32_e32 v95, v220
.Lmy_nomask1:
	v_mfma_f32_32x32x16_bf16 v[16:31], v[96:99], v[112:115], v[16:31]
	v_mov_b32_e32 v97, v81
	v_mov_b32_e32 v98, v80
	v_mov_b32_e32 v96, v82
	v_mov_b32_e32 v81, v78
	v_mov_b32_e32 v82, v77
	v_max_f32_e32 v77, v97, v97
	v_max_f32_e32 v78, v98, v98
	v_max_f32_e32 v77, v78, v77
	v_max3_f32 v77, v77, v96, v83
	v_max3_f32 v77, v77, v84, v85
	v_max3_f32 v77, v77, v86, v87
	v_max3_f32 v77, v77, v88, v89
	v_max3_f32 v77, v77, v90, v91
	v_max3_f32 v77, v77, v92, v93
	v_max3_f32 v77, v77, v94, v95
	v_mfma_f32_32x32x16_bf16 v[16:31], v[100:103], v[116:119], v[16:31]
	v_max3_f32 v77, v77, v64, v65
	v_max3_f32 v77, v77, v66, v67
	v_max3_f32 v77, v77, v68, v69
	v_max3_f32 v77, v77, v70, v71
	v_max3_f32 v77, v77, v72, v73
	v_max3_f32 v77, v77, v74, v75
	v_mov_b32_e32 v80, v79
	v_max3_f32 v77, v77, v76, v82
	v_max3_f32 v77, v77, v81, v80
	v_mfma_f32_32x32x16_bf16 v[16:31], v[104:107], v[120:123], v[16:31]
	v_mov_b32_e32 v78, v77
	s_nop 1
	v_permlane32_swap_b32_e32 v77, v78
	v_max_f32_e32 v78, v78, v78
	v_max_f32_e32 v77, v77, v77
	v_max_f32_e32 v77, v77, v78
	v_sub_f32_e32 v78, v77, v176
	v_mul_f32_e32 v78, 0x3db504f3, v78
	v_cmp_ge_f32_e32 vcc, s67, v78
	v_max_f32_e32 v78, v176, v176
	v_max_f32_e32 v77, v78, v77
	v_mfma_f32_32x32x16_bf16 v[16:31], v[108:111], v[124:127], v[16:31]
	v_sub_f32_e32 v78, v176, v77
	v_mul_f32_e32 v78, 0x3e0293ee, v78
	v_exp_f32_e32 v78, v78
	s_cmp_eq_u64 vcc, exec
	s_cselect_b64 s[40:41], -1, 0
	s_barrier
	s_waitcnt vmcnt(0)
	v_cndmask_b32_e64 v213, v78, 1.0, s[40:41]
	v_cmp_gt_f32_e32 vcc, 1.0, v213
	s_waitcnt vmcnt(3)
	ds_write_b128 v231, v[160:163]
	s_waitcnt vmcnt(2)
	ds_write_b128 v232, v[164:167]
	s_waitcnt vmcnt(1)
	ds_write_b128 v226, v[168:171] offset:32768
	s_waitcnt vmcnt(0)
	ds_write_b128 v226, v[172:175] offset:40960
	s_cbranch_vccz .LBB0_324
	s_and_saveexec_b64 s[42:43], s[38:39]
	ds_write_b32 v227, v213 offset:128
	s_or_b64 exec, exec, s[42:43]
	s_waitcnt lgkmcnt(0)
	v_add_u32_e32 v78, s69, v200
	ds_read_b128 v[100:103], v78 offset:224
	ds_read_b128 v[104:107], v78 offset:192
	ds_read_b128 v[108:111], v78 offset:160
	ds_read_b128 v[112:115], v78 offset:128
	s_waitcnt lgkmcnt(3)
	v_pk_mul_f32 v[12:13], v[12:13], v[100:101]
	s_waitcnt lgkmcnt(2)
	v_pk_mul_f32 v[8:9], v[8:9], v[104:105]
	s_waitcnt lgkmcnt(1)
	v_pk_mul_f32 v[4:5], v[4:5], v[108:109]
	v_pk_mul_f32 v[14:15], v[14:15], v[102:103]
	v_pk_mul_f32 v[10:11], v[10:11], v[106:107]
	v_pk_mul_f32 v[6:7], v[6:7], v[110:111]
	s_waitcnt lgkmcnt(0)
	v_pk_mul_f32 v[2:3], v[2:3], v[114:115]
	v_pk_mul_f32 v[0:1], v[0:1], v[112:113]
	v_pk_mul_f32 v[60:61], v[60:61], v[100:101]
	v_pk_mul_f32 v[56:57], v[56:57], v[104:105]
	v_pk_mul_f32 v[52:53], v[52:53], v[108:109]
	v_pk_mul_f32 v[62:63], v[62:63], v[102:103]
	v_pk_mul_f32 v[58:59], v[58:59], v[106:107]
	v_pk_mul_f32 v[54:55], v[54:55], v[110:111]
	v_pk_mul_f32 v[50:51], v[50:51], v[114:115]
	v_pk_mul_f32 v[48:49], v[48:49], v[112:113]
	v_pk_mul_f32 v[44:45], v[44:45], v[100:101]
	v_pk_mul_f32 v[40:41], v[40:41], v[104:105]
	v_pk_mul_f32 v[36:37], v[36:37], v[108:109]
	v_pk_mul_f32 v[46:47], v[46:47], v[102:103]
	v_pk_mul_f32 v[42:43], v[42:43], v[106:107]
	v_pk_mul_f32 v[38:39], v[38:39], v[110:111]
	v_pk_mul_f32 v[34:35], v[34:35], v[114:115]
	v_pk_mul_f32 v[32:33], v[32:33], v[112:113]
	v_pk_mul_f32 v[28:29], v[28:29], v[100:101]
	v_pk_mul_f32 v[24:25], v[24:25], v[104:105]
	v_pk_mul_f32 v[20:21], v[20:21], v[108:109]
	v_pk_mul_f32 v[30:31], v[30:31], v[102:103]
	v_pk_mul_f32 v[26:27], v[26:27], v[106:107]
	v_pk_mul_f32 v[22:23], v[22:23], v[110:111]
	v_pk_mul_f32 v[18:19], v[18:19], v[114:115]
	v_pk_mul_f32 v[16:17], v[16:17], v[112:113]

; __device__ __forceinline__ void partialSM(f32x16& p0, f32x16& p1, float& m_reg, float& mn, float& alpha) {
;     float pmax = p0[0]; for (int r = 1; r < 16; ++r) pmax = fmaxf(pmax, p0[r]); for (int r = 0; r < 16; ++r) pmax = fmaxf(pmax, p1[r]);
;     { auto rr = __builtin_amdgcn_permlane32_swap(__float_as_uint(pmax), __float_as_uint(pmax), false, false);
;       pmax = fmaxf(__uint_as_float(rr[0]), __uint_as_float(rr[1])); }
;     constexpr float C2 = 1.4426950408889634f * SCALE;
;     if (__builtin_expect(__all((pmax - m_reg) * SCALE <= THR), 1)) { mn = m_reg; alpha = 1.f; }
;     else { mn = fmaxf(m_reg, pmax); alpha = __builtin_amdgcn_exp2f((m_reg - mn) * C2); m_reg = mn; }
;     const float mnL = -mn * C2;
;     for (int r = 0; r < 16; ++r) p0[r] = fmaf(p0[r], C2, mnL); for (int r = 0; r < 16; ++r) p1[r] = fmaf(p1[r], C2, mnL);
;     for (int r = 0; r < 16; ++r) p0[r] = __builtin_amdgcn_exp2f(p0[r]);
; }
; template <int VB>
; __device__ __forceinline__ void pv_tile(f32x16* o, int vb0, bf16x8 pa0, bf16x8 pa1, bf16x8 pa2, bf16x8 pa3) {
;     ...
;     PV_D0(0); PV_D0(1); PV_D0(2); PV_D0(3);
.LBB0_326:
	ds_read_b64_tr_b16 v[238:239], v225 offset:0x4000
	ds_read_b64_tr_b16 v[240:241], v225 offset:0x4800
	ds_read_b64_tr_b16 v[242:243], v225 offset:0x5000
	ds_read_b64_tr_b16 v[244:245], v225 offset:0x5800
	ds_read_b64_tr_b16 v[246:247], v225 offset:0x6000
	ds_read_b64_tr_b16 v[248:249], v225 offset:0x6800
	ds_read_b64_tr_b16 v[250:251], v225 offset:0x7000
	ds_read_b64_tr_b16 v[252:253], v225 offset:0x7800
	s_waitcnt lgkmcnt(0)
	s_nop 0
	v_mfma_f32_32x32x16_bf16 v[0:15], v[176:179], v[238:241], v[0:15]
	ds_read_b64_tr_b16 v[238:239], v225 offset:0x4200
	ds_read_b64_tr_b16 v[240:241], v225 offset:0x4a00
	v_mfma_f32_32x32x16_bf16 v[0:15], v[180:183], v[242:245], v[0:15]
	ds_read_b64_tr_b16 v[242:243], v225 offset:0x5200
	ds_read_b64_tr_b16 v[244:245], v225 offset:0x5a00
	v_mfma_f32_32x32x16_bf16 v[0:15], v[184:187], v[246:249], v[0:15]
	ds_read_b64_tr_b16 v[246:247], v225 offset:0x6200
	ds_read_b64_tr_b16 v[248:249], v225 offset:0x6a00
	v_mfma_f32_32x32x16_bf16 v[0:15], v[188:191], v[250:253], v[0:15]
	ds_read_b64_tr_b16 v[250:251], v225 offset:0x7200
	ds_read_b64_tr_b16 v[252:253], v225 offset:0x7a00
	s_waitcnt lgkmcnt(0)
	v_mfma_f32_32x32x16_bf16 v[48:63], v[176:179], v[238:241], v[48:63]
	ds_read_b64_tr_b16 v[238:239], v225 offset:0x4400
	ds_read_b64_tr_b16 v[240:241], v225 offset:0x4c00
	v_mfma_f32_32x32x16_bf16 v[48:63], v[180:183], v[242:245], v[48:63]
	ds_read_b64_tr_b16 v[242:243], v225 offset:0x5400
	ds_read_b64_tr_b16 v[244:245], v225 offset:0x5c00
	v_mfma_f32_32x32x16_bf16 v[48:63], v[184:187], v[246:249], v[48:63]
	ds_read_b64_tr_b16 v[246:247], v225 offset:0x6400
	ds_read_b64_tr_b16 v[248:249], v225 offset:0x6c00
	v_mfma_f32_32x32x16_bf16 v[48:63], v[188:191], v[250:253], v[48:63]
	ds_read_b64_tr_b16 v[250:251], v225 offset:0x7400
	ds_read_b64_tr_b16 v[252:253], v225 offset:0x7c00
	s_waitcnt lgkmcnt(0)
	v_mfma_f32_32x32x16_bf16 v[32:47], v[176:179], v[238:241], v[32:47]
	ds_read_b64_tr_b16 v[238:239], v225 offset:0x4600
	ds_read_b64_tr_b16 v[240:241], v225 offset:0x4e00
	v_mfma_f32_32x32x16_bf16 v[32:47], v[180:183], v[242:245], v[32:47]
	ds_read_b64_tr_b16 v[242:243], v225 offset:0x5600
	ds_read_b64_tr_b16 v[244:245], v225 offset:0x5e00
	v_mfma_f32_32x32x16_bf16 v[32:47], v[184:187], v[246:249], v[32:47]
	ds_read_b64_tr_b16 v[246:247], v225 offset:0x6600
	ds_read_b64_tr_b16 v[248:249], v225 offset:0x6e00
	v_mfma_f32_32x32x16_bf16 v[32:47], v[188:191], v[250:253], v[32:47]
	ds_read_b64_tr_b16 v[250:251], v225 offset:0x7600
	ds_read_b64_tr_b16 v[252:253], v225 offset:0x7e00
	s_waitcnt lgkmcnt(0)
	v_mfma_f32_32x32x16_bf16 v[16:31], v[176:179], v[238:241], v[16:31]
	s_cmp_gt_i32 s50, s49
	s_cbranch_scc0 .Lmy_nomask2
	v_mov_b32_e32 v96, v220
	v_mov_b32_e32 v97, v220
	v_mov_b32_e32 v98, v220
	v_mov_b32_e32 v99, v220
	v_mov_b32_e32 v100, v220
	v_mov_b32_e32 v101, v220
	v_mov_b32_e32 v102, v220
	v_mov_b32_e32 v103, v220
	v_mov_b32_e32 v104, v220
	v_mov_b32_e32 v105, v220
	v_mov_b32_e32 v106, v220
	v_mov_b32_e32 v107, v220
	v_mov_b32_e32 v108, v220
	v_mov_b32_e32 v109, v220
	v_mov_b32_e32 v110, v220
	v_mov_b32_e32 v111, v220
	v_mov_b32_e32 v112, v220
	v_mov_b32_e32 v113, v220
	v_mov_b32_e32 v114, v220
	v_mov_b32_e32 v115, v220
	v_mov_b32_e32 v116, v220
	v_mov_b32_e32 v117, v220
	v_mov_b32_e32 v118, v220
	v_mov_b32_e32 v119, v220
	v_mov_b32_e32 v120, v220
	v_mov_b32_e32 v121, v220
	v_mov_b32_e32 v122, v220
	v_mov_b32_e32 v123, v220
	v_mov_b32_e32 v124, v220
	v_mov_b32_e32 v125, v220
	v_mov_b32_e32 v126, v220
	v_mov_b32_e32 v127, v220
.Lmy_nomask2:
	v_max_f32_e32 v176, v113, v113
	v_max_f32_e32 v177, v112, v112
	v_max_f32_e32 v176, v177, v176
	v_mfma_f32_32x32x16_bf16 v[16:31], v[180:183], v[242:245], v[16:31]
	v_max3_f32 v176, v176, v114, v115
	v_max3_f32 v176, v176, v116, v117
	v_max3_f32 v176, v176, v118, v119
	v_max3_f32 v176, v176, v120, v121
	v_max3_f32 v176, v176, v122, v123
	v_max3_f32 v176, v176, v124, v125
	v_max3_f32 v176, v176, v126, v127
	v_max3_f32 v176, v176, v96, v97
	v_mfma_f32_32x32x16_bf16 v[16:31], v[184:187], v[246:249], v[16:31]
	v_max3_f32 v176, v176, v98, v99
	v_max3_f32 v176, v176, v100, v101
	v_max3_f32 v176, v176, v102, v103
	v_max3_f32 v176, v176, v104, v105
	v_max3_f32 v176, v176, v106, v107
	v_max3_f32 v176, v176, v108, v109
	v_max3_f32 v176, v176, v110, v111
	v_mov_b32_e32 v177, v176
	v_mfma_f32_32x32x16_bf16 v[16:31], v[188:191], v[250:253], v[16:31]
	s_nop 0
	v_permlane32_swap_b32_e32 v176, v177
	v_max_f32_e32 v177, v177, v177
	v_max_f32_e32 v176, v176, v176
	v_max_f32_e32 v176, v176, v177
	v_sub_f32_e32 v177, v176, v235
	v_mul_f32_e32 v177, 0x3db504f3, v177
	v_cmp_ge_f32_e32 vcc, s67, v177
	s_cmp_eq_u64 vcc, exec
	s_cselect_b64 s[40:41], -1, 0
	s_andn2_b64 vcc, exec, s[42:43]
	s_barrier
	s_cbranch_vccnz .LBB0_328
	s_waitcnt vmcnt(0)
	s_waitcnt vmcnt(3)
	ds_write_b128 v231, v[160:163] offset:16384
	s_waitcnt vmcnt(2)
	ds_write_b128 v232, v[164:167] offset:16384
	s_waitcnt vmcnt(1)
	ds_write_b128 v226, v[168:171] offset:49152
	s_waitcnt vmcnt(0)
	ds_write_b128 v226, v[172:175] offset:57344

; __device__ __forceinline__ unsigned cvt_pk_bf16(float lo, float hi) { f32x2_t v = {lo, hi}; bf16x2_t b = __builtin_convertvector(v, bf16x2_t); return __builtin_bit_cast(unsigned, b); }
; __device__ __forceinline__ float wave_sum(float v) {
; #pragma unroll
;     for (int o = 1; o < 64; o <<= 1) v += __shfl_xor(v, o);
;     return v;
; }
; __device__ __forceinline__ void norm_mod_rows(const float* x, const float* g, const float* ada, int shift_off, int scale_off, bf16* XN, int gw, int NGW, int lane) {
;     ...
;         for (int i = 0; i < 16; ++i) {
;             const size_t row = (size_t)chunk * 16 + i;
;             { const f32x4* xr = (const f32x4*)(x + (row + (i < 15 ? 1 : 0)) * DM) + lane;
; #pragma unroll
;               for (int j = 0; j < 8; ++j) vn[j] = __builtin_nontemporal_load(xr + 64 * j); }
;             float s = 0.f;
; #pragma unroll
;             for (int j = 0; j < 8; ++j) s += (v[j].x * v[j].x + v[j].y * v[j].y) + (v[j].z * v[j].z + v[j].w * v[j].w);
;             const float rs = 1.0f / sqrtf(wave_sum(s) * (1.f / DM) + EPS);
;             v2u* o8 = (v2u*)(XN + row * DM) + lane;
; #pragma unroll
;             for (int j = 0; j < 8; ++j) { const f32x4 y = v[j] * rs * ca[j] + cb[j]; v2u w; w.x = pg8::cvt_pk_bf16(y.x, y.y); w.y = pg8::cvt_pk_bf16(y.z, y.w); o8[64 * j] = w; }
.LBB0_707:
	s_cmp_lg_u32 s24, 15
	s_cselect_b64 s[26:27], -1, 0
	s_mov_b32 s15, 0
	v_pk_mul_f32 v[70:71], v[54:55], v[54:55]
	v_pk_mul_f32 v[72:73], v[52:53], v[52:53]
	v_pk_mul_f32 v[74:75], v[42:43], v[42:43]
	v_pk_mul_f32 v[76:77], v[40:41], v[40:41]
	v_pk_mul_f32 v[78:79], v[34:35], v[34:35]
	v_pk_mul_f32 v[80:81], v[38:39], v[38:39]
	v_pk_mul_f32 v[82:83], v[32:33], v[32:33]
	v_pk_mul_f32 v[84:85], v[36:37], v[36:37]
	v_mul_f32_e32 v86, v44, v44
	v_mul_f32_e32 v88, v46, v46
	v_cndmask_b32_e64 v66, 0, 1, s[26:27]
	s_add_u32 s26, s18, s24
	v_mov_b32_e32 v67, s15
	v_mov_b32_e32 v94, v82
	v_mov_b32_e32 v95, v84
	v_mov_b32_e32 v84, v83
	v_mov_b32_e32 v82, v78
	v_mov_b32_e32 v83, v80
	v_mov_b32_e32 v80, v79
	v_pk_mov_b32 v[78:79], v[76:77], v[74:75] op_sel:[1,0]
	v_mov_b32_e32 v77, v75
	v_pk_fma_f32 v[74:75], v[44:45], v[44:45], v[86:87] op_sel_hi:[1,1,0]
	v_pk_fma_f32 v[86:87], v[46:47], v[46:47], v[88:89] op_sel_hi:[1,1,0]
	v_pk_mov_b32 v[88:89], v[72:73], v[70:71] op_sel:[1,0]
	v_mov_b32_e32 v73, v71
	s_addc_u32 s27, s19, s25
	v_mul_f32_e32 v90, v60, v60
	v_mul_f32_e32 v92, v62, v62
	v_pk_add_f32 v[72:73], v[88:89], v[72:73]
	v_lshl_add_u64 v[66:67], s[26:27], 0, v[66:67]
	v_pk_fma_f32 v[70:71], v[60:61], v[60:61], v[90:91] op_sel_hi:[1,1,0]
	v_pk_fma_f32 v[90:91], v[62:63], v[62:63], v[92:93] op_sel_hi:[1,1,0]
	v_pk_add_f32 v[84:85], v[94:95], v[84:85]
	v_pk_add_f32 v[80:81], v[82:83], v[80:81]
	v_pk_add_f32 v[164:165], v[72:73], v[72:73] op_sel_hi:[0,1]
	v_lshlrev_b64 v[66:67], 13, v[66:67]
	v_pk_add_f32 v[76:77], v[78:79], v[76:77]
	v_mul_f32_e32 v74, v48, v48
	v_mul_f32_e32 v86, v49, v49
	v_mul_f32_e32 v70, v68, v68
	v_mul_f32_e32 v90, v65, v65
	v_pk_add_f32 v[68:69], v[84:85], v[80:81]
	v_mul_f32_e32 v164, v64, v64
	v_lshl_add_u64 v[64:65], v[96:97], 0, v[66:67]
	v_pk_add_f32 v[76:77], v[76:77], v[76:77] op_sel_hi:[0,1]
	v_pk_add_f32 v[162:163], v[74:75], v[86:87]
	v_pk_add_f32 v[166:167], v[70:71], v[90:91]
	v_pk_add_f32 v[68:69], v[68:69], v[68:69] op_sel_hi:[0,1]
	global_load_dwordx4 v[92:95], v[64:65], off nt
	global_load_dwordx4 v[88:91], v[64:65], off offset:1024 nt
	global_load_dwordx4 v[84:87], v[64:65], off offset:2048 nt
	global_load_dwordx4 v[80:83], v[64:65], off offset:3072 nt
	v_add_co_u32_e32 v64, vcc, s13, v64
	v_mul_f32_e32 v76, v50, v50
	v_mul_f32_e32 v68, v51, v51
	v_addc_co_u32_e32 v65, vcc, 0, v65, vcc
	v_pk_add_f32 v[168:169], v[76:77], v[68:69]
	global_load_dwordx4 v[76:79], v[64:65], off nt
	global_load_dwordx4 v[72:75], v[64:65], off offset:1024 nt
	global_load_dwordx4 v[68:71], v[64:65], off offset:2048 nt
	s_nop 0
	global_load_dwordx4 v[64:67], v[64:65], off offset:3072 nt
	v_pk_add_f32 v[162:163], v[162:163], v[168:169]
	s_mov_b32 s15, 0xf800000
	v_pk_add_f32 v[162:163], v[162:163], v[162:163] op_sel_hi:[0,1]
	v_mul_f32_e32 v162, v160, v160
	v_pk_add_f32 v[160:161], v[164:165], v[162:163]
	s_add_u32 s24, s24, 1
	v_pk_add_f32 v[160:161], v[166:167], v[160:161]
	s_addc_u32 s25, s25, 0
	v_add_f32_e32 v160, v160, v161
	s_nop 1
	v_mov_b32_dpp v161, v160 quad_perm:[1,0,3,2] row_mask:0xf bank_mask:0xf
	s_cmp_eq_u32 s24, 16
	s_waitcnt lgkmcnt(0)
	v_add_f32_e32 v160, v160, v161
	s_nop 1
	v_mov_b32_dpp v161, v160 quad_perm:[2,3,0,1] row_mask:0xf bank_mask:0xf
	s_waitcnt lgkmcnt(0)
	v_add_f32_e32 v160, v160, v161
	s_nop 1
	v_mov_b32_dpp v161, v160 row_half_mirror row_mask:0xf bank_mask:0xf
	s_waitcnt lgkmcnt(0)
	v_add_f32_e32 v160, v160, v161
	s_nop 1
	v_mov_b32_dpp v161, v160 row_mirror row_mask:0xf bank_mask:0xf
	s_waitcnt lgkmcnt(0)
	v_add_f32_e32 v160, v160, v161
	v_mov_b32_e32 v161, v160
	s_nop 1
	v_permlane16_swap_b32_e32 v160, v161
	s_waitcnt lgkmcnt(0)
	v_add_f32_e32 v160, v160, v161
	v_mov_b32_e32 v161, v160
	s_nop 1
	v_permlane32_swap_b32_e32 v160, v161
	s_waitcnt lgkmcnt(0)
; __device__ __forceinline__ unsigned cvt_pk_bf16(float lo, float hi) { f32x2_t v = {lo, hi}; bf16x2_t b = __builtin_convertvector(v, bf16x2_t); return __builtin_bit_cast(unsigned, b); }
; __device__ __forceinline__ void norm_mod_rows(const float* x, const float* g, const float* ada, int shift_off, int scale_off, bf16* XN, int gw, int NGW, int lane) {
;     ...
;             float s = 0.f;
; #pragma unroll
;             for (int j = 0; j < 8; ++j) s += (v[j].x * v[j].x + v[j].y * v[j].y) + (v[j].z * v[j].z + v[j].w * v[j].w);
;             const float rs = 1.0f / sqrtf(wave_sum(s) * (1.f / DM) + EPS);
;             v2u* o8 = (v2u*)(XN + row * DM) + lane;
; #pragma unroll
;             for (int j = 0; j < 8; ++j) { const f32x4 y = v[j] * rs * ca[j] + cb[j]; v2u w; w.x = pg8::cvt_pk_bf16(y.x, y.y); w.y = pg8::cvt_pk_bf16(y.z, y.w); o8[64 * j] = w; }
; #pragma unroll
;             for (int j = 0; j < 8; ++j) v[j] = vn[j];
;         }
;     }
	v_add_f32_e32 v160, v160, v161
	v_fmamk_f32 v160, v160, 0x3a000000, v158
	v_mul_f32_e32 v161, 0x4f800000, v160
	v_cmp_gt_f32_e32 vcc, s15, v160
	s_nop 1
	v_cndmask_b32_e32 v160, v160, v161, vcc
	v_sqrt_f32_e32 v161, v160
	s_nop 0
	v_add_u32_e32 v162, -1, v161
	v_add_u32_e32 v163, 1, v161
	v_fma_f32 v164, -v162, v161, v160
	v_fma_f32 v165, -v163, v161, v160
	v_cmp_ge_f32_e64 s[38:39], 0, v164
	s_nop 1
	v_cndmask_b32_e64 v161, v161, v162, s[38:39]
	v_cmp_lt_f32_e64 s[38:39], 0, v165
	s_nop 1
	v_cndmask_b32_e64 v161, v161, v163, s[38:39]
	v_mul_f32_e32 v162, 0x37800000, v161
	v_cndmask_b32_e32 v161, v161, v162, vcc
	v_cmp_class_f32_e32 vcc, v160, v159
	s_nop 1
	v_cndmask_b32_e32 v160, v161, v160, vcc
	v_div_scale_f32 v161, s[26:27], v160, v160, 1.0
	v_rcp_f32_e32 v163, v161
	v_div_scale_f32 v162, vcc, 1.0, v160, 1.0
	s_mov_b64 s[26:27], 0x1000
	v_fma_f32 v164, -v161, v163, 1.0
	v_fmac_f32_e32 v163, v164, v163
	v_mul_f32_e32 v164, v162, v163
	v_fma_f32 v165, -v161, v164, v162
	v_fmac_f32_e32 v164, v165, v163
	v_fma_f32 v161, -v161, v164, v162
	v_div_fmas_f32 v161, v161, v163, v164
	v_div_fixup_f32 v160, v161, v160, 1.0
	v_pk_mul_f32 v[32:33], v[32:33], v[160:161] op_sel_hi:[1,0]
	v_pk_mul_f32 v[34:35], v[34:35], v[160:161] op_sel_hi:[1,0]
	v_pk_mul_f32 v[36:37], v[36:37], v[160:161] op_sel_hi:[1,0]
	v_pk_mul_f32 v[38:39], v[38:39], v[160:161] op_sel_hi:[1,0]
	v_pk_mul_f32 v[40:41], v[40:41], v[160:161] op_sel_hi:[1,0]
	v_pk_mul_f32 v[42:43], v[42:43], v[160:161] op_sel_hi:[1,0]
	v_pk_mul_f32 v[44:45], v[44:45], v[160:161] op_sel_hi:[1,0]
	v_pk_mul_f32 v[46:47], v[46:47], v[160:161] op_sel_hi:[1,0]
	v_pk_mul_f32 v[48:49], v[48:49], v[160:161] op_sel_hi:[1,0]
	v_pk_mul_f32 v[50:51], v[50:51], v[160:161] op_sel_hi:[1,0]
	v_pk_mul_f32 v[52:53], v[52:53], v[160:161] op_sel_hi:[1,0]
	v_pk_mul_f32 v[54:55], v[54:55], v[160:161] op_sel_hi:[1,0]
	v_pk_mul_f32 v[60:61], v[60:61], v[160:161] op_sel_hi:[1,0]
	v_pk_mul_f32 v[62:63], v[62:63], v[160:161] op_sel_hi:[1,0]
	v_pk_mul_f32 v[56:57], v[56:57], v[160:161] op_sel_hi:[1,0]
	v_pk_mul_f32 v[58:59], v[58:59], v[160:161] op_sel_hi:[1,0]
	v_pk_fma_f32 v[34:35], v[110:111], v[34:35], v[2:3]
	v_pk_fma_f32 v[32:33], v[112:113], v[32:33], v[0:1]
	v_pk_fma_f32 v[38:39], v[114:115], v[38:39], v[6:7]
	v_pk_fma_f32 v[36:37], v[116:117], v[36:37], v[4:5]
	v_pk_fma_f32 v[42:43], v[118:119], v[42:43], v[10:11]
	v_pk_fma_f32 v[40:41], v[120:121], v[40:41], v[8:9]
	v_pk_fma_f32 v[46:47], v[122:123], v[46:47], v[14:15]
	v_pk_fma_f32 v[44:45], v[124:125], v[44:45], v[12:13]
	v_pk_fma_f32 v[50:51], v[126:127], v[50:51], v[18:19]
	v_pk_fma_f32 v[48:49], v[128:129], v[48:49], v[16:17]
	v_pk_fma_f32 v[54:55], v[130:131], v[54:55], v[22:23]
	v_pk_fma_f32 v[52:53], v[132:133], v[52:53], v[20:21]
	v_pk_fma_f32 v[62:63], v[134:135], v[62:63], v[26:27]
	v_pk_fma_f32 v[60:61], v[136:137], v[60:61], v[24:25]
	v_pk_fma_f32 v[58:59], v[138:139], v[58:59], v[30:31]
	v_pk_fma_f32 v[56:57], v[140:141], v[56:57], v[28:29]
	v_cvt_pk_bf16_f32 v32, v32, v33
	v_cvt_pk_bf16_f32 v33, v34, v35
	v_cvt_pk_bf16_f32 v34, v36, v37
	v_cvt_pk_bf16_f32 v35, v38, v39
	v_cvt_pk_bf16_f32 v36, v40, v41
	v_cvt_pk_bf16_f32 v37, v42, v43
	v_cvt_pk_bf16_f32 v38, v44, v45
	v_cvt_pk_bf16_f32 v39, v46, v47
	v_cvt_pk_bf16_f32 v40, v48, v49
	v_cvt_pk_bf16_f32 v41, v50, v51
	v_cvt_pk_bf16_f32 v42, v52, v53
	v_cvt_pk_bf16_f32 v43, v54, v55
	v_cvt_pk_bf16_f32 v44, v60, v61
	v_cvt_pk_bf16_f32 v45, v62, v63
	v_cvt_pk_bf16_f32 v46, v56, v57
	v_cvt_pk_bf16_f32 v47, v58, v59
	s_waitcnt vmcnt(0)
	v_mov_b64_e32 v[56:57], v[64:65]
	global_store_dwordx2 v[142:143], v[32:33], off offset:-2048
	global_store_dwordx2 v[142:143], v[34:35], off offset:-1536
	global_store_dwordx2 v[142:143], v[36:37], off offset:-1024
	global_store_dwordx2 v[142:143], v[38:39], off offset:-512
	global_store_dwordx2 v[142:143], v[40:41], off
	global_store_dwordx2 v[142:143], v[42:43], off offset:512
	global_store_dwordx2 v[142:143], v[44:45], off offset:1024
	global_store_dwordx2 v[142:143], v[46:47], off offset:1536
	v_lshl_add_u64 v[142:143], v[142:143], 0, s[26:27]
	v_mov_b32_e32 v32, v92
	v_mov_b32_e32 v33, v93
	v_mov_b32_e32 v34, v94
	v_mov_b32_e32 v35, v95
	v_mov_b32_e32 v36, v88
	v_mov_b32_e32 v37, v89
	v_mov_b32_e32 v38, v90
	v_mov_b32_e32 v39, v91
	v_mov_b32_e32 v40, v84
	v_mov_b32_e32 v41, v85
	v_mov_b32_e32 v42, v86
	v_mov_b32_e32 v43, v87
	v_mov_b32_e32 v44, v80
	v_mov_b32_e32 v45, v81
	v_mov_b32_e32 v46, v82
	v_mov_b32_e32 v47, v83
	v_mov_b64_e32 v[58:59], v[66:67]
	v_mov_b32_e32 v48, v76
	v_mov_b32_e32 v49, v77
	v_mov_b32_e32 v50, v78
	v_mov_b32_e32 v51, v79
	v_mov_b32_e32 v52, v72
	v_mov_b32_e32 v53, v73
	v_mov_b32_e32 v54, v74
	v_mov_b32_e32 v55, v75
	v_mov_b32_e32 v60, v68
	v_mov_b32_e32 v61, v69
	v_mov_b32_e32 v62, v70
	v_mov_b32_e32 v63, v71
	v_mov_b32_e32 v68, v64
	v_mov_b32_e32 v64, v66
	v_mov_b32_e32 v160, v67
	s_cbranch_scc0 .LBB0_707
	s_add_i32 s14, s14, s12
	s_add_u32 s18, s18, s20
	s_addc_u32 s19, s19, s21
	s_cmpk_gt_i32 s14, 0x7ff
	v_lshl_add_u64 v[108:109], v[108:109], 0, s[22:23]
	s_cbranch_scc0 .LBB0_706
	v_readlane_b32 s24, v254, 43
	v_readlane_b32 s36, v254, 45
	v_readlane_b32 s38, v254, 47
	v_readlane_b32 s25, v254, 44
	v_readlane_b32 s37, v254, 46
	v_readlane_b32 s39, v254, 48
